# v3: + G1/G3 alpha_w prep loads de-serialized + G3 gain loads batched + DPP row sums
# speedup vs baseline: 1.0103x; 1.0044x over previous
; __device__ __forceinline__ unsigned pk_bf16(float lo, float hi) { unsigned r; asm volatile("v_cvt_pk_bf16_f32 %0, %1, %2" : "=v"(r) : "v"(lo), "v"(hi)); return r; }
; __device__ __forceinline__ void gla_prep_load(PrepRegs& R, const Params& p, int l, int h, int row0, int wave, int fr, int fq) {
;     const bf16_t* Z = (const bf16_t*)(p.ws + OFF_Z);
; #pragma unroll
;     for (int q = 0; q < 3; ++q) { const int tile = wave * 3 + q, mi = tile / 6, ni = tile % 6, dir = ni / 3, c = (ni % 3) * 16 + fr;
;         R.ga[q] = *(const u32x4*)(Z + (size_t)(row0 + mi * 16 + fr) * ZLD + ZC_GA + fq * 8);
;         R.bw[q] = (u32x4){0u, 0u, 0u, 0u};
;         if ((fq >> 1) == dir) { const float* aw = p.gla_alpha_w + ((size_t)(l * 2 + dir) * 16 + (fq & 1) * 8) * 192 + h * 48 + c; float w[8];
; #pragma unroll
;             for (int e = 0; e < 8; ++e) w[e] = aw[e * 192];
;             R.bw[q].x = pk_bf16(w[0], w[1]); R.bw[q].y = pk_bf16(w[2], w[3]); R.bw[q].z = pk_bf16(w[4], w[5]); R.bw[q].w = pk_bf16(w[6], w[7]); }
;         R.bias[q] = p.gla_alpha_b[(size_t)(l * 2 + dir) * 192 + h * 48 + c]; }
; }
.LBB0_678:
	v_add_u32_e32 v60, s89, v4
	v_ashrrev_i32_e32 v42, 6, v60
	v_lshrrev_b32_e32 v0, 31, v60
	v_add_u32_e32 v0, v42, v0
	v_and_b32_e32 v43, 15, v4
	v_ashrrev_i32_e32 v75, 1, v0
	v_add_u32_e32 v5, s15, v43
	v_lshlrev_b32_e32 v69, 4, v75
	v_bfe_u32 v68, v4, 4, 2
	v_add_u32_e32 v0, v5, v69
	s_waitcnt lgkmcnt(0)
	v_mov_b64_e32 v[2:3], s[8:9]
	v_mad_i64_i32 v[2:3], s[4:5], v0, s86, v[2:3]
	v_lshlrev_b32_e32 v0, 4, v68
	v_lshl_add_u64 v[2:3], v[2:3], 0, v[0:1]
	v_add_co_u32_e32 v2, vcc, 0x2c00000, v2
	v_lshl_add_u32 v8, v42, 1, v42
	s_nop 0
	v_addc_co_u32_e32 v3, vcc, 0, v3, vcc
	global_load_dwordx4 v[18:21], v[2:3], off offset:3072
	v_lshrrev_b32_e32 v2, 4, v4
	v_bfe_u32 v6, v2, 1, 1
	v_mul_hi_i32 v2, v8, s77
	v_lshrrev_b32_e32 v3, 31, v2
	v_add_u32_e32 v2, v2, v3
	v_mul_lo_u32 v2, v2, 6
	v_sub_u32_e32 v74, v8, v2
	s_movk_i32 s4, 0x56
	v_mul_lo_u16_sdwa v2, sext(v74), s4 dst_sel:DWORD dst_unused:UNUSED_PAD src0_sel:BYTE_0 src1_sel:DWORD
	v_lshrrev_b16_e32 v3, 15, v2
	v_add_u16_sdwa v2, v2, v3 dst_sel:DWORD dst_unused:UNUSED_PAD src0_sel:BYTE_1 src1_sel:DWORD
	v_bfe_i32 v70, v2, 0, 8
	v_mul_lo_u16_e32 v2, 3, v2
	v_sub_u16_e32 v2, v74, v2
	v_bfe_i32 v71, v2, 0, 8
	v_lshl_or_b32 v52, v71, 4, v43
	v_cmp_eq_u32_e32 vcc, v6, v70
	v_ashrrev_i32_e32 v53, 31, v52
	s_nop 1
	v_cndmask_b32_e64 v140, 0, -1, vcc
	v_lshlrev_b32_e32 v61, 3, v68
	s_and_b32 s26, s26, 3
	v_and_b32_e32 v2, 8, v61
	v_or_b32_e32 v3, s94, v6
	s_mul_i32 s27, s26, 48
	v_lshl_or_b32 v7, v3, 4, v2
	v_mul_u32_u24_e32 v2, 0x300, v7
	v_mov_b32_e32 v3, v1
	v_lshl_add_u64 v[2:3], s[16:17], 0, v[2:3]
	s_lshl_b32 s56, s27, 2
	v_lshl_add_u64 v[2:3], v[2:3], 0, s[56:57]
	v_lshl_add_u64 v[2:3], v[52:53], 2, v[2:3]
	global_load_dword v112, v[2:3], off offset:768
	global_load_dword v113, v[2:3], off
	global_load_dword v114, v[2:3], off offset:2304
	global_load_dword v115, v[2:3], off offset:1536
	global_load_dword v116, v[2:3], off offset:3840
	global_load_dword v117, v[2:3], off offset:3072
	v_add_co_u32_e32 v2, vcc, 0x1000, v2
	s_nop 1
	v_addc_co_u32_e32 v3, vcc, 0, v3, vcc
	global_load_dword v118, v[2:3], off offset:1280
	s_nop 0
	global_load_dword v119, v[2:3], off offset:512
	v_add_u32_e32 v2, s94, v70
	v_mul_i32_i24_e32 v2, 0xc0, v2
	v_ashrrev_i32_e32 v3, 31, v2
	v_lshl_add_u64 v[2:3], v[2:3], 2, s[18:19]
	s_lshl_b32 s56, s27, 2
	v_lshl_add_u64 v[2:3], v[2:3], 0, s[56:57]
	v_lshl_add_u64 v[2:3], v[52:53], 2, v[2:3]
	v_add_u32_e32 v9, 1, v8
	global_load_dword v78, v[2:3], off
	v_mul_hi_i32 v2, v9, s77
	v_lshrrev_b32_e32 v3, 31, v2
	v_add_u32_e32 v76, v2, v3
	v_lshlrev_b32_e32 v65, 4, v76
	v_add_u32_e32 v10, v5, v65
	v_mov_b64_e32 v[2:3], s[8:9]
	v_mad_i64_i32 v[10:11], s[4:5], v10, s86, v[2:3]
	v_lshlrev_b32_e32 v2, 1, v61
	v_mov_b32_e32 v3, v1
	v_lshl_add_u64 v[10:11], v[10:11], 0, v[2:3]
	v_add_co_u32_e32 v10, vcc, 0x2c00000, v10
	v_mul_lo_u32 v3, v76, 6
	s_nop 0
	v_addc_co_u32_e32 v11, vcc, 0, v11, vcc
	global_load_dwordx4 v[22:25], v[10:11], off offset:3072
	v_sub_u32_e32 v73, v9, v3
	v_mul_lo_u16_e32 v3, 0x56, v73
	v_lshrrev_b16_e32 v9, 15, v3
	v_add_u16_sdwa v3, v3, v9 dst_sel:DWORD dst_unused:UNUSED_PAD src0_sel:BYTE_1 src1_sel:DWORD
	v_bfe_i32 v66, v3, 0, 8
	v_mul_lo_u16_e32 v3, 3, v3
	v_sub_u16_e32 v3, v73, v3
	v_bfe_i32 v67, v3, 0, 8
	v_lshl_or_b32 v54, v67, 4, v43
	v_cmp_eq_u32_e32 vcc, v6, v66
	v_ashrrev_i32_e32 v55, 31, v54
	s_nop 1
	v_cndmask_b32_e64 v141, 0, -1, vcc
	v_mul_u32_u24_e32 v10, 0x300, v7
	v_mov_b32_e32 v11, v1
	v_lshl_add_u64 v[10:11], s[16:17], 0, v[10:11]
	v_lshl_add_u64 v[10:11], v[10:11], 0, s[56:57]
	v_lshl_add_u64 v[10:11], v[54:55], 2, v[10:11]
	global_load_dword v120, v[10:11], off offset:768
	global_load_dword v121, v[10:11], off
	global_load_dword v122, v[10:11], off offset:2304
	global_load_dword v123, v[10:11], off offset:1536
	global_load_dword v124, v[10:11], off offset:3840
	global_load_dword v125, v[10:11], off offset:3072
	v_add_co_u32_e32 v10, vcc, 0x1000, v10
	s_nop 1
	v_addc_co_u32_e32 v11, vcc, 0, v11, vcc
	global_load_dword v126, v[10:11], off offset:1280
	s_nop 0
	global_load_dword v127, v[10:11], off offset:512
	v_add_u32_e32 v3, s94, v66
	v_mul_i32_i24_e32 v10, 0xc0, v3
; __device__ __forceinline__ unsigned pk_bf16(float lo, float hi) { unsigned r; asm volatile("v_cvt_pk_bf16_f32 %0, %1, %2" : "=v"(r) : "v"(lo), "v"(hi)); return r; }
; __device__ __forceinline__ void gla_prep_load(PrepRegs& R, const Params& p, int l, int h, int row0, int wave, int fr, int fq) {
;     const bf16_t* Z = (const bf16_t*)(p.ws + OFF_Z);
; #pragma unroll
;     for (int q = 0; q < 3; ++q) { const int tile = wave * 3 + q, mi = tile / 6, ni = tile % 6, dir = ni / 3, c = (ni % 3) * 16 + fr;
;         R.ga[q] = *(const u32x4*)(Z + (size_t)(row0 + mi * 16 + fr) * ZLD + ZC_GA + fq * 8);
;         R.bw[q] = (u32x4){0u, 0u, 0u, 0u};
;         if ((fq >> 1) == dir) { const float* aw = p.gla_alpha_w + ((size_t)(l * 2 + dir) * 16 + (fq & 1) * 8) * 192 + h * 48 + c; float w[8];
; #pragma unroll
;             for (int e = 0; e < 8; ++e) w[e] = aw[e * 192];
;             R.bw[q].x = pk_bf16(w[0], w[1]); R.bw[q].y = pk_bf16(w[2], w[3]); R.bw[q].z = pk_bf16(w[4], w[5]); R.bw[q].w = pk_bf16(w[6], w[7]); }
;         R.bias[q] = p.gla_alpha_b[(size_t)(l * 2 + dir) * 192 + h * 48 + c]; }
; }
; __device__ __forceinline__ void gla_g1_item(int wv, const Params& p, int l, int it, LAS unsigned char* lds) {
;     ...
;     const int t3 = tid / 6, r6 = tid % 6, half = r6 / 3, j4 = (r6 % 3) * 4, c1 = half * 24 + j4;
;     u32x2 w1 = (u32x2){0u, 0u}, w2 = (u32x2){0u, 0u}; f32x4 ra = (f32x4){1.f, 0.f, 1.f, 0.f}, rb = ra;
;     if (tid < 384) { const bf16_t* zr = Z + (size_t)(row0 + t3) * ZLD + ZC_GK + h * 48 + c1; w1 = *(const u32x2*)zr; w2 = *(const u32x2*)(zr + 12);
;         if (latent) { const float* rp = (const float*)(p.ws + OFF_ROPE) + ((half ? t3 : n) * 12 + j4) * 2; ra = *(const f32x4*)rp; rb = *(const f32x4*)(rp + 4); } }
	v_ashrrev_i32_e32 v11, 31, v10
	v_lshl_add_u64 v[10:11], v[10:11], 2, s[18:19]
	v_lshl_add_u64 v[10:11], v[10:11], 0, s[56:57]
	v_lshl_add_u64 v[10:11], v[54:55], 2, v[10:11]
	global_load_dword v79, v[10:11], off
	v_add_u32_e32 v10, 2, v8
	v_mul_hi_i32 v3, v10, s77
	v_lshrrev_b32_e32 v8, 31, v3
	v_add_u32_e32 v77, v3, v8
	v_lshlrev_b32_e32 v62, 4, v77
	v_add_u32_e32 v3, v5, v62
	v_mov_b64_e32 v[8:9], s[8:9]
	v_mad_i64_i32 v[8:9], s[4:5], v3, s86, v[8:9]
	v_mov_b32_e32 v3, v1
	v_lshl_add_u64 v[2:3], v[8:9], 0, v[2:3]
	v_add_co_u32_e32 v2, vcc, 0x2c00000, v2
	s_nop 1
	v_addc_co_u32_e32 v3, vcc, 0, v3, vcc
	global_load_dwordx4 v[26:29], v[2:3], off offset:3072
	v_mul_lo_u32 v2, v77, 6
	v_sub_u32_e32 v72, v10, v2
	v_mul_lo_u16_e32 v2, 0x56, v72
	v_lshrrev_b16_e32 v3, 15, v2
	v_add_u16_sdwa v2, v2, v3 dst_sel:DWORD dst_unused:UNUSED_PAD src0_sel:BYTE_1 src1_sel:DWORD
	v_bfe_i32 v63, v2, 0, 8
	v_mul_lo_u16_e32 v2, 3, v2
	v_sub_u16_e32 v2, v72, v2
	v_bfe_i32 v64, v2, 0, 8
	v_lshl_or_b32 v56, v64, 4, v43
	v_cmp_eq_u32_e32 vcc, v6, v63
	v_ashrrev_i32_e32 v57, 31, v56
	s_nop 1
	v_cndmask_b32_e64 v142, 0, -1, vcc
	v_mov_b32_e32 v11, 0
	v_mul_u32_u24_e32 v2, 0x300, v7
	v_mov_b32_e32 v3, v1
	v_lshl_add_u64 v[2:3], s[16:17], 0, v[2:3]
	v_lshl_add_u64 v[2:3], v[2:3], 0, s[56:57]
	v_lshl_add_u64 v[2:3], v[56:57], 2, v[2:3]
	global_load_dword v132, v[2:3], off offset:768
	global_load_dword v133, v[2:3], off
	global_load_dword v134, v[2:3], off offset:2304
	global_load_dword v135, v[2:3], off offset:1536
	global_load_dword v136, v[2:3], off offset:3840
	global_load_dword v137, v[2:3], off offset:3072
	v_add_co_u32_e32 v2, vcc, 0x1000, v2
	s_nop 1
	v_addc_co_u32_e32 v3, vcc, 0, v3, vcc
	global_load_dword v138, v[2:3], off offset:1280
	s_nop 0
	global_load_dword v139, v[2:3], off offset:512
	v_add_u32_e32 v2, s94, v63
	v_mul_i32_i24_e32 v2, 0xc0, v2
	v_ashrrev_i32_e32 v3, 31, v2
	v_lshl_add_u64 v[2:3], v[2:3], 2, s[18:19]
	v_lshl_add_u64 v[2:3], v[2:3], 0, s[56:57]
	v_lshl_add_u64 v[2:3], v[56:57], 2, v[2:3]
	global_load_dword v80, v[2:3], off
	v_mul_hi_i32 v53, v60, s77
	v_lshrrev_b32_e32 v55, 31, v53
	v_add_u32_e32 v57, v53, v55
	v_mul_lo_u32 v2, v57, 6
	v_sub_u32_e32 v2, v60, v2
	v_mul_lo_u16_e32 v3, 0x56, v2
	v_lshrrev_b16_e32 v5, 15, v3
	v_add_u16_sdwa v5, v3, v5 dst_sel:DWORD dst_unused:UNUSED_PAD src0_sel:BYTE_1 src1_sel:DWORD
	v_mul_lo_u16_e32 v3, 3, v5
	v_sub_u16_e32 v3, v2, v3
	v_lshlrev_b32_sdwa v3, v240, sext(v3) dst_sel:DWORD dst_unused:UNUSED_PAD src0_sel:DWORD src1_sel:BYTE_0
	v_mul_lo_u16_e32 v5, 24, v5
	s_movk_i32 s4, 0x180
	v_add_u32_sdwa v46, v3, sext(v5) dst_sel:DWORD dst_unused:UNUSED_PAD src0_sel:DWORD src1_sel:BYTE_0
	v_cmp_gt_i32_e64 s[16:17], s4, v60
	v_mov_b32_e32 v10, 1.0
	v_mov_b32_e32 v12, 1.0
	v_mov_b32_e32 v13, 0
	v_mov_b32_e32 v14, 1.0
	v_mov_b32_e32 v15, 0
	v_mov_b32_e32 v16, 1.0
	v_mov_b32_e32 v17, 0
	v_mov_b32_e32 v48, 0
	v_mov_b32_e32 v49, 0
	v_mov_b32_e32 v50, 0
	v_mov_b32_e32 v51, 0
	s_and_saveexec_b64 s[18:19], s[16:17]
	s_cbranch_execz .LBB0_690
	v_add_u32_e32 v5, s15, v57
	v_mov_b64_e32 v[6:7], s[8:9]
	v_mad_i64_i32 v[6:7], s[4:5], v5, s86, v[6:7]
	s_lshl_b32 s56, s27, 1
	v_lshl_add_u64 v[6:7], v[6:7], 0, s[56:57]
	v_ashrrev_i32_e32 v47, 31, v46
	v_lshl_add_u64 v[6:7], v[46:47], 1, v[6:7]
	s_mov_b64 s[4:5], 0x2c00780
	v_lshl_add_u64 v[8:9], v[6:7], 0, s[4:5]
	v_add_co_u32_e32 v6, vcc, 0x2c00000, v6
	s_nop 1
	v_addc_co_u32_e32 v7, vcc, 0, v7, vcc
	global_load_dwordx2 v[50:51], v[6:7], off offset:1920
	global_load_dwordx2 v[48:49], v[8:9], off offset:24
	s_andn2_b64 vcc, exec, s[22:23]
	s_cbranch_vccnz .LBB0_689
	v_add_u32_e32 v2, 2, v2
	v_mov_b32_e32 v5, s6
	v_cmp_gt_u32_e32 vcc, 5, v2
	s_mov_b64 s[4:5], 0xfab8000
	s_nop 0
	v_cndmask_b32_e32 v2, v57, v5, vcc
	v_mul_lo_u32 v2, v2, 12
	v_add_lshl_u32 v2, v2, v3, 1
	v_ashrrev_i32_e32 v3, 31, v2
	v_lshl_add_u64 v[2:3], v[2:3], 2, s[8:9]
	v_lshl_add_u64 v[6:7], v[2:3], 0, s[4:5]
	v_add_co_u32_e32 v2, vcc, 0xfab8000, v2
	s_nop 1
	v_addc_co_u32_e32 v3, vcc, 0, v3, vcc
	global_load_dwordx4 v[14:17], v[2:3], off
	global_load_dwordx4 v[10:13], v[6:7], off offset:16
	s_branch .LBB0_690

; #define LAS __attribute__((address_space(3)))
; __device__ __forceinline__ unsigned pk_bf16(float lo, float hi) { unsigned r; asm volatile("v_cvt_pk_bf16_f32 %0, %1, %2" : "=v"(r) : "v"(lo), "v"(hi)); return r; }
; __device__ __forceinline__ f32x4 mfma16(bf16x8 a, bf16x8 b, f32x4 c) { return __builtin_amdgcn_mfma_f32_16x16x32_bf16(a, b, c, 0, 0, 0); }
; __device__ __forceinline__ void gla_prep(const PrepRegs& R, LAS unsigned char* lds, int wave, int fr, int fq) {
;     LAS float* G = (LAS float*)(lds + GL_G);
;     __syncthreads();
; #pragma unroll
;     for (int q = 0; q < 3; ++q) { const int tile = wave * 3 + q, mi = tile / 6, ni = tile % 6, dir = ni / 3, c = (ni % 3) * 16 + fr;
;         const f32x4 acc = mfma16(as_bf8(R.ga[q]), as_bf8(R.bw[q]), (f32x4){0.f, 0.f, 0.f, 0.f});
;         float g[4];
; #pragma unroll
;         for (int i = 0; i < 4; ++i) { const float sv = acc[i] + R.bias[q]; g[i] = (fminf(sv, 0.f) - __logf(1.f + __expf(-fabsf(sv)))) * (1.0f / 16.0f); }
;         u32x2 w2; w2.x = pk_bf16(g[0], g[1]); w2.y = pk_bf16(g[2], g[3]);
;         *(LAS u32x2*)(lds + GL_GT + (dir * 48 + c) * 144 + (mi * 16 + fq * 4) * 2) = w2; }
.LBB0_698:
	s_or_b64 exec, exec, s[4:5]
	s_waitcnt vmcnt(1)
	v_cvt_pk_bf16_f32 v30, v113, v112
	v_cvt_pk_bf16_f32 v31, v115, v114
	v_cvt_pk_bf16_f32 v32, v117, v116
	v_cvt_pk_bf16_f32 v33, v119, v118
	v_and_b32_e32 v30, v140, v30
	v_and_b32_e32 v31, v140, v31
	v_and_b32_e32 v32, v140, v32
	v_and_b32_e32 v33, v140, v33
	v_cvt_pk_bf16_f32 v34, v121, v120
	v_cvt_pk_bf16_f32 v35, v123, v122
	v_cvt_pk_bf16_f32 v36, v125, v124
	v_cvt_pk_bf16_f32 v37, v127, v126
	v_and_b32_e32 v34, v141, v34
	v_and_b32_e32 v35, v141, v35
	v_and_b32_e32 v36, v141, v36
	v_and_b32_e32 v37, v141, v37
	v_cvt_pk_bf16_f32 v38, v133, v132
	v_cvt_pk_bf16_f32 v39, v135, v134
	v_cvt_pk_bf16_f32 v40, v137, v136
	v_cvt_pk_bf16_f32 v41, v139, v138
	v_and_b32_e32 v38, v142, v38
	v_and_b32_e32 v39, v142, v39
	v_and_b32_e32 v40, v142, v40
	v_and_b32_e32 v41, v142, v41
	v_mfma_f32_16x16x32_bf16 v[18:21], v[18:21], v[30:33], 0
	s_barrier
	v_or_b32_e32 v33, 2, v61
	v_or_b32_e32 v47, 34, v61
	s_waitcnt vmcnt(4)
	s_nop 3
	v_add_f32_e32 v18, v78, v18
	v_mul_f32_e64 v30, |v18|, s33
	v_exp_f32_e32 v30, v30
	v_add_f32_e32 v19, v78, v19
	v_min_f32_e32 v18, 0, v18
	v_add_f32_e32 v20, v78, v20
	v_add_f32_e32 v30, 1.0, v30
	v_cmp_gt_f32_e64 s[18:19], s68, v30
	v_add_f32_e32 v21, v78, v21
	v_or_b32_e32 v58, 37, v61
	v_cndmask_b32_e64 v31, 0, 32, s[18:19]
	v_ldexp_f32 v30, v30, v31
	v_log_f32_e32 v30, v30
	v_mul_f32_e64 v31, |v19|, s33
	v_exp_f32_e32 v31, v31
	v_min_f32_e32 v19, 0, v19
	v_mul_f32_e32 v32, 0x3f317217, v30
	v_fma_f32 v32, v30, s2, -v32
	v_fmac_f32_e32 v32, 0x3377d1cf, v30
	v_fmac_f32_e32 v32, 0x3f317217, v30
	v_cmp_lt_f32_e64 s[20:21], |v30|, s83
	v_add_f32_e32 v31, 1.0, v31
	s_nop 0
	v_cndmask_b32_e64 v30, v30, v32, s[20:21]
	v_cndmask_b32_e64 v32, 0, v241, s[18:19]
	v_cmp_gt_f32_e64 s[18:19], s68, v31
	v_sub_f32_e32 v30, v30, v32
	v_sub_f32_e32 v18, v18, v30
	v_cndmask_b32_e64 v32, 0, 32, s[18:19]
	v_ldexp_f32 v31, v31, v32
	v_log_f32_e32 v31, v31
	v_mul_f32_e64 v32, |v20|, s33
	v_exp_f32_e32 v32, v32
	v_min_f32_e32 v20, 0, v20
	v_mul_f32_e32 v30, 0x3f317217, v31
	v_fma_f32 v30, v31, s2, -v30
	v_fmac_f32_e32 v30, 0x3377d1cf, v31
	v_fmac_f32_e32 v30, 0x3f317217, v31
	v_cmp_lt_f32_e64 s[20:21], |v31|, s83
	v_mul_f32_e32 v18, 0x3d800000, v18
	s_nop 0
	v_cndmask_b32_e64 v30, v31, v30, s[20:21]
	v_cndmask_b32_e64 v31, 0, v241, s[18:19]
	v_sub_f32_e32 v30, v30, v31
	v_add_f32_e32 v31, 1.0, v32
	v_cmp_gt_f32_e64 s[18:19], s68, v31
	v_sub_f32_e32 v19, v19, v30
	v_mul_f32_e32 v19, 0x3d800000, v19
	v_cndmask_b32_e64 v32, 0, 32, s[18:19]
	v_ldexp_f32 v31, v31, v32
	v_log_f32_e32 v31, v31
	v_mul_f32_e64 v32, |v21|, s33
	v_exp_f32_e32 v32, v32
	v_min_f32_e32 v21, 0, v21
	v_mul_f32_e32 v30, 0x3f317217, v31
	v_fma_f32 v30, v31, s2, -v30
	v_fmac_f32_e32 v30, 0x3377d1cf, v31
	v_fmac_f32_e32 v30, 0x3f317217, v31
	v_cmp_lt_f32_e64 s[20:21], |v31|, s83
	s_nop 1
	v_cndmask_b32_e64 v30, v31, v30, s[20:21]
	v_cndmask_b32_e64 v31, 0, v241, s[18:19]
	v_sub_f32_e32 v30, v30, v31
	v_add_f32_e32 v31, 1.0, v32
	v_cmp_gt_f32_e64 s[18:19], s68, v31
	v_sub_f32_e32 v20, v20, v30
	v_mul_f32_e32 v20, 0x3d800000, v20
	v_cndmask_b32_e64 v32, 0, 32, s[18:19]
	v_ldexp_f32 v31, v31, v32
	v_log_f32_e32 v31, v31
	v_mad_i32_i24 v32, v70, 48, v52
	v_or_b32_e32 v52, 35, v61
	v_mul_f32_e32 v30, 0x3f317217, v31
	v_fma_f32 v30, v31, s2, -v30
	v_fmac_f32_e32 v30, 0x3377d1cf, v31
	v_fmac_f32_e32 v30, 0x3f317217, v31
	v_cmp_lt_f32_e64 s[20:21], |v31|, s83
	s_nop 1
	v_cndmask_b32_e64 v30, v31, v30, s[20:21]
	v_cndmask_b32_e64 v31, 0, v241, s[18:19]
	v_sub_f32_e32 v30, v30, v31
	v_sub_f32_e32 v21, v21, v30
	v_mul_f32_e32 v21, 0x3d800000, v21
	v_cvt_pk_bf16_f32 v30, v18, v19
	v_cvt_pk_bf16_f32 v31, v20, v21
	s_waitcnt vmcnt(3)
	v_mfma_f32_16x16x32_bf16 v[18:21], v[22:25], v[34:37], 0
	v_mul_lo_u32 v23, v32, s55
	v_add_u32_e32 v23, 0, v23
	v_lshlrev_b32_e32 v24, 5, v75
	v_add3_u32 v23, v23, v24, v61
	ds_write_b64 v23, v[30:31]
	s_waitcnt vmcnt(2)
	s_nop 1
	v_add_f32_e32 v18, v79, v18
	v_mul_f32_e64 v22, |v18|, s33
	v_exp_f32_e32 v22, v22
	v_add_f32_e32 v19, v79, v19
	v_mul_f32_e64 v24, |v19|, s33
	v_exp_f32_e32 v24, v24
	v_add_f32_e32 v22, 1.0, v22
	v_cmp_gt_f32_e64 s[18:19], s68, v22
	v_min_f32_e32 v18, 0, v18
	v_add_f32_e32 v20, v79, v20
	v_cndmask_b32_e64 v25, 0, 32, s[18:19]
	v_ldexp_f32 v22, v22, v25
	v_log_f32_e32 v22, v22
	v_min_f32_e32 v19, 0, v19
	v_add_f32_e32 v21, v79, v21
	v_or_b32_e32 v32, 1, v61
	v_mul_f32_e32 v23, 0x3f317217, v22
	v_fma_f32 v23, v22, s2, -v23
	v_fmac_f32_e32 v23, 0x3377d1cf, v22
	v_fmac_f32_e32 v23, 0x3f317217, v22
	v_cmp_lt_f32_e64 s[20:21], |v22|, s83
	v_or_b32_e32 v34, 3, v61
	v_or_b32_e32 v35, 4, v61
	v_cndmask_b32_e64 v22, v22, v23, s[20:21]
	v_cndmask_b32_e64 v23, 0, v241, s[18:19]
	v_sub_f32_e32 v22, v22, v23
	v_add_f32_e32 v23, 1.0, v24
	v_cmp_gt_f32_e64 s[18:19], s68, v23
	v_sub_f32_e32 v18, v18, v22
	v_mul_f32_e32 v18, 0x3d800000, v18
	v_cndmask_b32_e64 v24, 0, 32, s[18:19]
	v_ldexp_f32 v23, v23, v24
	v_log_f32_e32 v23, v23
	v_mul_f32_e64 v24, |v20|, s33
	v_exp_f32_e32 v24, v24
	v_min_f32_e32 v20, 0, v20
	v_mul_f32_e32 v22, 0x3f317217, v23
	v_fma_f32 v22, v23, s2, -v22
	v_fmac_f32_e32 v22, 0x3377d1cf, v23
	v_fmac_f32_e32 v22, 0x3f317217, v23
	v_cmp_lt_f32_e64 s[20:21], |v23|, s83
	v_or_b32_e32 v36, 5, v61
	v_or_b32_e32 v37, 6, v61
	v_cndmask_b32_e64 v22, v23, v22, s[20:21]
	v_cndmask_b32_e64 v23, 0, v241, s[18:19]
	v_sub_f32_e32 v22, v22, v23
	v_add_f32_e32 v23, 1.0, v24
	v_cmp_gt_f32_e64 s[18:19], s68, v23
	v_sub_f32_e32 v19, v19, v22
	v_mul_f32_e32 v19, 0x3d800000, v19
	v_cndmask_b32_e64 v24, 0, 32, s[18:19]
	v_ldexp_f32 v23, v23, v24
	v_log_f32_e32 v23, v23
	v_mul_f32_e64 v24, |v21|, s33
	v_exp_f32_e32 v24, v24
	v_min_f32_e32 v21, 0, v21
	v_mul_f32_e32 v22, 0x3f317217, v23
	v_fma_f32 v22, v23, s2, -v22
	v_fmac_f32_e32 v22, 0x3377d1cf, v23
	v_fmac_f32_e32 v22, 0x3f317217, v23
	v_cmp_lt_f32_e64 s[20:21], |v23|, s83
	s_nop 1
	v_cndmask_b32_e64 v22, v23, v22, s[20:21]
	v_cndmask_b32_e64 v23, 0, v241, s[18:19]
	v_sub_f32_e32 v22, v22, v23
	v_add_f32_e32 v23, 1.0, v24
	v_cmp_gt_f32_e64 s[18:19], s68, v23
	v_sub_f32_e32 v20, v20, v22
	v_mul_f32_e32 v20, 0x3d800000, v20
	v_cndmask_b32_e64 v24, 0, 32, s[18:19]
	v_ldexp_f32 v23, v23, v24
	v_log_f32_e32 v23, v23
	v_mad_i32_i24 v24, v66, 48, v54
	v_mul_lo_u32 v24, v24, s55
	v_add_u32_e32 v24, 0, v24
	v_mul_f32_e32 v22, 0x3f317217, v23
	v_fma_f32 v22, v23, s2, -v22
	v_fmac_f32_e32 v22, 0x3377d1cf, v23
	v_fmac_f32_e32 v22, 0x3f317217, v23
	v_cmp_lt_f32_e64 s[20:21], |v23|, s83
	s_nop 1
	v_cndmask_b32_e64 v22, v23, v22, s[20:21]
	v_cndmask_b32_e64 v23, 0, v241, s[18:19]
	v_sub_f32_e32 v22, v22, v23
	v_sub_f32_e32 v21, v21, v22
	v_mul_f32_e32 v21, 0x3d800000, v21
	v_cvt_pk_bf16_f32 v22, v18, v19
	v_cvt_pk_bf16_f32 v23, v20, v21
	s_waitcnt vmcnt(1)
; #define LAS __attribute__((address_space(3)))
; __device__ __forceinline__ unsigned pk_bf16(float lo, float hi) { unsigned r; asm volatile("v_cvt_pk_bf16_f32 %0, %1, %2" : "=v"(r) : "v"(lo), "v"(hi)); return r; }
; __device__ __forceinline__ f32x4 mfma16(bf16x8 a, bf16x8 b, f32x4 c) { return __builtin_amdgcn_mfma_f32_16x16x32_bf16(a, b, c, 0, 0, 0); }
; __device__ __forceinline__ void gla_prep(const PrepRegs& R, LAS unsigned char* lds, int wave, int fr, int fq) {
;     ...
;     for (int q = 0; q < 3; ++q) { const int tile = wave * 3 + q, mi = tile / 6, ni = tile % 6, dir = ni / 3, c = (ni % 3) * 16 + fr;
;         const f32x4 acc = mfma16(as_bf8(R.ga[q]), as_bf8(R.bw[q]), (f32x4){0.f, 0.f, 0.f, 0.f});
;         float g[4];
; #pragma unroll
;         for (int i = 0; i < 4; ++i) { const float sv = acc[i] + R.bias[q]; g[i] = (fminf(sv, 0.f) - __logf(1.f + __expf(-fabsf(sv)))) * (1.0f / 16.0f); }
;         u32x2 w2; w2.x = pk_bf16(g[0], g[1]); w2.y = pk_bf16(g[2], g[3]);
;         *(LAS u32x2*)(lds + GL_GT + (dir * 48 + c) * 144 + (mi * 16 + fq * 4) * 2) = w2; }
;     __syncthreads();
; #pragma unroll
;     for (int q = 0; q < 3; ++q) { const int tile = wave * 3 + q, mi = tile / 6, ni = tile % 6, dir = ni / 3;
;         f32x4 acc = (f32x4){0.f, 0.f, 0.f, 0.f};
; #pragma unroll
;         for (int kk = 0; kk < 2; ++kk) { const int t = mi * 16 + fr; bf16x8 tri;
; #pragma unroll
;             for (int e = 0; e < 8; ++e) { const int sidx = kk * 32 + fq * 8 + e; tri[e] = (dir ? (sidx >= t) : (sidx <= t)) ? (short)0x3F80 : (short)0; }
;             const bf16x8 bb = *(const LAS bf16x8*)(lds + GL_GT + (ni * 16 + fr) * 144 + kk * 64 + fq * 16);
;             acc = mfma16(tri, bb, acc); }
	v_mfma_f32_16x16x32_bf16 v[18:21], v[26:29], v[38:41], 0
	v_lshlrev_b32_e32 v26, 5, v76
	v_add3_u32 v24, v24, v26, v61
	ds_write_b64 v24, v[22:23]
	v_or_b32_e32 v38, 7, v61
	v_or_b32_e32 v39, 32, v61
	s_waitcnt vmcnt(0)
	s_nop 1
	v_add_f32_e32 v18, v80, v18
	v_mul_f32_e64 v25, |v18|, s33
	v_exp_f32_e32 v25, v25
	v_add_f32_e32 v19, v80, v19
	v_mul_f32_e64 v23, |v19|, s33
	v_exp_f32_e32 v23, v23
	v_add_f32_e32 v25, 1.0, v25
	v_cmp_gt_f32_e64 s[18:19], s68, v25
	v_min_f32_e32 v18, 0, v18
	v_add_f32_e32 v23, 1.0, v23
	v_cndmask_b32_e64 v27, 0, 32, s[18:19]
	v_ldexp_f32 v25, v25, v27
	v_log_f32_e32 v25, v25
	v_cndmask_b32_e64 v24, 0, v241, s[18:19]
	v_cmp_gt_f32_e64 s[18:19], s68, v23
	v_add_f32_e32 v20, v80, v20
	v_mul_f32_e32 v22, 0x3f317217, v25
	v_fma_f32 v22, v25, s2, -v22
	v_fmac_f32_e32 v22, 0x3377d1cf, v25
	v_fmac_f32_e32 v22, 0x3f317217, v25
	v_cmp_lt_f32_e64 s[20:21], |v25|, s83
	v_min_f32_e32 v19, 0, v19
	v_add_f32_e32 v21, v80, v21
	v_cndmask_b32_e64 v22, v25, v22, s[20:21]
	v_sub_f32_e32 v22, v22, v24
	v_cndmask_b32_e64 v24, 0, 32, s[18:19]
	v_ldexp_f32 v23, v23, v24
	v_log_f32_e32 v23, v23
	v_sub_f32_e32 v18, v18, v22
	v_mul_f32_e64 v24, |v20|, s33
	v_exp_f32_e32 v24, v24
	v_mul_f32_e32 v22, 0x3f317217, v23
	v_fma_f32 v22, v23, s2, -v22
	v_fmac_f32_e32 v22, 0x3377d1cf, v23
	v_fmac_f32_e32 v22, 0x3f317217, v23
	v_cmp_lt_f32_e64 s[20:21], |v23|, s83
	v_min_f32_e32 v20, 0, v20
	v_mul_f32_e32 v18, 0x3d800000, v18
	v_cndmask_b32_e64 v22, v23, v22, s[20:21]
	v_cndmask_b32_e64 v23, 0, v241, s[18:19]
	v_sub_f32_e32 v22, v22, v23
	v_add_f32_e32 v23, 1.0, v24
	v_cmp_gt_f32_e64 s[18:19], s68, v23
	v_sub_f32_e32 v19, v19, v22
	v_mul_f32_e32 v19, 0x3d800000, v19
	v_cndmask_b32_e64 v24, 0, 32, s[18:19]
	v_ldexp_f32 v23, v23, v24
	v_log_f32_e32 v23, v23
	v_mul_f32_e64 v24, |v21|, s33
	v_exp_f32_e32 v24, v24
	v_min_f32_e32 v21, 0, v21
	v_mul_f32_e32 v22, 0x3f317217, v23
	v_fma_f32 v22, v23, s2, -v22
	v_fmac_f32_e32 v22, 0x3377d1cf, v23
	v_fmac_f32_e32 v22, 0x3f317217, v23
	v_cmp_lt_f32_e64 s[20:21], |v23|, s83
	v_cvt_pk_bf16_f32 v18, v18, v19
	v_or_b32_e32 v40, 33, v61
	s_nop 0
	v_cndmask_b32_e64 v22, v23, v22, s[20:21]
	v_cndmask_b32_e64 v23, 0, v241, s[18:19]
	v_sub_f32_e32 v22, v22, v23
	v_add_f32_e32 v23, 1.0, v24
	v_cmp_gt_f32_e64 s[18:19], s68, v23
	v_sub_f32_e32 v20, v20, v22
	v_mul_f32_e32 v20, 0x3d800000, v20
	v_cndmask_b32_e64 v24, 0, 32, s[18:19]
	v_ldexp_f32 v23, v23, v24
	v_log_f32_e32 v23, v23
	s_nop 0
	v_mul_f32_e32 v22, 0x3f317217, v23
	v_fma_f32 v22, v23, s2, -v22
	v_fmac_f32_e32 v22, 0x3377d1cf, v23
	v_fmac_f32_e32 v22, 0x3f317217, v23
	v_cmp_lt_f32_e64 s[20:21], |v23|, s83
	s_nop 1
	v_cndmask_b32_e64 v22, v23, v22, s[20:21]
	v_cndmask_b32_e64 v23, 0, v241, s[18:19]
	v_sub_f32_e32 v22, v22, v23
	v_sub_f32_e32 v21, v21, v22
	v_mul_f32_e32 v21, 0x3d800000, v21
	v_cvt_pk_bf16_f32 v19, v20, v21
	v_mad_i32_i24 v20, v63, 48, v56
	v_mul_lo_u32 v20, v20, s55
	v_add_u32_e32 v20, 0, v20
	v_lshlrev_b32_e32 v21, 5, v77
	v_add3_u32 v20, v20, v21, v61
	ds_write_b64 v20, v[18:19]
	v_or_b32_e32 v19, v69, v43
	v_add_u32_e32 v18, 0, v0
	v_lshl_or_b32 v21, v74, 4, v43
	v_cmp_le_i32_e64 s[18:19], v61, v19
	v_add_u32_e32 v20, 2, v74
	v_mad_i32_i24 v28, v21, s55, v18
	v_cndmask_b32_e64 v21, 0, 1, s[18:19]
	v_cmp_ge_i32_e64 s[18:19], v61, v19
	s_waitcnt lgkmcnt(0)
	s_barrier
	v_cndmask_b32_e64 v22, 0, 1, s[18:19]
	v_cmp_gt_u32_e64 s[18:19], 5, v20
	v_or_b32_e32 v56, 36, v61
	s_nop 0
	v_cndmask_b32_e64 v20, v22, v21, s[18:19]
	v_and_b32_e32 v20, 1, v20
	v_cmp_eq_u32_e64 s[20:21], 1, v20
	v_or_b32_e32 v74, 38, v61
	s_nop 0
	v_cndmask_b32_e64 v20, 0, v242, s[20:21]
	v_cmp_ge_i32_e64 s[20:21], v32, v19
	s_nop 1
	v_cndmask_b32_e64 v21, 0, 1, s[20:21]
	v_cmp_lt_i32_e64 s[20:21], v61, v19
	s_nop 1
	v_cndmask_b32_e64 v22, 0, 1, s[20:21]
	v_cndmask_b32_e64 v21, v21, v22, s[18:19]
	v_and_b32_e32 v21, 1, v21
	v_cmp_eq_u32_e64 s[20:21], 1, v21
	s_nop 1
	v_cndmask_b32_e64 v24, 0, v242, s[20:21]
	v_cmp_le_i32_e64 s[20:21], v33, v19
	v_perm_b32 v20, v24, v20, s62
	s_nop 0
	v_cndmask_b32_e64 v21, 0, 1, s[20:21]
	v_cmp_ge_i32_e64 s[20:21], v33, v19
	s_nop 1
	v_cndmask_b32_e64 v22, 0, 1, s[20:21]
	v_cndmask_b32_e64 v21, v22, v21, s[18:19]
	v_and_b32_e32 v21, 1, v21
	v_cmp_eq_u32_e64 s[20:21], 1, v21
	s_nop 1
	v_cndmask_b32_e64 v21, 0, v242, s[20:21]
	v_cmp_le_i32_e64 s[20:21], v34, v19
	s_nop 1
	v_cndmask_b32_e64 v22, 0, 1, s[20:21]
	v_cmp_ge_i32_e64 s[20:21], v34, v19
	s_nop 1
	v_cndmask_b32_e64 v23, 0, 1, s[20:21]
	v_cndmask_b32_e64 v22, v23, v22, s[18:19]
	v_and_b32_e32 v22, 1, v22
	v_cmp_eq_u32_e64 s[20:21], 1, v22
	s_nop 1
	v_cndmask_b32_e64 v25, 0, v242, s[20:21]
	v_cmp_le_i32_e64 s[20:21], v35, v19
	v_perm_b32 v21, v25, v21, s62
	s_nop 0
	v_cndmask_b32_e64 v22, 0, 1, s[20:21]
	v_cmp_ge_i32_e64 s[20:21], v35, v19
	s_nop 1
	v_cndmask_b32_e64 v23, 0, 1, s[20:21]
	v_cndmask_b32_e64 v22, v23, v22, s[18:19]
	v_and_b32_e32 v22, 1, v22
	v_cmp_eq_u32_e64 s[20:21], 1, v22
	s_nop 1
	v_cndmask_b32_e64 v22, 0, v242, s[20:21]
	v_cmp_le_i32_e64 s[20:21], v36, v19
	s_nop 1
	v_cndmask_b32_e64 v23, 0, 1, s[20:21]
	v_cmp_ge_i32_e64 s[20:21], v36, v19
	s_nop 1
	v_cndmask_b32_e64 v26, 0, 1, s[20:21]
	v_cndmask_b32_e64 v23, v26, v23, s[18:19]
	v_and_b32_e32 v23, 1, v23
	v_cmp_eq_u32_e64 s[20:21], 1, v23
	s_nop 1
	v_cndmask_b32_e64 v26, 0, v242, s[20:21]
	v_cmp_le_i32_e64 s[20:21], v37, v19
	v_perm_b32 v22, v26, v22, s62
	s_nop 0
	v_cndmask_b32_e64 v23, 0, 1, s[20:21]
	v_cmp_ge_i32_e64 s[20:21], v37, v19
	s_nop 1
	v_cndmask_b32_e64 v27, 0, 1, s[20:21]
	v_cndmask_b32_e64 v23, v27, v23, s[18:19]
	v_and_b32_e32 v23, 1, v23
	v_cmp_eq_u32_e64 s[20:21], 1, v23
	s_nop 1
	v_cndmask_b32_e64 v23, 0, v242, s[20:21]
	v_cmp_le_i32_e64 s[20:21], v38, v19
	s_nop 1
	v_cndmask_b32_e64 v27, 0, 1, s[20:21]
	v_cmp_ge_i32_e64 s[20:21], v38, v19
	s_nop 1
	v_cndmask_b32_e64 v29, 0, 1, s[20:21]
	v_cndmask_b32_e64 v27, v29, v27, s[18:19]
	v_and_b32_e32 v27, 1, v27
	v_cmp_eq_u32_e64 s[20:21], 1, v27
	s_nop 1
	v_cndmask_b32_e64 v27, 0, v242, s[20:21]
	v_perm_b32 v23, v27, v23, s62
	ds_read_b128 v[24:27], v28
	ds_read_b128 v[28:31], v28 offset:64
	v_cmp_le_i32_e64 s[20:21], v39, v19
	s_waitcnt lgkmcnt(1)
; #define LAS __attribute__((address_space(3)))
; __device__ __forceinline__ f32x4 mfma16(bf16x8 a, bf16x8 b, f32x4 c) { return __builtin_amdgcn_mfma_f32_16x16x32_bf16(a, b, c, 0, 0, 0); }
; __device__ __forceinline__ void gla_prep(const PrepRegs& R, LAS unsigned char* lds, int wave, int fr, int fq) {
;     ...
;     for (int q = 0; q < 3; ++q) { const int tile = wave * 3 + q, mi = tile / 6, ni = tile % 6, dir = ni / 3;
;         f32x4 acc = (f32x4){0.f, 0.f, 0.f, 0.f};
; #pragma unroll
;         for (int kk = 0; kk < 2; ++kk) { const int t = mi * 16 + fr; bf16x8 tri;
; #pragma unroll
;             for (int e = 0; e < 8; ++e) { const int sidx = kk * 32 + fq * 8 + e; tri[e] = (dir ? (sidx >= t) : (sidx <= t)) ? (short)0x3F80 : (short)0; }
;             const bf16x8 bb = *(const LAS bf16x8*)(lds + GL_GT + (ni * 16 + fr) * 144 + kk * 64 + fq * 16);
;             acc = mfma16(tri, bb, acc); }
; #pragma unroll
;         for (int i = 0; i < 4; ++i) G[(dir * 64 + mi * 16 + fq * 4 + i) * 48 + (ni % 3) * 16 + fr] = acc[i]; }
	v_mfma_f32_16x16x32_bf16 v[20:23], v[20:23], v[24:27], 0
	v_cndmask_b32_e64 v24, 0, 1, s[20:21]
	v_cmp_ge_i32_e64 s[20:21], v39, v19
	s_nop 1
	v_cndmask_b32_e64 v25, 0, 1, s[20:21]
	v_cndmask_b32_e64 v24, v25, v24, s[18:19]
	v_and_b32_e32 v24, 1, v24
	v_cmp_eq_u32_e64 s[20:21], 1, v24
	s_nop 1
	v_cndmask_b32_e64 v24, 0, v242, s[20:21]
	v_cmp_le_i32_e64 s[20:21], v40, v19
	s_nop 1
	v_cndmask_b32_e64 v25, 0, 1, s[20:21]
	v_cmp_ge_i32_e64 s[20:21], v40, v19
	s_nop 1
	v_cndmask_b32_e64 v26, 0, 1, s[20:21]
	v_cndmask_b32_e64 v25, v26, v25, s[18:19]
	v_and_b32_e32 v25, 1, v25
	v_cmp_eq_u32_e64 s[20:21], 1, v25
	s_nop 1
	v_cndmask_b32_e64 v41, 0, v242, s[20:21]
	v_cmp_le_i32_e64 s[20:21], v47, v19
	v_perm_b32 v24, v41, v24, s62
	v_lshl_add_u32 v41, v43, 2, 0
	v_cndmask_b32_e64 v25, 0, 1, s[20:21]
	v_cmp_ge_i32_e64 s[20:21], v47, v19
	s_nop 1
	v_cndmask_b32_e64 v26, 0, 1, s[20:21]
	v_cndmask_b32_e64 v25, v26, v25, s[18:19]
	v_and_b32_e32 v25, 1, v25
	v_cmp_eq_u32_e64 s[20:21], 1, v25
	s_nop 1
	v_cndmask_b32_e64 v25, 0, v242, s[20:21]
	v_cmp_le_i32_e64 s[20:21], v52, v19
	s_nop 1
	v_cndmask_b32_e64 v26, 0, 1, s[20:21]
	v_cmp_ge_i32_e64 s[20:21], v52, v19
	s_nop 1
	v_cndmask_b32_e64 v27, 0, 1, s[20:21]
	v_cndmask_b32_e64 v26, v27, v26, s[18:19]
	v_and_b32_e32 v26, 1, v26
	v_cmp_eq_u32_e64 s[20:21], 1, v26
	s_nop 1
	v_cndmask_b32_e64 v54, 0, v242, s[20:21]
	v_cmp_le_i32_e64 s[20:21], v56, v19
	v_perm_b32 v25, v54, v25, s62
	v_or_b32_e32 v54, v65, v43
	v_cndmask_b32_e64 v26, 0, 1, s[20:21]
	v_cmp_ge_i32_e64 s[20:21], v56, v19
	s_nop 1
	v_cndmask_b32_e64 v27, 0, 1, s[20:21]
	v_cndmask_b32_e64 v26, v27, v26, s[18:19]
	v_and_b32_e32 v26, 1, v26
	v_cmp_eq_u32_e64 s[20:21], 1, v26
	s_nop 1
	v_cndmask_b32_e64 v26, 0, v242, s[20:21]
	v_cmp_le_i32_e64 s[20:21], v58, v19
	s_nop 1
	v_cndmask_b32_e64 v27, 0, 1, s[20:21]
	v_cmp_ge_i32_e64 s[20:21], v58, v19
	s_nop 1
	v_cndmask_b32_e64 v59, 0, 1, s[20:21]
	v_cndmask_b32_e64 v27, v59, v27, s[18:19]
	v_and_b32_e32 v27, 1, v27
	v_cmp_eq_u32_e64 s[20:21], 1, v27
	s_nop 1
	v_cndmask_b32_e64 v59, 0, v242, s[20:21]
	v_cmp_le_i32_e64 s[20:21], v74, v19
	v_perm_b32 v26, v59, v26, s62
	s_nop 0
	v_cndmask_b32_e64 v27, 0, 1, s[20:21]
	v_cmp_ge_i32_e64 s[20:21], v74, v19
	s_nop 1
	v_cndmask_b32_e64 v75, 0, 1, s[20:21]
	v_cndmask_b32_e64 v27, v75, v27, s[18:19]
	v_and_b32_e32 v27, 1, v27
	v_cmp_eq_u32_e64 s[20:21], 1, v27
	v_or_b32_e32 v75, 39, v61
	s_nop 0
	v_cndmask_b32_e64 v27, 0, v242, s[20:21]
	v_cmp_le_i32_e64 s[20:21], v75, v19
	s_nop 1
	v_cndmask_b32_e64 v76, 0, 1, s[20:21]
	v_cmp_ge_i32_e64 s[20:21], v75, v19
	s_nop 1
	v_cndmask_b32_e64 v19, 0, 1, s[20:21]
	v_cndmask_b32_e64 v19, v19, v76, s[18:19]
	v_and_b32_e32 v19, 1, v19
	v_cmp_eq_u32_e64 s[18:19], 1, v19
	s_nop 1
	v_cndmask_b32_e64 v19, 0, v242, s[18:19]
	v_perm_b32 v27, v19, v27, s62
	v_lshlrev_b32_e32 v19, 2, v68
	v_cmp_le_i32_e64 s[18:19], v61, v54
	s_waitcnt lgkmcnt(0)
	v_mfma_f32_16x16x32_bf16 v[20:23], v[24:27], v[28:31], v[20:23]
	v_lshl_add_u32 v24, v70, 6, v69
	v_or_b32_e32 v24, v24, v19
	v_lshlrev_b32_e32 v25, 6, v71
	v_mul_lo_u32 v24, v24, s69
	v_add3_u32 v24, v41, v25, v24
	v_add_u32_e32 v25, 0x3400, v24
	s_nop 1
	ds_write2_b32 v25, v20, v21 offset0:128 offset1:176
	v_add_u32_e32 v20, 0x3600, v24
	v_lshl_or_b32 v21, v73, 4, v43
	ds_write2_b32 v20, v22, v23 offset0:96 offset1:144
	v_add_u32_e32 v20, 2, v73
	v_mad_u64_u32 v[28:29], s[4:5], v21, s55, v[18:19]
	v_cndmask_b32_e64 v21, 0, 1, s[18:19]
	v_cmp_ge_i32_e64 s[18:19], v61, v54
	s_nop 1
	v_cndmask_b32_e64 v22, 0, 1, s[18:19]
	v_cmp_gt_u32_e64 s[18:19], 5, v20
	s_nop 1
	v_cndmask_b32_e64 v20, v22, v21, s[18:19]
	v_and_b32_e32 v20, 1, v20
	v_cmp_eq_u32_e64 s[20:21], 1, v20
	s_nop 1
	v_cndmask_b32_e64 v20, 0, v242, s[20:21]
	v_cmp_ge_i32_e64 s[20:21], v32, v54
	s_nop 1
	v_cndmask_b32_e64 v21, 0, 1, s[20:21]
	v_cmp_lt_i32_e64 s[20:21], v61, v54
	s_nop 1
	v_cndmask_b32_e64 v22, 0, 1, s[20:21]
	v_cndmask_b32_e64 v21, v21, v22, s[18:19]
	v_and_b32_e32 v21, 1, v21
	v_cmp_eq_u32_e64 s[20:21], 1, v21
	s_nop 1
	v_cndmask_b32_e64 v24, 0, v242, s[20:21]
	v_cmp_le_i32_e64 s[20:21], v33, v54
	v_perm_b32 v20, v24, v20, s62
	s_nop 0
	v_cndmask_b32_e64 v21, 0, 1, s[20:21]
	v_cmp_ge_i32_e64 s[20:21], v33, v54
	s_nop 1
	v_cndmask_b32_e64 v22, 0, 1, s[20:21]
	v_cndmask_b32_e64 v21, v22, v21, s[18:19]
	v_and_b32_e32 v21, 1, v21
	v_cmp_eq_u32_e64 s[20:21], 1, v21
	s_nop 1
	v_cndmask_b32_e64 v21, 0, v242, s[20:21]
	v_cmp_le_i32_e64 s[20:21], v34, v54
	s_nop 1
	v_cndmask_b32_e64 v22, 0, 1, s[20:21]
	v_cmp_ge_i32_e64 s[20:21], v34, v54
	s_nop 1
	v_cndmask_b32_e64 v23, 0, 1, s[20:21]
	v_cndmask_b32_e64 v22, v23, v22, s[18:19]
	v_and_b32_e32 v22, 1, v22
	v_cmp_eq_u32_e64 s[20:21], 1, v22
	s_nop 1
	v_cndmask_b32_e64 v25, 0, v242, s[20:21]
	v_cmp_le_i32_e64 s[20:21], v35, v54
	v_perm_b32 v21, v25, v21, s62
	s_nop 0
	v_cndmask_b32_e64 v22, 0, 1, s[20:21]
	v_cmp_ge_i32_e64 s[20:21], v35, v54
	s_nop 1
	v_cndmask_b32_e64 v23, 0, 1, s[20:21]
	v_cndmask_b32_e64 v22, v23, v22, s[18:19]
	v_and_b32_e32 v22, 1, v22
	v_cmp_eq_u32_e64 s[20:21], 1, v22
	s_nop 1
	v_cndmask_b32_e64 v22, 0, v242, s[20:21]
	v_cmp_le_i32_e64 s[20:21], v36, v54
	s_nop 1
	v_cndmask_b32_e64 v23, 0, 1, s[20:21]
	v_cmp_ge_i32_e64 s[20:21], v36, v54
	s_nop 1
	v_cndmask_b32_e64 v26, 0, 1, s[20:21]
	v_cndmask_b32_e64 v23, v26, v23, s[18:19]
	v_and_b32_e32 v23, 1, v23
	v_cmp_eq_u32_e64 s[20:21], 1, v23
	s_nop 1
	v_cndmask_b32_e64 v26, 0, v242, s[20:21]
	v_cmp_le_i32_e64 s[20:21], v37, v54
	v_perm_b32 v22, v26, v22, s62
	s_nop 0
	v_cndmask_b32_e64 v23, 0, 1, s[20:21]
	v_cmp_ge_i32_e64 s[20:21], v37, v54
	s_nop 1
	v_cndmask_b32_e64 v27, 0, 1, s[20:21]
	v_cndmask_b32_e64 v23, v27, v23, s[18:19]
	v_and_b32_e32 v23, 1, v23
	v_cmp_eq_u32_e64 s[20:21], 1, v23
	s_nop 1
	v_cndmask_b32_e64 v23, 0, v242, s[20:21]
	v_cmp_le_i32_e64 s[20:21], v38, v54
	s_nop 1
	v_cndmask_b32_e64 v27, 0, 1, s[20:21]
	v_cmp_ge_i32_e64 s[20:21], v38, v54
	s_nop 1
	v_cndmask_b32_e64 v29, 0, 1, s[20:21]
	v_cndmask_b32_e64 v27, v29, v27, s[18:19]
	v_and_b32_e32 v27, 1, v27
	v_cmp_eq_u32_e64 s[20:21], 1, v27
	s_nop 1
	v_cndmask_b32_e64 v27, 0, v242, s[20:21]
	v_perm_b32 v23, v27, v23, s62
	ds_read_b128 v[24:27], v28
	ds_read_b128 v[28:31], v28 offset:64
	v_cmp_le_i32_e64 s[20:21], v39, v54
	s_waitcnt lgkmcnt(1)
; #define LAS __attribute__((address_space(3)))
; __device__ __forceinline__ f32x4 mfma16(bf16x8 a, bf16x8 b, f32x4 c) { return __builtin_amdgcn_mfma_f32_16x16x32_bf16(a, b, c, 0, 0, 0); }
; __device__ __forceinline__ void gla_prep(const PrepRegs& R, LAS unsigned char* lds, int wave, int fr, int fq) {
;     ...
;     for (int q = 0; q < 3; ++q) { const int tile = wave * 3 + q, mi = tile / 6, ni = tile % 6, dir = ni / 3;
;         f32x4 acc = (f32x4){0.f, 0.f, 0.f, 0.f};
; #pragma unroll
;         for (int kk = 0; kk < 2; ++kk) { const int t = mi * 16 + fr; bf16x8 tri;
; #pragma unroll
;             for (int e = 0; e < 8; ++e) { const int sidx = kk * 32 + fq * 8 + e; tri[e] = (dir ? (sidx >= t) : (sidx <= t)) ? (short)0x3F80 : (short)0; }
;             const bf16x8 bb = *(const LAS bf16x8*)(lds + GL_GT + (ni * 16 + fr) * 144 + kk * 64 + fq * 16);
;             acc = mfma16(tri, bb, acc); }
; #pragma unroll
;         for (int i = 0; i < 4; ++i) G[(dir * 64 + mi * 16 + fq * 4 + i) * 48 + (ni % 3) * 16 + fr] = acc[i]; }
	v_mfma_f32_16x16x32_bf16 v[20:23], v[20:23], v[24:27], 0
	v_cndmask_b32_e64 v24, 0, 1, s[20:21]
	v_cmp_ge_i32_e64 s[20:21], v39, v54
	s_nop 1
	v_cndmask_b32_e64 v25, 0, 1, s[20:21]
	v_cndmask_b32_e64 v24, v25, v24, s[18:19]
	v_and_b32_e32 v24, 1, v24
	v_cmp_eq_u32_e64 s[20:21], 1, v24
	s_nop 1
	v_cndmask_b32_e64 v24, 0, v242, s[20:21]
	v_cmp_le_i32_e64 s[20:21], v40, v54
	s_nop 1
	v_cndmask_b32_e64 v25, 0, 1, s[20:21]
	v_cmp_ge_i32_e64 s[20:21], v40, v54
	s_nop 1
	v_cndmask_b32_e64 v26, 0, 1, s[20:21]
	v_cndmask_b32_e64 v25, v26, v25, s[18:19]
	v_and_b32_e32 v25, 1, v25
	v_cmp_eq_u32_e64 s[20:21], 1, v25
	s_nop 1
	v_cndmask_b32_e64 v59, 0, v242, s[20:21]
	v_cmp_le_i32_e64 s[20:21], v47, v54
	v_perm_b32 v24, v59, v24, s62
	s_nop 0
	v_cndmask_b32_e64 v25, 0, 1, s[20:21]
	v_cmp_ge_i32_e64 s[20:21], v47, v54
	s_nop 1
	v_cndmask_b32_e64 v26, 0, 1, s[20:21]
	v_cndmask_b32_e64 v25, v26, v25, s[18:19]
	v_and_b32_e32 v25, 1, v25
	v_cmp_eq_u32_e64 s[20:21], 1, v25
	s_nop 1
	v_cndmask_b32_e64 v25, 0, v242, s[20:21]
	v_cmp_le_i32_e64 s[20:21], v52, v54
	s_nop 1
	v_cndmask_b32_e64 v26, 0, 1, s[20:21]
	v_cmp_ge_i32_e64 s[20:21], v52, v54
	s_nop 1
	v_cndmask_b32_e64 v27, 0, 1, s[20:21]
	v_cndmask_b32_e64 v26, v27, v26, s[18:19]
	v_and_b32_e32 v26, 1, v26
	v_cmp_eq_u32_e64 s[20:21], 1, v26
	s_nop 1
	v_cndmask_b32_e64 v68, 0, v242, s[20:21]
	v_cmp_le_i32_e64 s[20:21], v56, v54
	v_perm_b32 v25, v68, v25, s62
	s_nop 0
	v_cndmask_b32_e64 v26, 0, 1, s[20:21]
	v_cmp_ge_i32_e64 s[20:21], v56, v54
	s_nop 1
	v_cndmask_b32_e64 v27, 0, 1, s[20:21]
	v_cndmask_b32_e64 v26, v27, v26, s[18:19]
	v_and_b32_e32 v26, 1, v26
	v_cmp_eq_u32_e64 s[20:21], 1, v26
	s_nop 1
	v_cndmask_b32_e64 v26, 0, v242, s[20:21]
	v_cmp_le_i32_e64 s[20:21], v58, v54
	s_nop 1
	v_cndmask_b32_e64 v27, 0, 1, s[20:21]
	v_cmp_ge_i32_e64 s[20:21], v58, v54
	s_nop 1
	v_cndmask_b32_e64 v69, 0, 1, s[20:21]
	v_cndmask_b32_e64 v27, v69, v27, s[18:19]
	v_and_b32_e32 v27, 1, v27
	v_cmp_eq_u32_e64 s[20:21], 1, v27
	s_nop 1
	v_cndmask_b32_e64 v69, 0, v242, s[20:21]
	v_cmp_le_i32_e64 s[20:21], v74, v54
	v_perm_b32 v26, v69, v26, s62
	s_nop 0
	v_cndmask_b32_e64 v27, 0, 1, s[20:21]
	v_cmp_ge_i32_e64 s[20:21], v74, v54
	s_nop 1
	v_cndmask_b32_e64 v70, 0, 1, s[20:21]
	v_cndmask_b32_e64 v27, v70, v27, s[18:19]
	v_and_b32_e32 v27, 1, v27
	v_cmp_eq_u32_e64 s[20:21], 1, v27
	s_nop 1
	v_cndmask_b32_e64 v27, 0, v242, s[20:21]
	v_cmp_le_i32_e64 s[20:21], v75, v54
	s_nop 1
	v_cndmask_b32_e64 v70, 0, 1, s[20:21]
	v_cmp_ge_i32_e64 s[20:21], v75, v54
	s_nop 1
	v_cndmask_b32_e64 v54, 0, 1, s[20:21]
	v_cndmask_b32_e64 v54, v54, v70, s[18:19]
	v_and_b32_e32 v54, 1, v54
	v_cmp_eq_u32_e64 s[18:19], 1, v54
	s_nop 1
	v_cndmask_b32_e64 v54, 0, v242, s[18:19]
	v_perm_b32 v27, v54, v27, s62
	v_or_b32_e32 v54, v62, v43
	v_cmp_le_i32_e64 s[18:19], v61, v54
	s_waitcnt lgkmcnt(0)
	v_mfma_f32_16x16x32_bf16 v[20:23], v[24:27], v[28:31], v[20:23]
	v_lshl_add_u32 v24, v66, 6, v65
	v_or_b32_e32 v24, v24, v19
	v_lshlrev_b32_e32 v25, 6, v67
	v_mul_lo_u32 v24, v24, s69
	v_add3_u32 v24, v41, v25, v24
	v_add_u32_e32 v25, 0x3400, v24
	s_nop 1
	ds_write2_b32 v25, v20, v21 offset0:128 offset1:176
	v_add_u32_e32 v20, 0x3600, v24
	v_lshl_or_b32 v21, v72, 4, v43
	ds_write2_b32 v20, v22, v23 offset0:96 offset1:144
	v_add_u32_e32 v20, 2, v72
	v_mad_u64_u32 v[28:29], s[4:5], v21, s55, v[18:19]
	v_cndmask_b32_e64 v18, 0, 1, s[18:19]
	v_cmp_ge_i32_e64 s[18:19], v61, v54
	s_nop 1
	v_cndmask_b32_e64 v21, 0, 1, s[18:19]
	v_cmp_gt_u32_e64 s[18:19], 5, v20
	s_nop 1
	v_cndmask_b32_e64 v18, v21, v18, s[18:19]
	v_and_b32_e32 v18, 1, v18
	v_cmp_eq_u32_e64 s[20:21], 1, v18
	s_nop 1
	v_cndmask_b32_e64 v18, 0, v242, s[20:21]
	v_cmp_ge_i32_e64 s[20:21], v32, v54
	s_nop 1
	v_cndmask_b32_e64 v20, 0, 1, s[20:21]
	v_cmp_lt_i32_e64 s[20:21], v61, v54
	s_nop 1
	v_cndmask_b32_e64 v21, 0, 1, s[20:21]
	v_cndmask_b32_e64 v20, v20, v21, s[18:19]
	v_and_b32_e32 v20, 1, v20
	v_cmp_eq_u32_e64 s[20:21], 1, v20
	s_nop 1
	v_cndmask_b32_e64 v20, 0, v242, s[20:21]
	v_cmp_le_i32_e64 s[20:21], v33, v54
	v_perm_b32 v20, v20, v18, s62
	s_nop 0
	v_cndmask_b32_e64 v21, 0, 1, s[20:21]
	v_cmp_ge_i32_e64 s[20:21], v33, v54
	s_nop 1
	v_cndmask_b32_e64 v22, 0, 1, s[20:21]
	v_cndmask_b32_e64 v21, v22, v21, s[18:19]
	v_and_b32_e32 v21, 1, v21
	v_cmp_eq_u32_e64 s[20:21], 1, v21
	s_nop 1
	v_cndmask_b32_e64 v21, 0, v242, s[20:21]
	v_cmp_le_i32_e64 s[20:21], v34, v54
	s_nop 1
	v_cndmask_b32_e64 v22, 0, 1, s[20:21]
	v_cmp_ge_i32_e64 s[20:21], v34, v54
	s_nop 1
	v_cndmask_b32_e64 v23, 0, 1, s[20:21]
	v_cndmask_b32_e64 v22, v23, v22, s[18:19]
	v_and_b32_e32 v22, 1, v22
	v_cmp_eq_u32_e64 s[20:21], 1, v22
	s_nop 1
	v_cndmask_b32_e64 v24, 0, v242, s[20:21]
	v_cmp_le_i32_e64 s[20:21], v35, v54
	v_perm_b32 v21, v24, v21, s62
	s_nop 0
	v_cndmask_b32_e64 v22, 0, 1, s[20:21]
	v_cmp_ge_i32_e64 s[20:21], v35, v54
	s_nop 1
	v_cndmask_b32_e64 v23, 0, 1, s[20:21]
	v_cndmask_b32_e64 v22, v23, v22, s[18:19]
	v_and_b32_e32 v22, 1, v22
	v_cmp_eq_u32_e64 s[20:21], 1, v22
	s_nop 1
	v_cndmask_b32_e64 v22, 0, v242, s[20:21]
	v_cmp_le_i32_e64 s[20:21], v36, v54
	s_nop 1
	v_cndmask_b32_e64 v23, 0, 1, s[20:21]
	v_cmp_ge_i32_e64 s[20:21], v36, v54
	s_nop 1
	v_cndmask_b32_e64 v25, 0, 1, s[20:21]
	v_cndmask_b32_e64 v23, v25, v23, s[18:19]
	v_and_b32_e32 v23, 1, v23
	v_cmp_eq_u32_e64 s[20:21], 1, v23
	s_nop 1
	v_cndmask_b32_e64 v25, 0, v242, s[20:21]
	v_cmp_le_i32_e64 s[20:21], v37, v54
	v_perm_b32 v22, v25, v22, s62
	s_nop 0
	v_cndmask_b32_e64 v23, 0, 1, s[20:21]
	v_cmp_ge_i32_e64 s[20:21], v37, v54
	s_nop 1
	v_cndmask_b32_e64 v26, 0, 1, s[20:21]
	v_cndmask_b32_e64 v23, v26, v23, s[18:19]
	v_and_b32_e32 v23, 1, v23
	v_cmp_eq_u32_e64 s[20:21], 1, v23
	s_nop 1
	v_cndmask_b32_e64 v23, 0, v242, s[20:21]
	v_cmp_le_i32_e64 s[20:21], v38, v54
	s_nop 1
	v_cndmask_b32_e64 v26, 0, 1, s[20:21]
	v_cmp_ge_i32_e64 s[20:21], v38, v54
	s_nop 1
	v_cndmask_b32_e64 v27, 0, 1, s[20:21]
	v_cndmask_b32_e64 v26, v27, v26, s[18:19]
	v_and_b32_e32 v26, 1, v26
	v_cmp_eq_u32_e64 s[20:21], 1, v26
	s_nop 1
	v_cndmask_b32_e64 v26, 0, v242, s[20:21]
	v_perm_b32 v23, v26, v23, s62
	ds_read_b128 v[24:27], v28
	ds_read_b128 v[28:31], v28 offset:64
	v_cmp_le_i32_e64 s[20:21], v39, v54
	s_waitcnt lgkmcnt(1)
; #define LAS __attribute__((address_space(3)))
; __device__ __forceinline__ f32x4 mfma16(bf16x8 a, bf16x8 b, f32x4 c) { return __builtin_amdgcn_mfma_f32_16x16x32_bf16(a, b, c, 0, 0, 0); }
; __device__ __forceinline__ void gla_prep(const PrepRegs& R, LAS unsigned char* lds, int wave, int fr, int fq) {
;     ...
;     for (int q = 0; q < 3; ++q) { const int tile = wave * 3 + q, mi = tile / 6, ni = tile % 6, dir = ni / 3;
;         f32x4 acc = (f32x4){0.f, 0.f, 0.f, 0.f};
; #pragma unroll
;         for (int kk = 0; kk < 2; ++kk) { const int t = mi * 16 + fr; bf16x8 tri;
; #pragma unroll
;             for (int e = 0; e < 8; ++e) { const int sidx = kk * 32 + fq * 8 + e; tri[e] = (dir ? (sidx >= t) : (sidx <= t)) ? (short)0x3F80 : (short)0; }
;             const bf16x8 bb = *(const LAS bf16x8*)(lds + GL_GT + (ni * 16 + fr) * 144 + kk * 64 + fq * 16);
;             acc = mfma16(tri, bb, acc); }
; #pragma unroll
;         for (int i = 0; i < 4; ++i) G[(dir * 64 + mi * 16 + fq * 4 + i) * 48 + (ni % 3) * 16 + fr] = acc[i]; }
;     __syncthreads();
; }
; __device__ __forceinline__ void gla_g1_item(int wv, const Params& p, int l, int it, LAS unsigned char* lds) {
;     ...
;     if (tid < 384) { const int t = t3;
	v_mfma_f32_16x16x32_bf16 v[20:23], v[20:23], v[24:27], 0
	v_cndmask_b32_e64 v18, 0, 1, s[20:21]
	v_cmp_ge_i32_e64 s[20:21], v39, v54
	s_nop 1
	v_cndmask_b32_e64 v24, 0, 1, s[20:21]
	v_cndmask_b32_e64 v18, v24, v18, s[18:19]
	v_and_b32_e32 v18, 1, v18
	v_cmp_eq_u32_e64 s[20:21], 1, v18
	s_nop 1
	v_cndmask_b32_e64 v18, 0, v242, s[20:21]
	v_cmp_le_i32_e64 s[20:21], v40, v54
	s_nop 1
	v_cndmask_b32_e64 v24, 0, 1, s[20:21]
	v_cmp_ge_i32_e64 s[20:21], v40, v54
	s_nop 1
	v_cndmask_b32_e64 v25, 0, 1, s[20:21]
	v_cndmask_b32_e64 v24, v25, v24, s[18:19]
	v_and_b32_e32 v24, 1, v24
	v_cmp_eq_u32_e64 s[20:21], 1, v24
	s_nop 1
	v_cndmask_b32_e64 v24, 0, v242, s[20:21]
	v_cmp_le_i32_e64 s[20:21], v47, v54
	v_perm_b32 v24, v24, v18, s62
	v_lshl_add_u32 v18, v63, 6, v62
	v_cndmask_b32_e64 v25, 0, 1, s[20:21]
	v_cmp_ge_i32_e64 s[20:21], v47, v54
	v_or_b32_e32 v18, v18, v19
	v_mul_lo_u32 v18, v18, s69
	v_cndmask_b32_e64 v26, 0, 1, s[20:21]
	v_cndmask_b32_e64 v25, v26, v25, s[18:19]
	v_and_b32_e32 v25, 1, v25
	v_cmp_eq_u32_e64 s[20:21], 1, v25
	s_nop 1
	v_cndmask_b32_e64 v25, 0, v242, s[20:21]
	v_cmp_le_i32_e64 s[20:21], v52, v54
	s_nop 1
	v_cndmask_b32_e64 v26, 0, 1, s[20:21]
	v_cmp_ge_i32_e64 s[20:21], v52, v54
	s_nop 1
	v_cndmask_b32_e64 v27, 0, 1, s[20:21]
	v_cndmask_b32_e64 v26, v27, v26, s[18:19]
	v_and_b32_e32 v26, 1, v26
	v_cmp_eq_u32_e64 s[20:21], 1, v26
	s_nop 1
	v_cndmask_b32_e64 v32, 0, v242, s[20:21]
	v_cmp_le_i32_e64 s[20:21], v56, v54
	v_perm_b32 v25, v32, v25, s62
	s_nop 0
	v_cndmask_b32_e64 v26, 0, 1, s[20:21]
	v_cmp_ge_i32_e64 s[20:21], v56, v54
	s_nop 1
	v_cndmask_b32_e64 v27, 0, 1, s[20:21]
	v_cndmask_b32_e64 v26, v27, v26, s[18:19]
	v_and_b32_e32 v26, 1, v26
	v_cmp_eq_u32_e64 s[20:21], 1, v26
	s_nop 1
	v_cndmask_b32_e64 v26, 0, v242, s[20:21]
	v_cmp_le_i32_e64 s[20:21], v58, v54
	s_nop 1
	v_cndmask_b32_e64 v27, 0, 1, s[20:21]
	v_cmp_ge_i32_e64 s[20:21], v58, v54
	s_nop 1
	v_cndmask_b32_e64 v33, 0, 1, s[20:21]
	v_cndmask_b32_e64 v27, v33, v27, s[18:19]
	v_and_b32_e32 v27, 1, v27
	v_cmp_eq_u32_e64 s[20:21], 1, v27
	s_nop 1
	v_cndmask_b32_e64 v33, 0, v242, s[20:21]
	v_cmp_le_i32_e64 s[20:21], v74, v54
	v_perm_b32 v26, v33, v26, s62
	s_nop 0
	v_cndmask_b32_e64 v27, 0, 1, s[20:21]
	v_cmp_ge_i32_e64 s[20:21], v74, v54
	s_nop 1
	v_cndmask_b32_e64 v34, 0, 1, s[20:21]
	v_cndmask_b32_e64 v27, v34, v27, s[18:19]
	v_and_b32_e32 v27, 1, v27
	v_cmp_eq_u32_e64 s[20:21], 1, v27
	s_nop 1
	v_cndmask_b32_e64 v27, 0, v242, s[20:21]
	v_cmp_le_i32_e64 s[20:21], v75, v54
	s_nop 1
	v_cndmask_b32_e64 v34, 0, 1, s[20:21]
	v_cmp_ge_i32_e64 s[20:21], v75, v54
	s_nop 1
	v_cndmask_b32_e64 v35, 0, 1, s[20:21]
	v_cndmask_b32_e64 v34, v35, v34, s[18:19]
	v_and_b32_e32 v34, 1, v34
	v_cmp_eq_u32_e64 s[18:19], 1, v34
	s_nop 1
	v_cndmask_b32_e64 v34, 0, v242, s[18:19]
	v_perm_b32 v27, v34, v27, s62
	s_waitcnt lgkmcnt(0)
	s_nop 0
	v_mfma_f32_16x16x32_bf16 v[20:23], v[24:27], v[28:31], v[20:23]
	v_lshlrev_b32_e32 v24, 6, v64
	v_add3_u32 v18, v41, v24, v18
	v_add_u32_e32 v24, 0x3400, v18
	v_add_u32_e32 v18, 0x3600, v18
	s_nop 3
	ds_write2_b32 v24, v20, v21 offset0:128 offset1:176
	ds_write2_b32 v18, v22, v23 offset0:96 offset1:144
	s_waitcnt lgkmcnt(0)
	s_barrier
	s_and_saveexec_b64 s[18:19], s[16:17]
	s_cbranch_execz .LBB0_828
; #define LAS __attribute__((address_space(3)))
; __device__ __forceinline__ bf16_t f2bf(float f) { unsigned u = __float_as_uint(f); u += 0x7FFFu + ((u >> 16) & 1u); return (bf16_t)(u >> 16); }
; __device__ __forceinline__ float bflo(unsigned w) { return __uint_as_float(w << 16); }
; __device__ __forceinline__ float bfhi(unsigned w) { return __uint_as_float(w & 0xffff0000u); }
; __device__ __forceinline__ void gla_g1_item(int wv, const Params& p, int l, int it, LAS unsigned char* lds) {
;     ...
;     if (tid < 384) { const int t = t3;
;         float x1[4] = {bflo(w1.x), bfhi(w1.x), bflo(w1.y), bfhi(w1.y)}, x2[4] = {bflo(w2.x), bfhi(w2.x), bflo(w2.y), bfhi(w2.y)};
;         { const float cn[4] = {ra[0], ra[2], rb[0], rb[2]}, sn[4] = {ra[1], ra[3], rb[1], rb[3]};
; #pragma unroll
;             for (int e = 0; e < 4; ++e) { const float a1 = x1[e], a2 = x2[e]; x1[e] = a1 * cn[e] - a2 * sn[e]; x2[e] = a2 * cn[e] + a1 * sn[e]; } }
; #pragma unroll
;         for (int dir = 0; dir < 2; ++dir) { const int tl = dir ? 0 : 63;
;             const f32x4 b1 = *(const LAS f32x4*)(G + (dir * 64 + t) * 48 + c1), b2 = *(const LAS f32x4*)(G + (dir * 64 + t) * 48 + c1 + 12);
;             const f32x4 l1 = *(const LAS f32x4*)(G + (dir * 64 + tl) * 48 + c1), l2 = *(const LAS f32x4*)(G + (dir * 64 + tl) * 48 + c1 + 12);
; #pragma unroll
;             for (int e = 0; e < 4; ++e) {
;                 *(LAS bf16_t*)(lds + GL_X + (dir * 48 + c1 + e) * 144 + t * 2) = f2bf(x1[e] * __expf(l1[e] - b1[e]));
;                 *(LAS bf16_t*)(lds + GL_X + (dir * 48 + c1 + 12 + e) * 144 + t * 2) = f2bf(x2[e] * __expf(l2[e] - b2[e])); } } }
; #pragma unroll
;     for (int i = 0; i < 2; ++i) { const int e = tid + i * 512; if (e < 768) *(LAS u32x4*)(lds + GL_VT + (e >> 3) * 144 + (e & 7) * 16) = vw[i]; }
;     bf16_t* Sb = (bf16_t*)(p.ws + OFF_S); float* DEC = (float*)(p.ws + OFF_DEC);
;     if (tid < 96) { const int dir = tid / 48, c = tid % 48; const size_t slot = (size_t)((b * 4 + h) * 2 + dir) * 36 + n;
;         DEC[slot * 48 + c] = __expf(dir ? G[64 * 48 + c] : G[63 * 48 + c]); }
	v_lshlrev_b32_e32 v18, 16, v50
	v_lshlrev_b32_e32 v22, 16, v48
	v_and_b32_e32 v23, 0xffff0000, v48
	v_mul_f32_e32 v27, v15, v22
	v_mul_f32_e32 v31, v15, v18
	v_and_b32_e32 v20, 0xffff0000, v50
	v_lshlrev_b32_e32 v25, 16, v49
	v_fma_f32 v30, v14, v18, -v27
	v_fmac_f32_e32 v31, v14, v22
	v_mul_f32_e32 v14, v17, v23
	v_lshl_add_u32 v18, v46, 2, 0
	v_lshlrev_b32_e32 v21, 16, v51
	v_fma_f32 v32, v16, v20, -v14
	v_mul_f32_e32 v33, v17, v20
	v_mul_f32_e32 v14, v11, v25
	v_mad_u64_u32 v[28:29], s[4:5], v57, s69, v[18:19]
	v_fmac_f32_e32 v33, v16, v23
	v_fma_f32 v34, v10, v21, -v14
	v_mul_f32_e32 v35, v11, v21
	ds_read_b128 v[14:17], v28 offset:13824
	ds_read_b128 v[20:23], v18 offset:25920
	v_and_b32_e32 v26, 0xffff0000, v49
	v_and_b32_e32 v24, 0xffff0000, v51
	v_fmac_f32_e32 v35, v10, v25
	v_mul_f32_e32 v10, v13, v26
	v_fma_f32 v29, v12, v24, -v10
	s_waitcnt lgkmcnt(0)
	v_sub_f32_e32 v10, v20, v14
	v_mul_f32_e32 v36, v13, v24
	v_mul_f32_e32 v10, 0x3fb8aa3b, v10
	v_fmac_f32_e32 v36, v12, v26
	v_exp_f32_e32 v14, v10
	ds_read_b128 v[10:13], v28 offset:13872
	ds_read_b128 v[24:27], v18 offset:25968
	v_lshlrev_b32_e32 v37, 1, v57
	s_add_i32 s4, 0, 0x16000
	v_mul_f32_e32 v14, v30, v14
	v_bfe_u32 v20, v14, 16, 1
	s_waitcnt lgkmcnt(0)
	v_sub_f32_e32 v10, v24, v10
	v_add3_u32 v14, v14, v20, s54
	v_mul_f32_e32 v10, 0x3fb8aa3b, v10
	v_mul_i32_i24_e32 v20, 0x90, v46
	v_exp_f32_e32 v10, v10
	v_add3_u32 v37, s4, v37, v20
	ds_write_b16_d16_hi v37, v14
	v_sub_f32_e32 v14, v21, v15
	v_mul_f32_e32 v14, 0x3fb8aa3b, v14
	v_exp_f32_e32 v14, v14
	v_mul_f32_e32 v10, v31, v10
	v_sub_f32_e32 v11, v25, v11
	v_bfe_u32 v15, v10, 16, 1
	v_mul_f32_e32 v11, 0x3fb8aa3b, v11
	v_add3_u32 v10, v10, v15, s54
	v_exp_f32_e32 v11, v11
	ds_write_b16_d16_hi v37, v10 offset:1728
	v_mul_f32_e32 v10, v32, v14
	v_bfe_u32 v14, v10, 16, 1
	v_add3_u32 v10, v10, v14, s54
	ds_write_b16_d16_hi v37, v10 offset:144
	v_mul_f32_e32 v10, v33, v11
	v_sub_f32_e32 v11, v22, v16
	v_mul_f32_e32 v11, 0x3fb8aa3b, v11
	v_exp_f32_e32 v11, v11
	v_bfe_u32 v14, v10, 16, 1
	v_add3_u32 v10, v10, v14, s54
	ds_write_b16_d16_hi v37, v10 offset:1872
	v_mul_f32_e32 v10, v34, v11
	v_sub_f32_e32 v11, v26, v12
	v_mul_f32_e32 v11, 0x3fb8aa3b, v11
	v_exp_f32_e32 v11, v11
	v_bfe_u32 v12, v10, 16, 1
	v_add3_u32 v10, v10, v12, s54
	ds_write_b16_d16_hi v37, v10 offset:288
	v_mul_f32_e32 v10, v35, v11
	v_sub_f32_e32 v11, v23, v17
	v_mul_f32_e32 v11, 0x3fb8aa3b, v11
	v_exp_f32_e32 v11, v11
	v_bfe_u32 v12, v10, 16, 1
	v_add3_u32 v10, v10, v12, s54
	ds_write_b16_d16_hi v37, v10 offset:2016
	v_mul_f32_e32 v10, v29, v11
	v_sub_f32_e32 v11, v27, v13
	v_mul_f32_e32 v11, 0x3fb8aa3b, v11
	v_exp_f32_e32 v11, v11
	v_bfe_u32 v12, v10, 16, 1
	v_add3_u32 v10, v10, v12, s54
	ds_write_b16_d16_hi v37, v10 offset:432
	v_mul_f32_e32 v10, v36, v11
	v_bfe_u32 v11, v10, 16, 1
	v_add3_u32 v10, v10, v11, s54
	ds_write_b16_d16_hi v37, v10 offset:2160
	ds_read_b128 v[10:13], v28 offset:26112
	ds_read_b128 v[14:17], v18 offset:26112
	ds_read_b128 v[20:23], v28 offset:26160
	ds_read_b128 v[24:27], v18 offset:26160
	s_waitcnt lgkmcnt(2)
	v_sub_f32_e32 v10, v14, v10
	v_mul_f32_e32 v10, 0x3fb8aa3b, v10
	v_exp_f32_e32 v10, v10
	s_waitcnt lgkmcnt(0)
	v_sub_f32_e32 v14, v24, v20
	v_mul_f32_e32 v14, 0x3fb8aa3b, v14
	v_exp_f32_e32 v14, v14
	v_mul_f32_e32 v10, v30, v10
	v_sub_f32_e32 v11, v15, v11
	v_bfe_u32 v18, v10, 16, 1
	v_mul_f32_e32 v11, 0x3fb8aa3b, v11
	v_add3_u32 v10, v10, v18, s54
	v_exp_f32_e32 v11, v11
	ds_write_b16_d16_hi v37, v10 offset:6912
	v_mul_f32_e32 v10, v31, v14
	v_bfe_u32 v14, v10, 16, 1
	v_add3_u32 v10, v10, v14, s54
	ds_write_b16_d16_hi v37, v10 offset:8640
	v_mul_f32_e32 v10, v32, v11
	v_sub_f32_e32 v11, v25, v21
	v_mul_f32_e32 v11, 0x3fb8aa3b, v11
	v_exp_f32_e32 v11, v11
	v_bfe_u32 v14, v10, 16, 1
	v_add3_u32 v10, v10, v14, s54
	ds_write_b16_d16_hi v37, v10 offset:7056
	v_mul_f32_e32 v10, v33, v11
	v_sub_f32_e32 v11, v16, v12
	v_mul_f32_e32 v11, 0x3fb8aa3b, v11
	v_exp_f32_e32 v11, v11
	v_bfe_u32 v12, v10, 16, 1
	v_add3_u32 v10, v10, v12, s54
	ds_write_b16_d16_hi v37, v10 offset:8784
	v_mul_f32_e32 v10, v34, v11
	v_sub_f32_e32 v11, v26, v22
	v_mul_f32_e32 v11, 0x3fb8aa3b, v11
	v_exp_f32_e32 v11, v11
	v_bfe_u32 v12, v10, 16, 1
	v_add3_u32 v10, v10, v12, s54
	ds_write_b16_d16_hi v37, v10 offset:7200
	v_mul_f32_e32 v10, v35, v11
	v_sub_f32_e32 v11, v17, v13
	v_mul_f32_e32 v11, 0x3fb8aa3b, v11
	v_exp_f32_e32 v11, v11
	v_bfe_u32 v12, v10, 16, 1
	v_add3_u32 v10, v10, v12, s54
	ds_write_b16_d16_hi v37, v10 offset:8928
	v_mul_f32_e32 v10, v29, v11
	v_sub_f32_e32 v11, v27, v23
	v_mul_f32_e32 v11, 0x3fb8aa3b, v11
	v_exp_f32_e32 v11, v11
	v_bfe_u32 v12, v10, 16, 1
	v_add3_u32 v10, v10, v12, s54
	ds_write_b16_d16_hi v37, v10 offset:7344
	v_mul_f32_e32 v10, v36, v11
	v_bfe_u32 v11, v10, 16, 1
	v_add3_u32 v10, v10, v11, s54
	ds_write_b16_d16_hi v37, v10 offset:9072
	s_or_b64 exec, exec, s[18:19]
	v_add_u32_e32 v10, s87, v44
	s_and_saveexec_b64 s[4:5], vcc
	s_cbranch_execnz .LBB0_829

; #define LAS __attribute__((address_space(3)))
; __device__ __forceinline__ unsigned pk_bf16(float lo, float hi) { unsigned r; asm volatile("v_cvt_pk_bf16_f32 %0, %1, %2" : "=v"(r) : "v"(lo), "v"(hi)); return r; }
; __device__ __forceinline__ float bflo(unsigned w) { return __uint_as_float(w << 16); }
; __device__ __forceinline__ float bfhi(unsigned w) { return __uint_as_float(w & 0xffff0000u); }
; __device__ __forceinline__ float shx(float v, int m, int lane) { return __int_as_float(__builtin_amdgcn_ds_bpermute((lane ^ m) << 2, __float_as_int(v))); }
; __device__ __forceinline__ u32x4 norm_krow(u32x4 w, int lane) {
;     float v[8]; v[0] = bflo(w.x); v[1] = bfhi(w.x); v[2] = bflo(w.y); v[3] = bfhi(w.y); v[4] = bflo(w.z); v[5] = bfhi(w.z); v[6] = bflo(w.w); v[7] = bfhi(w.w);
;     float ss = 0.f;
; #pragma unroll
;     for (int e = 0; e < 8; ++e) ss += v[e] * v[e];
;     ss += shx(ss, 1, lane); ss += shx(ss, 2, lane); ss += shx(ss, 4, lane);
;     const float rk = rsqrtf(ss * (1.0f / 64.0f) + 1e-6f);
;     u32x4 o; o.x = pk_bf16(v[0] * rk, v[1] * rk); o.y = pk_bf16(v[2] * rk, v[3] * rk); o.z = pk_bf16(v[4] * rk, v[5] * rk); o.w = pk_bf16(v[6] * rk, v[7] * rk); return o;
; }
; __device__ __forceinline__ void na_item(int wv, const Params& p, int l, int it, LAS unsigned char* lds) {
;     ...
;         if (lat) {
; #pragma unroll
;             for (int i = 0; i < 5; ++i) { const int e = tid + i * 512, key = e >> 3, seg = e & 7; *(LAS u32x4*)(lds + NB_KLOC + key * 144 + seg * 16) = norm_krow(kl[i], lane); }
; #pragma unroll
;             for (int i = 0; i < 5; ++i) { const int e = tid + i * 512, d = e / 40, seg = e % 40; *(LAS u32x4*)(lds + NB_VLOC + d * 656 + seg * 16) = vl[i]; }
;         }
; #pragma unroll
;         for (int i = 0; i < 2; ++i) { const int e = tid + i * 512, key = e >> 3, seg = e & 7; *(LAS u32x4*)(lds + NB_KCTX + key * 144 + seg * 16) = norm_krow(kc[i], lane); }
.LBB0_746:
	s_or_b64 exec, exec, s[50:51]
	s_and_b64 vcc, exec, s[14:15]
	s_cbranch_vccnz .LBB0_748
	s_waitcnt vmcnt(4)
	v_lshlrev_b32_e32 v2, 16, v16
	v_and_b32_e32 v3, 0xffff0000, v16
	v_pk_mul_f32 v[84:85], v[2:3], v[2:3]
	v_and_b32_e32 v86, 0xffff0000, v17
	v_lshlrev_b32_e32 v87, 16, v17
	v_pk_mul_f32 v[88:89], v[86:87], v[86:87]
	v_add_f32_e32 v0, v84, v85
	v_and_b32_e32 v90, 0xffff0000, v18
	v_lshlrev_b32_e32 v91, 16, v18
	v_add_f32_e32 v0, v89, v0
	v_pk_mul_f32 v[92:93], v[90:91], v[90:91]
	v_add_f32_e32 v0, v88, v0
	v_and_b32_e32 v94, 0xffff0000, v19
	v_lshlrev_b32_e32 v95, 16, v19
	v_add_f32_e32 v0, v93, v0
	v_pk_mul_f32 v[96:97], v[94:95], v[94:95]
	v_add_f32_e32 v0, v92, v0
	v_add_f32_e32 v0, v97, v0
	v_add_f32_e32 v0, v96, v0
	s_nop 1
	v_mov_b32_dpp v84, v0 quad_perm:[1,0,3,2] row_mask:0xf bank_mask:0xf
	v_add_f32_e32 v0, v0, v84
	s_nop 1
	v_mov_b32_dpp v84, v0 quad_perm:[2,3,0,1] row_mask:0xf bank_mask:0xf
	v_add_f32_e32 v0, v0, v84
	s_nop 1
	v_mov_b32_dpp v84, v0 row_half_mirror row_mask:0xf bank_mask:0xf
	v_add_f32_e32 v0, v0, v84
	v_fmamk_f32 v0, v0, 0x3c800000, v197
	v_cmp_gt_f32_e32 vcc, s68, v0
	v_mul_f32_e32 v84, 0x4b800000, v0
	s_nop 0
	v_cndmask_b32_e32 v0, v0, v84, vcc
	v_rsq_f32_e32 v0, v0
	s_nop 0
	v_mul_f32_e32 v84, 0x45800000, v0
	v_cndmask_b32_e32 v0, v0, v84, vcc
	v_mul_f32_e32 v2, v0, v2
	v_mul_f32_e32 v3, v0, v3
	v_cvt_pk_bf16_f32 v84, v2, v3
	v_mul_f32_e32 v2, v0, v87
	v_mul_f32_e32 v3, v0, v86
	v_cvt_pk_bf16_f32 v85, v2, v3
	v_mul_f32_e32 v2, v0, v91
	v_mul_f32_e32 v3, v0, v90
	v_cvt_pk_bf16_f32 v86, v2, v3
	v_mul_f32_e32 v2, v0, v95
	v_mul_f32_e32 v0, v0, v94
	v_cvt_pk_bf16_f32 v87, v2, v0
	v_add_u32_e32 v0, v143, v160
	v_lshlrev_b32_e32 v2, 16, v12
	v_and_b32_e32 v3, 0xffff0000, v12
	ds_write_b128 v0, v[84:87]
	v_pk_mul_f32 v[84:85], v[2:3], v[2:3]
	v_and_b32_e32 v86, 0xffff0000, v13
	v_lshlrev_b32_e32 v87, 16, v13
	v_pk_mul_f32 v[88:89], v[86:87], v[86:87]
	v_add_f32_e32 v0, v84, v85
	v_and_b32_e32 v90, 0xffff0000, v14
	v_lshlrev_b32_e32 v91, 16, v14
	v_add_f32_e32 v0, v89, v0
	v_pk_mul_f32 v[92:93], v[90:91], v[90:91]
	v_add_f32_e32 v0, v88, v0
	v_and_b32_e32 v94, 0xffff0000, v15
	v_lshlrev_b32_e32 v95, 16, v15
	v_add_f32_e32 v0, v93, v0
	v_pk_mul_f32 v[96:97], v[94:95], v[94:95]
	v_add_f32_e32 v0, v92, v0
	v_add_f32_e32 v0, v97, v0
	v_add_f32_e32 v0, v96, v0
	s_nop 1
	v_mov_b32_dpp v84, v0 quad_perm:[1,0,3,2] row_mask:0xf bank_mask:0xf
	v_add_f32_e32 v0, v0, v84
	s_nop 1
	v_mov_b32_dpp v84, v0 quad_perm:[2,3,0,1] row_mask:0xf bank_mask:0xf
	v_add_f32_e32 v0, v0, v84
	s_nop 1
	v_mov_b32_dpp v84, v0 row_half_mirror row_mask:0xf bank_mask:0xf
	v_add_f32_e32 v0, v0, v84
	v_fmamk_f32 v0, v0, 0x3c800000, v197
	v_cmp_gt_f32_e32 vcc, s68, v0
	v_mul_f32_e32 v84, 0x4b800000, v0
	s_nop 0
	v_cndmask_b32_e32 v0, v0, v84, vcc
	v_rsq_f32_e32 v0, v0
	s_nop 0
	v_mul_f32_e32 v84, 0x45800000, v0
	v_cndmask_b32_e32 v0, v0, v84, vcc
	v_mul_f32_e32 v2, v0, v2
	v_mul_f32_e32 v3, v0, v3
	v_cvt_pk_bf16_f32 v84, v2, v3
	v_mul_f32_e32 v2, v0, v87
	v_mul_f32_e32 v3, v0, v86
	v_cvt_pk_bf16_f32 v85, v2, v3
	v_mul_f32_e32 v2, v0, v91
	v_mul_f32_e32 v3, v0, v90
	v_cvt_pk_bf16_f32 v86, v2, v3
	v_mul_f32_e32 v2, v0, v95
	v_mul_f32_e32 v0, v0, v94
	v_cvt_pk_bf16_f32 v87, v2, v0
	v_add_u32_e32 v0, v143, v161
	v_lshlrev_b32_e32 v2, 16, v20
	v_and_b32_e32 v3, 0xffff0000, v20
	ds_write_b128 v0, v[84:87]
	v_pk_mul_f32 v[84:85], v[2:3], v[2:3]
	v_and_b32_e32 v86, 0xffff0000, v21
	v_lshlrev_b32_e32 v87, 16, v21
	v_pk_mul_f32 v[88:89], v[86:87], v[86:87]
	v_add_f32_e32 v0, v84, v85
	v_and_b32_e32 v90, 0xffff0000, v22
	v_lshlrev_b32_e32 v91, 16, v22
	v_add_f32_e32 v0, v89, v0
	v_pk_mul_f32 v[92:93], v[90:91], v[90:91]
	v_add_f32_e32 v0, v88, v0
	v_and_b32_e32 v94, 0xffff0000, v23
	v_lshlrev_b32_e32 v95, 16, v23
	v_add_f32_e32 v0, v93, v0
	v_pk_mul_f32 v[96:97], v[94:95], v[94:95]
	v_add_f32_e32 v0, v92, v0
	v_add_f32_e32 v0, v97, v0
	v_add_f32_e32 v0, v96, v0
	s_nop 1
	v_mov_b32_dpp v84, v0 quad_perm:[1,0,3,2] row_mask:0xf bank_mask:0xf
	v_add_f32_e32 v0, v0, v84
	s_nop 1
	v_mov_b32_dpp v84, v0 quad_perm:[2,3,0,1] row_mask:0xf bank_mask:0xf
	v_add_f32_e32 v0, v0, v84
	s_nop 1
	v_mov_b32_dpp v84, v0 row_half_mirror row_mask:0xf bank_mask:0xf
	v_add_f32_e32 v0, v0, v84
	v_fmamk_f32 v0, v0, 0x3c800000, v197
	v_cmp_gt_f32_e32 vcc, s68, v0
	v_mul_f32_e32 v84, 0x4b800000, v0
	s_nop 0
	v_cndmask_b32_e32 v0, v0, v84, vcc
	v_rsq_f32_e32 v0, v0
	s_nop 0
	v_mul_f32_e32 v84, 0x45800000, v0
	v_cndmask_b32_e32 v0, v0, v84, vcc
	v_mul_f32_e32 v2, v0, v2
	v_mul_f32_e32 v3, v0, v3
	v_cvt_pk_bf16_f32 v84, v2, v3
	v_mul_f32_e32 v2, v0, v87
	v_mul_f32_e32 v3, v0, v86
	v_cvt_pk_bf16_f32 v85, v2, v3
	v_mul_f32_e32 v2, v0, v91
	v_mul_f32_e32 v3, v0, v90
	v_cvt_pk_bf16_f32 v86, v2, v3
	v_mul_f32_e32 v2, v0, v95
	v_mul_f32_e32 v0, v0, v94
	v_cvt_pk_bf16_f32 v87, v2, v0
	v_lshlrev_b32_e32 v2, 16, v24
	v_and_b32_e32 v3, 0xffff0000, v24
	ds_write_b128 v176, v[84:87]
	v_pk_mul_f32 v[84:85], v[2:3], v[2:3]
	v_and_b32_e32 v86, 0xffff0000, v25
	v_lshlrev_b32_e32 v87, 16, v25
	v_pk_mul_f32 v[88:89], v[86:87], v[86:87]
	v_add_f32_e32 v0, v84, v85
	v_and_b32_e32 v90, 0xffff0000, v26
	v_lshlrev_b32_e32 v91, 16, v26
	v_add_f32_e32 v0, v89, v0
	v_pk_mul_f32 v[92:93], v[90:91], v[90:91]
	v_add_f32_e32 v0, v88, v0
	v_and_b32_e32 v94, 0xffff0000, v27
	v_lshlrev_b32_e32 v95, 16, v27
	v_add_f32_e32 v0, v93, v0
	v_pk_mul_f32 v[96:97], v[94:95], v[94:95]
	v_add_f32_e32 v0, v92, v0
	v_add_f32_e32 v0, v97, v0
	v_add_f32_e32 v0, v96, v0
	s_nop 1
	v_mov_b32_dpp v84, v0 quad_perm:[1,0,3,2] row_mask:0xf bank_mask:0xf
	v_add_f32_e32 v0, v0, v84
	s_nop 1
	v_mov_b32_dpp v84, v0 quad_perm:[2,3,0,1] row_mask:0xf bank_mask:0xf
; #define LAS __attribute__((address_space(3)))
; __device__ __forceinline__ unsigned pk_bf16(float lo, float hi) { unsigned r; asm volatile("v_cvt_pk_bf16_f32 %0, %1, %2" : "=v"(r) : "v"(lo), "v"(hi)); return r; }
; __device__ __forceinline__ float bflo(unsigned w) { return __uint_as_float(w << 16); }
; __device__ __forceinline__ float bfhi(unsigned w) { return __uint_as_float(w & 0xffff0000u); }
; __device__ __forceinline__ float shx(float v, int m, int lane) { return __int_as_float(__builtin_amdgcn_ds_bpermute((lane ^ m) << 2, __float_as_int(v))); }
; __device__ __forceinline__ u32x4 norm_krow(u32x4 w, int lane) {
;     float v[8]; v[0] = bflo(w.x); v[1] = bfhi(w.x); v[2] = bflo(w.y); v[3] = bfhi(w.y); v[4] = bflo(w.z); v[5] = bfhi(w.z); v[6] = bflo(w.w); v[7] = bfhi(w.w);
;     float ss = 0.f;
; #pragma unroll
;     for (int e = 0; e < 8; ++e) ss += v[e] * v[e];
;     ss += shx(ss, 1, lane); ss += shx(ss, 2, lane); ss += shx(ss, 4, lane);
;     const float rk = rsqrtf(ss * (1.0f / 64.0f) + 1e-6f);
;     u32x4 o; o.x = pk_bf16(v[0] * rk, v[1] * rk); o.y = pk_bf16(v[2] * rk, v[3] * rk); o.z = pk_bf16(v[4] * rk, v[5] * rk); o.w = pk_bf16(v[6] * rk, v[7] * rk); return o;
; }
; __device__ __forceinline__ void na_item(int wv, const Params& p, int l, int it, LAS unsigned char* lds) {
;     ...
;         if (lat) {
; #pragma unroll
;             for (int i = 0; i < 5; ++i) { const int e = tid + i * 512, key = e >> 3, seg = e & 7; *(LAS u32x4*)(lds + NB_KLOC + key * 144 + seg * 16) = norm_krow(kl[i], lane); }
; #pragma unroll
;             for (int i = 0; i < 5; ++i) { const int e = tid + i * 512, d = e / 40, seg = e % 40; *(LAS u32x4*)(lds + NB_VLOC + d * 656 + seg * 16) = vl[i]; }
;         }
; #pragma unroll
;         for (int i = 0; i < 2; ++i) { const int e = tid + i * 512, key = e >> 3, seg = e & 7; *(LAS u32x4*)(lds + NB_KCTX + key * 144 + seg * 16) = norm_krow(kc[i], lane); }
; #pragma unroll
;         for (int i = 0; i < 2; ++i) { const int e = tid + i * 512, d = e >> 4, seg = e & 15; *(LAS u32x4*)(lds + NB_VCTX + d * 272 + seg * 16) = vc[i]; }
;         __syncthreads();
;         if (ps == 0) NA_LOAD(1);
	v_add_f32_e32 v0, v0, v84
	s_nop 1
	v_mov_b32_dpp v84, v0 row_half_mirror row_mask:0xf bank_mask:0xf
	v_add_f32_e32 v0, v0, v84
	v_fmamk_f32 v0, v0, 0x3c800000, v197
	v_cmp_gt_f32_e32 vcc, s68, v0
	v_mul_f32_e32 v84, 0x4b800000, v0
	s_nop 0
	v_cndmask_b32_e32 v0, v0, v84, vcc
	v_rsq_f32_e32 v0, v0
	s_nop 0
	v_mul_f32_e32 v84, 0x45800000, v0
	v_cndmask_b32_e32 v0, v0, v84, vcc
	v_mul_f32_e32 v2, v0, v2
	v_mul_f32_e32 v3, v0, v3
	v_cvt_pk_bf16_f32 v84, v2, v3
	v_mul_f32_e32 v2, v0, v87
	v_mul_f32_e32 v3, v0, v86
	v_cvt_pk_bf16_f32 v85, v2, v3
	v_mul_f32_e32 v2, v0, v91
	v_mul_f32_e32 v3, v0, v90
	v_cvt_pk_bf16_f32 v86, v2, v3
	v_mul_f32_e32 v2, v0, v95
	v_mul_f32_e32 v0, v0, v94
	v_cvt_pk_bf16_f32 v87, v2, v0
	v_lshlrev_b32_e32 v2, 16, v28
	v_and_b32_e32 v3, 0xffff0000, v28
	ds_write_b128 v177, v[84:87]
	v_pk_mul_f32 v[84:85], v[2:3], v[2:3]
	v_and_b32_e32 v86, 0xffff0000, v29
	v_lshlrev_b32_e32 v87, 16, v29
	v_pk_mul_f32 v[88:89], v[86:87], v[86:87]
	v_add_f32_e32 v0, v84, v85
	v_and_b32_e32 v90, 0xffff0000, v30
	v_lshlrev_b32_e32 v91, 16, v30
	v_add_f32_e32 v0, v89, v0
	v_pk_mul_f32 v[92:93], v[90:91], v[90:91]
	v_add_f32_e32 v0, v88, v0
	v_and_b32_e32 v94, 0xffff0000, v31
	v_lshlrev_b32_e32 v95, 16, v31
	v_add_f32_e32 v0, v93, v0
	v_pk_mul_f32 v[96:97], v[94:95], v[94:95]
	v_add_f32_e32 v0, v92, v0
	v_add_f32_e32 v0, v97, v0
	v_add_f32_e32 v0, v96, v0
	s_nop 1
	v_mov_b32_dpp v84, v0 quad_perm:[1,0,3,2] row_mask:0xf bank_mask:0xf
	v_add_f32_e32 v0, v0, v84
	s_nop 1
	v_mov_b32_dpp v84, v0 quad_perm:[2,3,0,1] row_mask:0xf bank_mask:0xf
	v_add_f32_e32 v0, v0, v84
	s_nop 1
	v_mov_b32_dpp v84, v0 row_half_mirror row_mask:0xf bank_mask:0xf
	v_add_f32_e32 v0, v0, v84
	v_fmamk_f32 v0, v0, 0x3c800000, v197
	v_cmp_gt_f32_e32 vcc, s68, v0
	v_mul_f32_e32 v84, 0x4b800000, v0
	s_nop 0
	v_cndmask_b32_e32 v0, v0, v84, vcc
	v_rsq_f32_e32 v0, v0
	s_nop 0
	v_mul_f32_e32 v84, 0x45800000, v0
	v_cndmask_b32_e32 v0, v0, v84, vcc
	v_mul_f32_e32 v2, v0, v2
	v_mul_f32_e32 v3, v0, v3
	v_cvt_pk_bf16_f32 v84, v2, v3
	v_mul_f32_e32 v2, v0, v87
	v_mul_f32_e32 v3, v0, v86
	v_cvt_pk_bf16_f32 v85, v2, v3
	v_mul_f32_e32 v2, v0, v91
	v_mul_f32_e32 v3, v0, v90
	v_cvt_pk_bf16_f32 v86, v2, v3
	v_mul_f32_e32 v2, v0, v95
	v_mul_f32_e32 v0, v0, v94
	v_cvt_pk_bf16_f32 v87, v2, v0
	ds_write_b128 v178, v[84:87]
	s_waitcnt vmcnt(8)
	ds_write_b128 v179, v[32:35] offset:46080
	s_waitcnt vmcnt(7)
	ds_write_b128 v180, v[36:39] offset:46080
	s_waitcnt vmcnt(6)
	ds_write_b128 v181, v[40:43] offset:46080
	s_waitcnt vmcnt(5)
	ds_write_b128 v182, v[44:47] offset:46080
	s_waitcnt vmcnt(4)
	ds_write_b128 v183, v[48:51] offset:46080
.LBB0_748:
	s_waitcnt vmcnt(3)
	v_lshlrev_b32_e32 v2, 16, v52
	v_and_b32_e32 v3, 0xffff0000, v52
	v_pk_mul_f32 v[84:85], v[2:3], v[2:3]
	v_and_b32_e32 v86, 0xffff0000, v53
	v_lshlrev_b32_e32 v87, 16, v53
	v_pk_mul_f32 v[88:89], v[86:87], v[86:87]
	v_add_f32_e32 v0, v84, v85
	v_and_b32_e32 v90, 0xffff0000, v54
	v_lshlrev_b32_e32 v91, 16, v54
	v_add_f32_e32 v0, v89, v0
	v_pk_mul_f32 v[92:93], v[90:91], v[90:91]
	v_add_f32_e32 v0, v88, v0
	v_and_b32_e32 v94, 0xffff0000, v55
	v_lshlrev_b32_e32 v95, 16, v55
	v_add_f32_e32 v0, v93, v0
	v_pk_mul_f32 v[96:97], v[94:95], v[94:95]
	v_add_f32_e32 v0, v92, v0
	v_add_f32_e32 v0, v97, v0
	v_add_f32_e32 v0, v96, v0
	s_nop 1
	v_mov_b32_dpp v84, v0 quad_perm:[1,0,3,2] row_mask:0xf bank_mask:0xf
	s_waitcnt vmcnt(2)
	v_lshlrev_b32_e32 v88, 16, v56
	v_and_b32_e32 v89, 0xffff0000, v56
	v_and_b32_e32 v92, 0xffff0000, v57
	v_lshlrev_b32_e32 v93, 16, v57
	v_add_f32_e32 v0, v0, v84
	s_nop 1
	v_mov_b32_dpp v84, v0 quad_perm:[2,3,0,1] row_mask:0xf bank_mask:0xf
	v_pk_mul_f32 v[96:97], v[92:93], v[92:93]
	v_and_b32_e32 v98, 0xffff0000, v58
	v_lshlrev_b32_e32 v99, 16, v58
	v_pk_mul_f32 v[190:191], v[98:99], v[98:99]
	v_add_f32_e32 v0, v0, v84
	s_nop 1
	v_mov_b32_dpp v84, v0 row_half_mirror row_mask:0xf bank_mask:0xf
	v_and_b32_e32 v192, 0xffff0000, v59
	v_lshlrev_b32_e32 v193, 16, v59
	v_pk_mul_f32 v[194:195], v[192:193], v[192:193]
	s_xor_b64 s[4:5], s[72:73], -1
	v_add_f32_e32 v0, v0, v84
	v_fmamk_f32 v0, v0, 0x3c800000, v197
	v_mul_f32_e32 v84, 0x4b800000, v0
	v_cmp_gt_f32_e32 vcc, s68, v0
	s_nop 1
	v_cndmask_b32_e32 v0, v0, v84, vcc
	v_pk_mul_f32 v[84:85], v[88:89], v[88:89]
	v_rsq_f32_e32 v0, v0
	v_add_f32_e32 v84, v84, v85
	v_add_f32_e32 v84, v97, v84
	v_add_f32_e32 v84, v96, v84
	v_add_f32_e32 v84, v191, v84
	v_add_f32_e32 v84, v190, v84
	v_add_f32_e32 v84, v195, v84
	v_add_f32_e32 v85, v194, v84
	s_nop 1
	v_mov_b32_dpp v96, v85 quad_perm:[1,0,3,2] row_mask:0xf bank_mask:0xf
	v_mul_f32_e32 v198, 0x45800000, v0
	v_cndmask_b32_e32 v0, v0, v198, vcc
	v_mul_f32_e32 v2, v0, v2
	v_mul_f32_e32 v3, v0, v3
	v_cvt_pk_bf16_f32 v84, v2, v3
	v_add_f32_e32 v2, v85, v96
	s_nop 1
	v_mov_b32_dpp v3, v2 quad_perm:[2,3,0,1] row_mask:0xf bank_mask:0xf
	v_mul_f32_e32 v85, v0, v87
	v_mul_f32_e32 v86, v0, v86
	v_cvt_pk_bf16_f32 v85, v85, v86
	v_mul_f32_e32 v86, v0, v91
	v_add_f32_e32 v2, v2, v3
	s_nop 1
	v_mov_b32_dpp v3, v2 row_half_mirror row_mask:0xf bank_mask:0xf
	v_mul_f32_e32 v87, v0, v90
	v_cvt_pk_bf16_f32 v86, v86, v87
	v_mul_f32_e32 v87, v0, v95
	v_mul_f32_e32 v0, v0, v94
	v_add_f32_e32 v2, v2, v3
	v_fmamk_f32 v2, v2, 0x3c800000, v197
	v_mul_f32_e32 v3, 0x4b800000, v2
	v_cmp_gt_f32_e32 vcc, s68, v2
	v_cvt_pk_bf16_f32 v87, v87, v0
	v_add_u32_e32 v0, v144, v160
	ds_write_b128 v0, v[84:87]
	v_cndmask_b32_e32 v2, v2, v3, vcc
	v_rsq_f32_e32 v2, v2
	s_nop 0
	v_mul_f32_e32 v0, 0x45800000, v2
	v_cndmask_b32_e32 v0, v2, v0, vcc
	v_mul_f32_e32 v2, v0, v88
	v_mul_f32_e32 v3, v0, v89
	v_cvt_pk_bf16_f32 v84, v2, v3
	v_mul_f32_e32 v2, v0, v93
	v_mul_f32_e32 v3, v0, v92
	v_cvt_pk_bf16_f32 v85, v2, v3
	v_mul_f32_e32 v2, v0, v99
	v_mul_f32_e32 v3, v0, v98
	v_cvt_pk_bf16_f32 v86, v2, v3
	v_mul_f32_e32 v2, v0, v193
	v_mul_f32_e32 v0, v0, v192
	v_cvt_pk_bf16_f32 v87, v2, v0
	v_add_u32_e32 v0, v144, v161
	s_andn2_b64 vcc, exec, s[4:5]
	ds_write_b128 v0, v[84:87]
	s_waitcnt vmcnt(1)
	ds_write_b128 v184, v[60:63]
	s_waitcnt vmcnt(0)
	ds_write_b128 v185, v[64:67]
	s_waitcnt lgkmcnt(0)
	s_barrier
	s_cbranch_vccnz .LBB0_772
	s_and_b64 vcc, exec, s[14:15]
	s_cbranch_vccnz .LBB0_771
	v_mov_b32_e32 v14, v1
	v_mov_b32_e32 v15, v1
	v_mov_b32_e32 v12, v1
	v_mov_b32_e32 v13, v1
	v_mov_b64_e32 v[18:19], v[14:15]
	v_mov_b64_e32 v[16:17], v[12:13]
	s_and_saveexec_b64 s[4:5], s[18:19]
	s_cbranch_execz .LBB0_752
	global_load_dwordx4 v[16:19], v[110:111], off offset:768

; #define LAS __attribute__((address_space(3)))
; __device__ __forceinline__ bf16_t f2bf(float f) { unsigned u = __float_as_uint(f); u += 0x7FFFu + ((u >> 16) & 1u); return (bf16_t)(u >> 16); }
; __device__ __forceinline__ f32x4 mfma16(bf16x8 a, bf16x8 b, f32x4 c) { return __builtin_amdgcn_mfma_f32_16x16x32_bf16(a, b, c, 0, 0, 0); }
; __device__ __forceinline__ void gla_g3_item(int wv, const Params& p, int l, int b, int n, int h, LAS unsigned char* lds) {
;     ...
;     { const int dir = wave >> 2, mi = wave & 3;
;       bf16x8 a[2];
; #pragma unroll
;       for (int kk = 0; kk < 2; ++kk) a[kk] = *(const LAS bf16x8*)(lds + GL_Q + (dir * 64 + mi * 16 + fr) * 144 + kk * 64 + fq * 16);
; #pragma unroll
;       for (int ni = 0; ni < 4; ++ni) { f32x4 acc = (f32x4){0.f, 0.f, 0.f, 0.f};
; #pragma unroll
;           for (int kk = 0; kk < 2; ++kk) { const bf16x8 bb = *(const LAS bf16x8*)(lds + GL_K + (dir * 64 + ni * 16 + fr) * 144 + kk * 64 + fq * 16); acc = mfma16(a[kk], bb, acc); }
; #pragma unroll
;           for (int i = 0; i < 4; ++i) { const int t = mi * 16 + fq * 4 + i, sidx = ni * 16 + fr; const bool keep = dir ? (sidx >= t) : (sidx <= t);
;               *(LAS bf16_t*)(lds + GL_X + (dir * 64 + t) * 144 + sidx * 2) = f2bf(keep ? acc[i] : 0.f); } } }
.LBB0_954:
	s_or_b64 exec, exec, s[4:5]
	v_ashrrev_i32_e32 v3, 2, v2
	v_and_b32_e32 v3, 0xffffffc0, v3
	v_lshlrev_b32_e32 v4, 4, v82
	v_and_b32_e32 v26, 48, v4
	v_or_b32_e32 v4, v3, v81
	v_or_b32_e32 v5, v4, v26
	v_mul_lo_u32 v5, v5, s55
	v_add3_u32 v18, 0, v5, v0
	s_waitcnt lgkmcnt(0)
	s_barrier
	ds_read_b128 v[10:13], v18 offset:39424
	v_mad_u64_u32 v[4:5], s[4:5], v4, s55, v[38:39]
	ds_read_b128 v[14:17], v4 offset:57856
	ds_read_b128 v[18:21], v18 offset:39488
	ds_read_b128 v[22:25], v4 offset:57920
	s_waitcnt lgkmcnt(2)
	v_mfma_f32_16x16x32_bf16 v[14:17], v[10:13], v[14:17], 0
	v_or_b32_e32 v5, v26, v40
	v_cmp_le_u32_e32 vcc, v81, v5
	s_add_i32 s3, 0, 0x16000
	s_waitcnt lgkmcnt(0)
	v_mfma_f32_16x16x32_bf16 v[14:17], v[18:21], v[22:25], v[14:17]
	v_cndmask_b32_e64 v23, 0, 1, vcc
	v_cmp_ge_u32_e32 vcc, v81, v5
	v_lshl_add_u32 v22, v81, 1, s3
	v_or_b32_e32 v27, 1, v5
	v_cndmask_b32_e64 v24, 0, 1, vcc
	v_cmp_gt_u32_e32 vcc, s43, v2
	v_or_b32_e32 v29, 2, v5
	v_or_b32_e32 v32, 3, v5
	v_cndmask_b32_e32 v23, v24, v23, vcc
	v_and_b32_e32 v23, 1, v23
	v_cmp_eq_u32_e64 s[14:15], 1, v23
	v_and_b32_e32 v2, 64, v2
	v_add_u32_e32 v33, s87, v0
	v_cndmask_b32_e64 v14, 0, v14, s[14:15]
	v_bfe_u32 v23, v14, 16, 1
	v_add3_u32 v14, v14, v23, s54
	v_or_b32_e32 v23, v5, v3
	v_mul_lo_u32 v26, v23, s55
	v_add_u32_e32 v23, v22, v26
	v_cmp_gt_u32_e64 s[14:15], v81, v5
	ds_write_b16_d16_hi v23, v14
	v_mov_b32_e32 v61, v1
	v_cndmask_b32_e64 v14, 0, 1, s[14:15]
	v_cmp_le_u32_e64 s[14:15], v81, v27
	s_mov_b64 s[4:5], 0x800500
	s_nop 0
	v_cndmask_b32_e64 v23, 0, 1, s[14:15]
	v_cndmask_b32_e32 v14, v14, v23, vcc
	v_and_b32_e32 v14, 1, v14
	v_cmp_eq_u32_e64 s[14:15], 1, v14
	s_nop 1
	v_cndmask_b32_e64 v14, 0, v15, s[14:15]
	v_bfe_u32 v15, v14, 16, 1
	v_add3_u32 v14, v14, v15, s54
	v_or_b32_e32 v15, v27, v3
	v_mul_lo_u32 v28, v15, s55
	v_add_u32_e32 v15, v22, v28
	v_cmp_le_u32_e64 s[14:15], v81, v29
	ds_write_b16_d16_hi v15, v14
	s_nop 0
	v_cndmask_b32_e64 v14, 0, 1, s[14:15]
	v_cmp_ge_u32_e64 s[14:15], v81, v29
	s_nop 1
	v_cndmask_b32_e64 v15, 0, 1, s[14:15]
	v_cndmask_b32_e32 v14, v15, v14, vcc
	v_and_b32_e32 v14, 1, v14
	v_cmp_eq_u32_e64 s[14:15], 1, v14
	s_nop 1
	v_cndmask_b32_e64 v14, 0, v16, s[14:15]
	v_bfe_u32 v15, v14, 16, 1
	v_add3_u32 v14, v14, v15, s54
	v_or_b32_e32 v15, v29, v3
	v_mul_lo_u32 v31, v15, s55
	v_add_u32_e32 v15, v22, v31
	v_cmp_le_u32_e64 s[14:15], v81, v32
	ds_write_b16_d16_hi v15, v14
	v_or_b32_e32 v3, v32, v3
	v_cndmask_b32_e64 v14, 0, 1, s[14:15]
	v_cmp_ge_u32_e64 s[14:15], v81, v32
	v_mul_lo_u32 v3, v3, s55
	s_nop 0
	v_cndmask_b32_e64 v15, 0, 1, s[14:15]
	v_cndmask_b32_e32 v14, v15, v14, vcc
	v_and_b32_e32 v14, 1, v14
	v_cmp_eq_u32_e64 s[14:15], 1, v14
	s_nop 1
	v_cndmask_b32_e64 v14, 0, v17, s[14:15]
	v_bfe_u32 v15, v14, 16, 1
	v_add3_u32 v14, v14, v15, s54
	v_add_u32_e32 v15, v22, v3
	ds_write_b16_d16_hi v15, v14
	ds_read_b128 v[14:17], v4 offset:60160
	ds_read_b128 v[22:25], v4 offset:60224
	s_waitcnt lgkmcnt(1)
	v_mfma_f32_16x16x32_bf16 v[14:17], v[10:13], v[14:17], 0
	s_waitcnt lgkmcnt(0)
	v_mfma_f32_16x16x32_bf16 v[14:17], v[18:21], v[22:25], v[14:17]
	v_or_b32_e32 v22, 16, v81
	v_cmp_le_u32_e64 s[14:15], v22, v5
	v_lshl_add_u32 v23, v22, 1, s3
	s_nop 0
	v_cndmask_b32_e64 v24, 0, 1, s[14:15]
	v_cmp_ge_u32_e64 s[14:15], v22, v5
	s_nop 1
	v_cndmask_b32_e64 v25, 0, 1, s[14:15]
	v_cndmask_b32_e32 v24, v25, v24, vcc
	v_and_b32_e32 v24, 1, v24
	v_cmp_eq_u32_e64 s[14:15], 1, v24
	s_nop 1
	v_cndmask_b32_e64 v14, 0, v14, s[14:15]
	v_bfe_u32 v24, v14, 16, 1
	v_add3_u32 v14, v14, v24, s54
	v_add_u32_e32 v24, v23, v26
	v_cmp_gt_u32_e64 s[14:15], v22, v5
	ds_write_b16_d16_hi v24, v14
	s_nop 0
	v_cndmask_b32_e64 v14, 0, 1, s[14:15]
	v_cmp_le_u32_e64 s[14:15], v22, v27
	s_nop 1
	v_cndmask_b32_e64 v24, 0, 1, s[14:15]
	v_cndmask_b32_e32 v14, v14, v24, vcc
	v_and_b32_e32 v14, 1, v14
	v_cmp_eq_u32_e64 s[14:15], 1, v14
	s_nop 1
	v_cndmask_b32_e64 v14, 0, v15, s[14:15]
	v_bfe_u32 v15, v14, 16, 1
	v_add3_u32 v14, v14, v15, s54
	v_add_u32_e32 v15, v23, v28
	v_cmp_le_u32_e64 s[14:15], v22, v29
	ds_write_b16_d16_hi v15, v14
	s_nop 0
	v_cndmask_b32_e64 v14, 0, 1, s[14:15]
	v_cmp_ge_u32_e64 s[14:15], v22, v29
	s_nop 1
	v_cndmask_b32_e64 v15, 0, 1, s[14:15]
	v_cndmask_b32_e32 v14, v15, v14, vcc
	v_and_b32_e32 v14, 1, v14
	v_cmp_eq_u32_e64 s[14:15], 1, v14
	s_nop 1
	v_cndmask_b32_e64 v14, 0, v16, s[14:15]
	v_bfe_u32 v15, v14, 16, 1
	v_add3_u32 v14, v14, v15, s54
	v_add_u32_e32 v15, v23, v31
	v_cmp_le_u32_e64 s[14:15], v22, v32
	ds_write_b16_d16_hi v15, v14
	s_nop 0
	v_cndmask_b32_e64 v14, 0, 1, s[14:15]
	v_cmp_ge_u32_e64 s[14:15], v22, v32
	s_nop 1
	v_cndmask_b32_e64 v15, 0, 1, s[14:15]
	v_cndmask_b32_e32 v14, v15, v14, vcc
	v_and_b32_e32 v14, 1, v14
	v_cmp_eq_u32_e64 s[14:15], 1, v14
	s_nop 1
	v_cndmask_b32_e64 v14, 0, v17, s[14:15]
	v_bfe_u32 v15, v14, 16, 1
	v_add3_u32 v14, v14, v15, s54
	v_add_u32_e32 v15, v23, v3
	ds_write_b16_d16_hi v15, v14
	ds_read_b128 v[14:17], v4 offset:62464
	ds_read_b128 v[22:25], v4 offset:62528
	s_waitcnt lgkmcnt(1)
	v_mfma_f32_16x16x32_bf16 v[14:17], v[10:13], v[14:17], 0
	s_waitcnt lgkmcnt(0)
; #define LAS __attribute__((address_space(3)))
; __device__ __forceinline__ bf16_t f2bf(float f) { unsigned u = __float_as_uint(f); u += 0x7FFFu + ((u >> 16) & 1u); return (bf16_t)(u >> 16); }
; __device__ __forceinline__ f32x4 mfma16(bf16x8 a, bf16x8 b, f32x4 c) { return __builtin_amdgcn_mfma_f32_16x16x32_bf16(a, b, c, 0, 0, 0); }
; __device__ __forceinline__ void gla_g3_item(int wv, const Params& p, int l, int b, int n, int h, LAS unsigned char* lds) {
;     ...
;     { const int dir = wave >> 2, mi = wave & 3;
;       bf16x8 a[2];
; #pragma unroll
;       for (int kk = 0; kk < 2; ++kk) a[kk] = *(const LAS bf16x8*)(lds + GL_Q + (dir * 64 + mi * 16 + fr) * 144 + kk * 64 + fq * 16);
; #pragma unroll
;       for (int ni = 0; ni < 4; ++ni) { f32x4 acc = (f32x4){0.f, 0.f, 0.f, 0.f};
; #pragma unroll
;           for (int kk = 0; kk < 2; ++kk) { const bf16x8 bb = *(const LAS bf16x8*)(lds + GL_K + (dir * 64 + ni * 16 + fr) * 144 + kk * 64 + fq * 16); acc = mfma16(a[kk], bb, acc); }
; #pragma unroll
;           for (int i = 0; i < 4; ++i) { const int t = mi * 16 + fq * 4 + i, sidx = ni * 16 + fr; const bool keep = dir ? (sidx >= t) : (sidx <= t);
;               *(LAS bf16_t*)(lds + GL_X + (dir * 64 + t) * 144 + sidx * 2) = f2bf(keep ? acc[i] : 0.f); } } }
;     __syncthreads();
;     LAS float* Ob = (LAS float*)lds;
;     { const int mi = wave >> 1, nb = (wave & 1) * 3;
; #pragma unroll
;       for (int nn = 0; nn < 3; ++nn) { const int ni = nb + nn; f32x4 acc = (f32x4){0.f, 0.f, 0.f, 0.f};
; #pragma unroll
;           for (int dir = 0; dir < 2; ++dir)
; #pragma unroll
;               for (int kk = 0; kk < 2; ++kk) {
;                   const bf16x8 a1 = *(const LAS bf16x8*)(lds + GL_X + (dir * 64 + mi * 16 + fr) * 144 + kk * 64 + fq * 16);
;                   const bf16x8 b1 = *(const LAS bf16x8*)(lds + GL_VT + (ni * 16 + fr) * 144 + kk * 64 + fq * 16);
;                   acc = mfma16(a1, b1, acc);
;                   const bf16x8 a2 = *(const LAS bf16x8*)(lds + GL_Q + (dir * 64 + mi * 16 + fr) * 144 + kk * 64 + fq * 16);
;                   const bf16x8 b2 = *(const LAS bf16x8*)(lds + GL_ST + (dir * 96 + ni * 16 + fr) * 144 + kk * 64 + fq * 16);
;                   acc = mfma16(a2, b2, acc); }
; #pragma unroll
;           for (int i = 0; i < 4; ++i) Ob[(mi * 16 + fq * 4 + i) * 97 + ni * 16 + fr] = acc[i]; } }
	v_mfma_f32_16x16x32_bf16 v[14:17], v[18:21], v[22:25], v[14:17]
	v_or_b32_e32 v22, 32, v81
	v_cmp_le_u32_e64 s[14:15], v22, v5
	v_lshl_add_u32 v23, v22, 1, s3
	s_nop 0
	v_cndmask_b32_e64 v24, 0, 1, s[14:15]
	v_cmp_ge_u32_e64 s[14:15], v22, v5
	s_nop 1
	v_cndmask_b32_e64 v25, 0, 1, s[14:15]
	v_cndmask_b32_e32 v24, v25, v24, vcc
	v_and_b32_e32 v24, 1, v24
	v_cmp_eq_u32_e64 s[14:15], 1, v24
	s_nop 1
	v_cndmask_b32_e64 v14, 0, v14, s[14:15]
	v_bfe_u32 v24, v14, 16, 1
	v_add3_u32 v14, v14, v24, s54
	v_add_u32_e32 v24, v23, v26
	v_cmp_gt_u32_e64 s[14:15], v22, v5
	ds_write_b16_d16_hi v24, v14
	s_nop 0
	v_cndmask_b32_e64 v14, 0, 1, s[14:15]
	v_cmp_le_u32_e64 s[14:15], v22, v27
	s_nop 1
	v_cndmask_b32_e64 v24, 0, 1, s[14:15]
	v_cndmask_b32_e32 v14, v14, v24, vcc
	v_and_b32_e32 v14, 1, v14
	v_cmp_eq_u32_e64 s[14:15], 1, v14
	s_nop 1
	v_cndmask_b32_e64 v14, 0, v15, s[14:15]
	v_bfe_u32 v15, v14, 16, 1
	v_add3_u32 v14, v14, v15, s54
	v_add_u32_e32 v15, v23, v28
	v_cmp_le_u32_e64 s[14:15], v22, v29
	ds_write_b16_d16_hi v15, v14
	s_nop 0
	v_cndmask_b32_e64 v14, 0, 1, s[14:15]
	v_cmp_ge_u32_e64 s[14:15], v22, v29
	s_nop 1
	v_cndmask_b32_e64 v15, 0, 1, s[14:15]
	v_cndmask_b32_e32 v14, v15, v14, vcc
	v_and_b32_e32 v14, 1, v14
	v_cmp_eq_u32_e64 s[14:15], 1, v14
	s_nop 1
	v_cndmask_b32_e64 v14, 0, v16, s[14:15]
	v_bfe_u32 v15, v14, 16, 1
	v_add3_u32 v14, v14, v15, s54
	v_add_u32_e32 v15, v23, v31
	v_cmp_le_u32_e64 s[14:15], v22, v32
	ds_write_b16_d16_hi v15, v14
	s_nop 0
	v_cndmask_b32_e64 v14, 0, 1, s[14:15]
	v_cmp_ge_u32_e64 s[14:15], v22, v32
	s_nop 1
	v_cndmask_b32_e64 v15, 0, 1, s[14:15]
	v_cndmask_b32_e32 v14, v15, v14, vcc
	v_and_b32_e32 v14, 1, v14
	v_cmp_eq_u32_e64 s[14:15], 1, v14
	s_nop 1
	v_cndmask_b32_e64 v14, 0, v17, s[14:15]
	v_bfe_u32 v15, v14, 16, 1
	v_add3_u32 v14, v14, v15, s54
	v_add_u32_e32 v15, v23, v3
	ds_write_b16_d16_hi v15, v14
	ds_read_b128 v[14:17], v4 offset:64768
	s_waitcnt lgkmcnt(0)
	v_mfma_f32_16x16x32_bf16 v[10:13], v[10:13], v[14:17], 0
	ds_read_b128 v[14:17], v4 offset:64832
	v_or_b32_e32 v4, 48, v81
	v_cmp_le_u32_e64 s[14:15], v4, v5
	s_waitcnt lgkmcnt(0)
	v_mfma_f32_16x16x32_bf16 v[10:13], v[18:21], v[14:17], v[10:13]
	v_cndmask_b32_e64 v15, 0, 1, s[14:15]
	v_cmp_ge_u32_e64 s[14:15], v4, v5
	v_lshl_add_u32 v14, v4, 1, s3
	v_add_u32_e32 v3, v14, v3
	v_cndmask_b32_e64 v16, 0, 1, s[14:15]
	v_cndmask_b32_e32 v15, v16, v15, vcc
	v_and_b32_e32 v15, 1, v15
	v_cmp_eq_u32_e64 s[14:15], 1, v15
	s_nop 1
	v_cndmask_b32_e64 v10, 0, v10, s[14:15]
	v_bfe_u32 v15, v10, 16, 1
	v_cmp_gt_u32_e64 s[14:15], v4, v5
	v_add3_u32 v10, v10, v15, s54
	v_add_u32_e32 v15, v14, v26
	v_cndmask_b32_e64 v5, 0, 1, s[14:15]
	v_cmp_le_u32_e64 s[14:15], v4, v27
	ds_write_b16_d16_hi v15, v10
	s_nop 0
	v_cndmask_b32_e64 v10, 0, 1, s[14:15]
	v_cndmask_b32_e32 v5, v5, v10, vcc
	v_and_b32_e32 v5, 1, v5
	v_cmp_eq_u32_e64 s[14:15], 1, v5
	s_nop 1
	v_cndmask_b32_e64 v5, 0, v11, s[14:15]
	v_bfe_u32 v10, v5, 16, 1
	v_add3_u32 v5, v5, v10, s54
	v_add_u32_e32 v10, v14, v28
	v_cmp_le_u32_e64 s[14:15], v4, v29
	ds_write_b16_d16_hi v10, v5
	s_nop 0
	v_cndmask_b32_e64 v5, 0, 1, s[14:15]
	v_cmp_ge_u32_e64 s[14:15], v4, v29
	s_nop 1
	v_cndmask_b32_e64 v10, 0, 1, s[14:15]
	v_cndmask_b32_e32 v5, v10, v5, vcc
	v_and_b32_e32 v5, 1, v5
	v_cmp_eq_u32_e64 s[14:15], 1, v5
	s_nop 1
	v_cndmask_b32_e64 v5, 0, v12, s[14:15]
	v_bfe_u32 v10, v5, 16, 1
	v_add3_u32 v5, v5, v10, s54
	v_add_u32_e32 v10, v14, v31
	v_cmp_le_u32_e64 s[14:15], v4, v32
	ds_write_b16_d16_hi v10, v5
	s_nop 0
	v_cndmask_b32_e64 v5, 0, 1, s[14:15]
	v_cmp_ge_u32_e64 s[14:15], v4, v32
	v_and_b32_e32 v32, -16, v63
	s_nop 0
	v_cndmask_b32_e64 v4, 0, 1, s[14:15]
	v_cndmask_b32_e32 v4, v4, v5, vcc
	v_and_b32_e32 v4, 1, v4
	v_cmp_eq_u32_e32 vcc, 1, v4
	s_add_u32 s14, s30, s8
	s_addc_u32 s15, s31, s9
	v_cndmask_b32_e32 v4, 0, v13, vcc
	v_cmp_ne_u32_e32 vcc, 0, v2
	v_or_b32_e32 v2, v32, v81
	v_bfe_u32 v5, v4, 16, 1
	v_mul_lo_u32 v14, v2, s55
	v_add3_u32 v4, v4, v5, s54
	v_add3_u32 v34, s3, v0, v14
	ds_write_b16_d16_hi v3, v4
	s_waitcnt lgkmcnt(0)
	s_barrier
	ds_read_b128 v[2:5], v34
	v_cndmask_b32_e64 v31, 0, 3, vcc
	v_lshl_or_b32 v18, v31, 4, v81
	v_mad_u32_u24 v26, v18, s55, v33
	v_add_u32_e32 v35, v38, v14
	ds_read_b128 v[10:13], v26
	ds_read_b128 v[14:17], v35 offset:39424
	v_add_u32_e32 v0, s70, v0
	v_mad_u32_u24 v36, v18, s55, v0
	ds_read_b128 v[18:21], v34 offset:64
	s_waitcnt lgkmcnt(2)
	v_mfma_f32_16x16x32_bf16 v[2:5], v[2:5], v[10:13], 0
	ds_read_b128 v[22:25], v36
	ds_read_b128 v[26:29], v26 offset:64
	s_waitcnt lgkmcnt(1)
	v_mfma_f32_16x16x32_bf16 v[2:5], v[14:17], v[22:25], v[2:5]
	ds_read_b128 v[14:17], v35 offset:39488
	ds_read_b128 v[22:25], v36 offset:64
	s_waitcnt lgkmcnt(2)
	v_mfma_f32_16x16x32_bf16 v[2:5], v[18:21], v[26:29], v[2:5]
	ds_read_b128 v[18:21], v34 offset:9216
	s_waitcnt lgkmcnt(1)
	v_mfma_f32_16x16x32_bf16 v[2:5], v[14:17], v[22:25], v[2:5]
	ds_read_b128 v[14:17], v35 offset:48640
	ds_read_b128 v[22:25], v34 offset:9280
	s_waitcnt lgkmcnt(2)
	v_mfma_f32_16x16x32_bf16 v[2:5], v[18:21], v[10:13], v[2:5]
	ds_read_b128 v[10:13], v36 offset:13824
	v_or_b32_e32 v18, v32, v40
	v_mul_lo_u32 v32, v18, s64
	s_waitcnt lgkmcnt(0)
	v_mfma_f32_16x16x32_bf16 v[2:5], v[14:17], v[10:13], v[2:5]
	ds_read_b128 v[10:13], v35 offset:48704
	ds_read_b128 v[14:17], v36 offset:13888
	v_add_u32_e32 v36, 1, v31
	v_mfma_f32_16x16x32_bf16 v[2:5], v[22:25], v[26:29], v[2:5]
	v_lshl_or_b32 v18, v36, 4, v81
	v_mad_u32_u24 v26, v18, s55, v33
	v_mad_u32_u24 v37, v18, s55, v0
	s_waitcnt lgkmcnt(0)
; #define LAS __attribute__((address_space(3)))
; __device__ __forceinline__ f32x4 mfma16(bf16x8 a, bf16x8 b, f32x4 c) { return __builtin_amdgcn_mfma_f32_16x16x32_bf16(a, b, c, 0, 0, 0); }
; __device__ __forceinline__ void gla_g3_item(int wv, const Params& p, int l, int b, int n, int h, LAS unsigned char* lds) {
;     ...
;     LAS float* Ob = (LAS float*)lds;
;     { const int mi = wave >> 1, nb = (wave & 1) * 3;
; #pragma unroll
;       for (int nn = 0; nn < 3; ++nn) { const int ni = nb + nn; f32x4 acc = (f32x4){0.f, 0.f, 0.f, 0.f};
; #pragma unroll
;           for (int dir = 0; dir < 2; ++dir)
; #pragma unroll
;               for (int kk = 0; kk < 2; ++kk) {
;                   const bf16x8 a1 = *(const LAS bf16x8*)(lds + GL_X + (dir * 64 + mi * 16 + fr) * 144 + kk * 64 + fq * 16);
;                   const bf16x8 b1 = *(const LAS bf16x8*)(lds + GL_VT + (ni * 16 + fr) * 144 + kk * 64 + fq * 16);
;                   acc = mfma16(a1, b1, acc);
;                   const bf16x8 a2 = *(const LAS bf16x8*)(lds + GL_Q + (dir * 64 + mi * 16 + fr) * 144 + kk * 64 + fq * 16);
;                   const bf16x8 b2 = *(const LAS bf16x8*)(lds + GL_ST + (dir * 96 + ni * 16 + fr) * 144 + kk * 64 + fq * 16);
;                   acc = mfma16(a2, b2, acc); }
; #pragma unroll
;           for (int i = 0; i < 4; ++i) Ob[(mi * 16 + fq * 4 + i) * 97 + ni * 16 + fr] = acc[i]; } }
;     __syncthreads();
	v_mfma_f32_16x16x32_bf16 v[2:5], v[10:13], v[14:17], v[2:5]
	v_lshlrev_b32_e32 v10, 6, v31
	v_add3_u32 v10, v39, v10, v32
	v_add_u32_e32 v31, 2, v31
	s_nop 4
	ds_write2_b32 v10, v2, v3 offset1:97
	v_add_u32_e32 v2, 0x200, v10
	ds_write2_b32 v2, v4, v5 offset0:66 offset1:163
	ds_read_b128 v[2:5], v34
	ds_read_b128 v[10:13], v26
	ds_read_b128 v[14:17], v35 offset:39424
	ds_read_b128 v[18:21], v34 offset:64
	s_waitcnt lgkmcnt(2)
	v_mfma_f32_16x16x32_bf16 v[2:5], v[2:5], v[10:13], 0
	ds_read_b128 v[22:25], v37
	ds_read_b128 v[26:29], v26 offset:64
	s_waitcnt lgkmcnt(1)
	v_mfma_f32_16x16x32_bf16 v[2:5], v[14:17], v[22:25], v[2:5]
	ds_read_b128 v[14:17], v35 offset:39488
	ds_read_b128 v[22:25], v37 offset:64
	s_waitcnt lgkmcnt(2)
	v_mfma_f32_16x16x32_bf16 v[2:5], v[18:21], v[26:29], v[2:5]
	ds_read_b128 v[18:21], v34 offset:9216
	s_waitcnt lgkmcnt(1)
	v_mfma_f32_16x16x32_bf16 v[2:5], v[14:17], v[22:25], v[2:5]
	ds_read_b128 v[14:17], v35 offset:48640
	ds_read_b128 v[22:25], v34 offset:9280
	s_waitcnt lgkmcnt(2)
	v_mfma_f32_16x16x32_bf16 v[2:5], v[18:21], v[10:13], v[2:5]
	ds_read_b128 v[10:13], v37 offset:13824
	v_lshl_or_b32 v18, v31, 4, v81
	v_mad_u32_u24 v0, v18, s55, v0
	s_waitcnt lgkmcnt(0)
	v_mfma_f32_16x16x32_bf16 v[2:5], v[14:17], v[10:13], v[2:5]
	ds_read_b128 v[10:13], v35 offset:48704
	ds_read_b128 v[14:17], v37 offset:13888
	v_mfma_f32_16x16x32_bf16 v[2:5], v[22:25], v[26:29], v[2:5]
	v_mad_u32_u24 v26, v18, s55, v33
	s_waitcnt lgkmcnt(0)
	v_mfma_f32_16x16x32_bf16 v[2:5], v[10:13], v[14:17], v[2:5]
	v_lshlrev_b32_e32 v10, 6, v36
	v_add3_u32 v10, v39, v10, v32
	s_nop 5
	ds_write2_b32 v10, v2, v3 offset1:97
	v_add_u32_e32 v2, 0x200, v10
	ds_write2_b32 v2, v4, v5 offset0:66 offset1:163
	ds_read_b128 v[2:5], v34
	ds_read_b128 v[10:13], v26
	ds_read_b128 v[14:17], v35 offset:39424
	ds_read_b128 v[18:21], v34 offset:64
	s_waitcnt lgkmcnt(2)
	v_mfma_f32_16x16x32_bf16 v[2:5], v[2:5], v[10:13], 0
	ds_read_b128 v[22:25], v0
	ds_read_b128 v[26:29], v26 offset:64
	s_waitcnt lgkmcnt(1)
	v_mfma_f32_16x16x32_bf16 v[2:5], v[14:17], v[22:25], v[2:5]
	ds_read_b128 v[14:17], v35 offset:39488
	ds_read_b128 v[22:25], v0 offset:64
	s_waitcnt lgkmcnt(2)
	v_mfma_f32_16x16x32_bf16 v[2:5], v[18:21], v[26:29], v[2:5]
	ds_read_b128 v[18:21], v34 offset:9216
	s_waitcnt lgkmcnt(1)
	v_mfma_f32_16x16x32_bf16 v[2:5], v[14:17], v[22:25], v[2:5]
	ds_read_b128 v[14:17], v35 offset:48640
	ds_read_b128 v[22:25], v34 offset:9280
	s_waitcnt lgkmcnt(2)
	v_mfma_f32_16x16x32_bf16 v[2:5], v[18:21], v[10:13], v[2:5]
	ds_read_b128 v[10:13], v0 offset:13824
	s_waitcnt lgkmcnt(0)
	v_mfma_f32_16x16x32_bf16 v[2:5], v[14:17], v[10:13], v[2:5]
	ds_read_b128 v[10:13], v35 offset:48704
	ds_read_b128 v[14:17], v0 offset:13888
	v_lshlrev_b32_e32 v0, 6, v31
	v_mfma_f32_16x16x32_bf16 v[2:5], v[22:25], v[26:29], v[2:5]
	v_add3_u32 v0, v39, v0, v32
	s_waitcnt vmcnt(0)
	v_lshlrev_b32_e32 v26, 16, v7
	v_and_b32_e32 v28, 0xffff0000, v7
	s_waitcnt lgkmcnt(0)
	v_mfma_f32_16x16x32_bf16 v[2:5], v[10:13], v[14:17], v[2:5]
	v_mul_lo_u32 v10, v63, s64
	s_nop 6
	ds_write2_b32 v0, v2, v3 offset1:97
	v_add_u32_e32 v0, 0x200, v0
	ds_write2_b32 v0, v4, v5 offset0:66 offset1:163
	v_lshlrev_b32_e32 v0, 2, v65
	s_waitcnt lgkmcnt(0)
	s_barrier
; __device__ __forceinline__ unsigned pk_bf16(float lo, float hi) { unsigned r; asm volatile("v_cvt_pk_bf16_f32 %0, %1, %2" : "=v"(r) : "v"(lo), "v"(hi)); return r; }
; __device__ __forceinline__ float bflo(unsigned w) { return __uint_as_float(w << 16); }
; __device__ __forceinline__ float bfhi(unsigned w) { return __uint_as_float(w & 0xffff0000u); }
; __device__ __forceinline__ float shx(float v, int m, int lane) { return __int_as_float(__builtin_amdgcn_ds_bpermute((lane ^ m) << 2, __float_as_int(v))); }
; __device__ __forceinline__ void gla_g3_item(int wv, const Params& p, int l, int b, int n, int h, LAS unsigned char* lds) {
;     ...
;     { const int t = tf; float o[12]; float ss = 0.f;
; #pragma unroll
;       for (int e = 0; e < 12; ++e) { o[e] = Ob[t * 97 + part * 12 + e]; ss += o[e] * o[e]; }
;       ss += shx(ss, 1, lane); ss += shx(ss, 2, lane); ss += shx(ss, 4, lane);
;       const float rs = rsqrtf(ss * (1.0f / 96.0f) + 1e-6f);
;       const float* gn = p.gla_o_norm + l * 96 + part * 12;
;       bf16_t* yp = (bf16_t*)(p.ws + OFF_HY) + (size_t)(row0 + t) * 1024 + 640 + h * 96 + part * 12;
; #pragma unroll
;       for (int q4 = 0; q4 < 3; ++q4) { const u32x2 gw = ggw[q4]; float g[4] = {bflo(gw.x), bfhi(gw.x), bflo(gw.y), bfhi(gw.y)}; float r[4];
; #pragma unroll
;           for (int e = 0; e < 4; ++e) r[e] = o[q4 * 4 + e] * rs * gn[q4 * 4 + e] * (g[e] * __builtin_amdgcn_rcpf(1.f + __expf(-g[e])));
;           u32x2 w; w.x = pk_bf16(r[0], r[1]); w.y = pk_bf16(r[2], r[3]); *(u32x2*)(yp + q4 * 4) = w; } }
	global_load_dwordx4 v[2:5], v0, s[14:15]
	global_load_dwordx4 v[144:147], v0, s[14:15] offset:16
	global_load_dwordx4 v[148:151], v0, s[14:15] offset:32
	v_add3_u32 v22, 0, v10, v0
	ds_read2_b32 v[10:11], v22 offset1:1
	ds_read2_b32 v[12:13], v22 offset0:2 offset1:3
	ds_read2_b32 v[14:15], v22 offset0:4 offset1:5
	ds_read2_b32 v[16:17], v22 offset0:6 offset1:7
	s_waitcnt lgkmcnt(3)
	v_mul_f32_e32 v20, v11, v11
	v_fmac_f32_e32 v20, v10, v10
	s_waitcnt lgkmcnt(2)
	v_fmac_f32_e32 v20, v12, v12
	v_fmac_f32_e32 v20, v13, v13
	s_waitcnt lgkmcnt(1)
	v_pk_mul_f32 v[18:19], v[14:15], v[14:15]
	s_waitcnt vmcnt(0)
	v_mov_b32_e32 v31, v2
	v_add_f32_e32 v18, v20, v18
	v_add_f32_e32 v23, v18, v19
	ds_read2_b32 v[18:19], v22 offset0:8 offset1:9
	s_waitcnt lgkmcnt(1)
	v_pk_mul_f32 v[20:21], v[16:17], v[16:17]
	s_nop 0
	v_add_f32_e32 v20, v23, v20
	ds_read2_b32 v[22:23], v22 offset0:10 offset1:11
	v_add_f32_e32 v24, v20, v21
	s_waitcnt lgkmcnt(1)
	v_pk_mul_f32 v[20:21], v[18:19], v[18:19]
	s_nop 0
	v_add_f32_e32 v20, v24, v20
	v_add_f32_e32 v24, v20, v21
	s_waitcnt lgkmcnt(0)
	v_pk_mul_f32 v[20:21], v[22:23], v[22:23]
	s_nop 0
	v_add_f32_e32 v20, v24, v20
	v_add_f32_e32 v20, v20, v21
	v_lshlrev_b32_e32 v21, 2, v30
	v_xor_b32_e32 v24, 4, v21
	s_nop 1
	v_mov_b32_dpp v24, v20 quad_perm:[1,0,3,2] row_mask:0xf bank_mask:0xf
	s_waitcnt lgkmcnt(0)
	v_add_f32_e32 v20, v20, v24
	v_xor_b32_e32 v24, 8, v21
	s_nop 1
	v_mov_b32_dpp v24, v20 quad_perm:[2,3,0,1] row_mask:0xf bank_mask:0xf
	v_xor_b32_e32 v21, 16, v21
	s_waitcnt lgkmcnt(0)
	v_add_f32_e32 v20, v20, v24
	s_nop 1
	v_mov_b32_dpp v21, v20 row_half_mirror row_mask:0xf bank_mask:0xf
	v_lshlrev_b32_e32 v24, 16, v6
	v_and_b32_e32 v6, 0xffff0000, v6
	v_mul_f32_e32 v7, 0xbfb8aa3b, v24
	v_exp_f32_e32 v7, v7
	s_waitcnt lgkmcnt(0)
	v_add_f32_e32 v20, v20, v21
	v_fmamk_f32 v20, v20, 0x3c2aaaab, v197
	v_mul_f32_e32 v21, 0x4b800000, v20
	v_cmp_gt_f32_e32 vcc, s68, v20
	v_add_f32_e32 v7, 1.0, v7
	v_rcp_f32_e32 v30, v7
	v_cndmask_b32_e32 v20, v20, v21, vcc
	v_rsq_f32_e32 v20, v20
	s_nop 0
	v_mul_f32_e32 v21, 0x45800000, v20
	v_cndmask_b32_e32 v32, v20, v21, vcc
	v_mul_f32_e32 v25, v10, v32
	v_mul_f32_e32 v10, 0xbfb8aa3b, v6
	v_exp_f32_e32 v10, v10
	v_mul_f32_e32 v7, v11, v32
	v_lshlrev_b64 v[20:21], 11, v[58:59]
	v_lshl_add_u64 v[20:21], s[6:7], 0, v[20:21]
	v_add_f32_e32 v2, 1.0, v10
	v_rcp_f32_e32 v2, v2
	v_lshl_add_u64 v[20:21], v[20:21], 0, s[56:57]
	v_mul_f32_e32 v27, v12, v32
	v_lshl_add_u64 v[20:21], v[20:21], 0, v[60:61]
	v_pk_mul_f32 v[2:3], v[2:3], v[6:7]
	v_mul_f32_e32 v29, v13, v32
	v_mul_f32_e32 v6, v2, v3
	v_mul_f32_e32 v2, 0xbfb8aa3b, v26
	v_exp_f32_e32 v2, v2
	v_mul_f32_e32 v3, 0xbfb8aa3b, v28
	v_exp_f32_e32 v7, v3
	v_mov_b32_e32 v3, v4
	v_add_f32_e32 v2, 1.0, v2
	v_rcp_f32_e32 v2, v2
	v_add_f32_e32 v4, 1.0, v7
	v_rcp_f32_e32 v4, v4
	v_pk_mul_f32 v[24:25], v[30:31], v[24:25]
	v_pk_mul_f32 v[2:3], v[2:3], v[26:27]
	v_mul_f32_e32 v10, v24, v25
	v_mul_f32_e32 v7, v2, v3
	v_pk_mul_f32 v[2:3], v[4:5], v[28:29]
	v_add_co_u32_e32 v4, vcc, s68, v20
	v_mul_f32_e32 v3, v2, v3
	s_nop 0
	v_addc_co_u32_e32 v5, vcc, 0, v21, vcc
	v_cvt_pk_bf16_f32 v2, v10, v6
	v_cvt_pk_bf16_f32 v3, v7, v3
	global_store_dwordx2 v[4:5], v[2:3], off offset:1280
	v_lshlrev_b32_e32 v10, 16, v8
	v_mul_f32_e32 v11, 0xbfb8aa3b, v10
	v_exp_f32_e32 v13, v11
	v_lshl_add_u64 v[6:7], v[20:21], 0, s[4:5]
	v_and_b32_e32 v8, 0xffff0000, v8
	v_lshlrev_b32_e32 v12, 16, v9
	v_and_b32_e32 v20, 0xffff0000, v9
	v_add_f32_e32 v9, 1.0, v13
	v_rcp_f32_e32 v24, v9
	v_mul_f32_e32 v9, 0xbfb8aa3b, v8
	v_exp_f32_e32 v9, v9
	v_mul_f32_e32 v11, v14, v32
	v_mov_b32_e32 v2, v144
	v_mov_b32_e32 v3, v145
	v_mov_b32_e32 v4, v146
	v_mov_b32_e32 v5, v147
	v_mov_b32_e32 v25, v2
	v_add_f32_e32 v2, 1.0, v9
	v_rcp_f32_e32 v2, v2
	v_pk_mul_f32 v[10:11], v[24:25], v[10:11]
	v_mul_f32_e32 v9, 0xbfb8aa3b, v12
	v_mul_f32_e32 v10, v10, v11
	v_exp_f32_e32 v11, v9
	v_mul_f32_e32 v9, v15, v32
	v_pk_mul_f32 v[2:3], v[2:3], v[8:9]
	v_mov_b32_e32 v13, v4
	v_mul_f32_e32 v14, v2, v3
	v_mul_f32_e32 v3, 0xbfb8aa3b, v20
	v_exp_f32_e32 v8, v3
	v_add_f32_e32 v2, 1.0, v11
	v_rcp_f32_e32 v2, v2
	v_mul_f32_e32 v3, v16, v32
	v_add_f32_e32 v4, 1.0, v8
	v_rcp_f32_e32 v8, v4
	v_pk_mul_f32 v[2:3], v[2:3], v[12:13]
	v_mul_f32_e32 v9, v17, v32
	v_mov_b32_e32 v21, v5
	v_mul_f32_e32 v4, v2, v3
	v_pk_mul_f32 v[2:3], v[8:9], v[20:21]
	v_lshlrev_b32_e32 v8, 16, v46
	v_mul_f32_e32 v3, v2, v3
	v_cvt_pk_bf16_f32 v2, v10, v14
	v_cvt_pk_bf16_f32 v3, v4, v3
	global_store_dwordx2 v[6:7], v[2:3], off offset:8
	v_mul_f32_e32 v0, 0xbfb8aa3b, v8
	v_exp_f32_e32 v0, v0
	v_and_b32_e32 v10, 0xffff0000, v46
	v_mul_f32_e32 v17, v18, v32
	v_lshlrev_b32_e32 v12, 16, v47
	v_add_f32_e32 v0, 1.0, v0
	v_rcp_f32_e32 v16, v0
	v_mul_f32_e32 v0, 0xbfb8aa3b, v10
	v_exp_f32_e32 v0, v0
	v_and_b32_e32 v14, 0xffff0000, v47
	v_add_f32_e32 v0, 1.0, v0
	v_mov_b32_e32 v2, v148
	v_mov_b32_e32 v3, v149
	v_mov_b32_e32 v4, v150
	v_mov_b32_e32 v5, v151
	v_mov_b32_e32 v9, v2
	v_pk_mul_f32 v[8:9], v[16:17], v[8:9]
	v_mov_b32_e32 v11, v3
	v_mul_f32_e32 v16, v8, v9
	v_rcp_f32_e32 v8, v0
	v_mul_f32_e32 v0, 0xbfb8aa3b, v12
	v_exp_f32_e32 v0, v0
	v_mul_f32_e32 v9, v19, v32
	v_pk_mul_f32 v[2:3], v[8:9], v[10:11]
	v_mov_b32_e32 v13, v4
	v_add_f32_e32 v0, 1.0, v0
	v_mul_f32_e32 v10, v2, v3
	v_rcp_f32_e32 v2, v0
	v_mul_f32_e32 v0, 0xbfb8aa3b, v14
	v_exp_f32_e32 v0, v0
	v_mul_f32_e32 v3, v22, v32
	v_pk_mul_f32 v[2:3], v[2:3], v[12:13]
	v_mul_f32_e32 v9, v23, v32
	v_add_f32_e32 v0, 1.0, v0
	v_rcp_f32_e32 v8, v0
	v_mov_b32_e32 v15, v5
	v_mul_f32_e32 v0, v2, v3
	v_pk_mul_f32 v[2:3], v[8:9], v[14:15]
	s_nop 0
	v_mul_f32_e32 v3, v2, v3
	v_cvt_pk_bf16_f32 v2, v16, v10
	v_cvt_pk_bf16_f32 v3, v0, v3
	global_store_dwordx2 v[6:7], v[2:3], off offset:16

; __device__ __forceinline__ unsigned pk_bf16(float lo, float hi) { unsigned r; asm volatile("v_cvt_pk_bf16_f32 %0, %1, %2" : "=v"(r) : "v"(lo), "v"(hi)); return r; }
; __device__ __forceinline__ void gla_prep_load(PrepRegs& R, const Params& p, int l, int h, int row0, int wave, int fr, int fq) {
;     const bf16_t* Z = (const bf16_t*)(p.ws + OFF_Z);
; #pragma unroll
;     for (int q = 0; q < 3; ++q) { const int tile = wave * 3 + q, mi = tile / 6, ni = tile % 6, dir = ni / 3, c = (ni % 3) * 16 + fr;
;         R.ga[q] = *(const u32x4*)(Z + (size_t)(row0 + mi * 16 + fr) * ZLD + ZC_GA + fq * 8);
;         R.bw[q] = (u32x4){0u, 0u, 0u, 0u};
;         if ((fq >> 1) == dir) { const float* aw = p.gla_alpha_w + ((size_t)(l * 2 + dir) * 16 + (fq & 1) * 8) * 192 + h * 48 + c; float w[8];
; #pragma unroll
;             for (int e = 0; e < 8; ++e) w[e] = aw[e * 192];
;             R.bw[q].x = pk_bf16(w[0], w[1]); R.bw[q].y = pk_bf16(w[2], w[3]); R.bw[q].z = pk_bf16(w[4], w[5]); R.bw[q].w = pk_bf16(w[6], w[7]); }
;         R.bias[q] = p.gla_alpha_b[(size_t)(l * 2 + dir) * 192 + h * 48 + c]; }
; }
.LBB0_965:
	v_add_u32_e32 v2, s89, v83
	v_ashrrev_i32_e32 v82, 6, v2
	v_lshrrev_b32_e32 v0, 31, v2
	v_add_u32_e32 v0, v82, v0
	v_and_b32_e32 v81, 15, v83
	v_ashrrev_i32_e32 v100, 1, v0
	v_add_u32_e32 v3, s3, v81
	v_lshlrev_b32_e32 v93, 4, v100
	v_add_u32_e32 v0, v3, v93
	s_waitcnt lgkmcnt(0)
	v_mov_b64_e32 v[4:5], s[6:7]
	v_mad_i64_i32 v[4:5], s[4:5], v0, s86, v[4:5]
	v_and_b32_e32 v0, 48, v83
	v_lshl_add_u64 v[4:5], v[4:5], 0, v[0:1]
	v_add_co_u32_e32 v4, vcc, 0x2c00000, v4
	v_lshl_add_u32 v12, v82, 1, v82
	s_nop 0
	v_addc_co_u32_e32 v5, vcc, 0, v5, vcc
	global_load_dwordx4 v[6:9], v[4:5], off offset:3072
	v_mul_hi_i32 v4, v12, s77
	v_lshrrev_b32_e32 v5, 31, v4
	v_add_u32_e32 v4, v4, v5
	v_mul_lo_u32 v4, v4, 6
	v_sub_u32_e32 v99, v12, v4
	v_mul_lo_u16_sdwa v4, sext(v99), s51 dst_sel:DWORD dst_unused:UNUSED_PAD src0_sel:BYTE_0 src1_sel:DWORD
	v_lshrrev_b16_e32 v5, 15, v4
	v_add_u16_sdwa v4, v4, v5 dst_sel:DWORD dst_unused:UNUSED_PAD src0_sel:BYTE_1 src1_sel:DWORD
	v_bfe_i32 v94, v4, 0, 8
	v_mul_lo_u16_e32 v4, 3, v4
	v_sub_u16_e32 v4, v99, v4
	v_bfe_i32 v95, v4, 0, 8
	v_bfe_u32 v10, v83, 5, 1
	v_lshl_or_b32 v74, v95, 4, v81
	v_cmp_eq_u32_e32 vcc, v10, v94
	v_ashrrev_i32_e32 v75, 31, v74
	s_nop 1
	v_cndmask_b32_e64 v140, 0, -1, vcc
	v_bfe_u32 v96, v83, 4, 2
	v_lshlrev_b32_e32 v84, 3, v96
	s_and_b32 s25, s22, 3
	v_and_b32_e32 v4, 8, v84
	v_or_b32_e32 v5, s94, v10
	s_mul_i32 s35, s25, 48
	v_lshl_or_b32 v11, v5, 4, v4
	v_mul_u32_u24_e32 v4, 0x300, v11
	v_mov_b32_e32 v5, v1
	v_lshl_add_u64 v[4:5], s[16:17], 0, v[4:5]
	s_lshl_b32 s56, s35, 2
	v_lshl_add_u64 v[4:5], v[4:5], 0, s[56:57]
	v_lshl_add_u64 v[4:5], v[74:75], 2, v[4:5]
	global_load_dword v112, v[4:5], off offset:768
	global_load_dword v113, v[4:5], off
	global_load_dword v114, v[4:5], off offset:2304
	global_load_dword v115, v[4:5], off offset:1536
	global_load_dword v116, v[4:5], off offset:3840
	global_load_dword v117, v[4:5], off offset:3072
	v_add_co_u32_e32 v4, vcc, 0x1000, v4
	s_nop 1
	v_addc_co_u32_e32 v5, vcc, 0, v5, vcc
	global_load_dword v118, v[4:5], off offset:1280
	s_nop 0
	global_load_dword v119, v[4:5], off offset:512
	v_add_u32_e32 v4, s94, v94
	v_mul_i32_i24_e32 v4, 0xc0, v4
	v_ashrrev_i32_e32 v5, 31, v4
	v_lshl_add_u64 v[4:5], v[4:5], 2, s[18:19]
	s_lshl_b32 s56, s35, 2
	v_lshl_add_u64 v[4:5], v[4:5], 0, s[56:57]
	v_lshl_add_u64 v[4:5], v[74:75], 2, v[4:5]
	v_add_u32_e32 v13, 1, v12
	global_load_dword v103, v[4:5], off
	v_mul_hi_i32 v4, v13, s77
	v_lshrrev_b32_e32 v5, 31, v4
	v_add_u32_e32 v101, v4, v5
	v_lshlrev_b32_e32 v88, 4, v101
	v_add_u32_e32 v14, v3, v88
	v_mov_b64_e32 v[4:5], s[6:7]
	v_mad_i64_i32 v[14:15], s[4:5], v14, s86, v[4:5]
	v_lshlrev_b32_e32 v4, 1, v84
	v_mov_b32_e32 v5, v1
	v_lshl_add_u64 v[14:15], v[14:15], 0, v[4:5]
	v_add_co_u32_e32 v14, vcc, 0x2c00000, v14
	v_mul_lo_u32 v5, v101, 6
	s_nop 0
	v_addc_co_u32_e32 v15, vcc, 0, v15, vcc
	global_load_dwordx4 v[38:41], v[14:15], off offset:3072
	v_sub_u32_e32 v98, v13, v5
	v_mul_lo_u16_e32 v5, 0x56, v98
	v_lshrrev_b16_e32 v13, 15, v5
	v_add_u16_sdwa v5, v5, v13 dst_sel:DWORD dst_unused:UNUSED_PAD src0_sel:BYTE_1 src1_sel:DWORD
	v_bfe_i32 v89, v5, 0, 8
	v_mul_lo_u16_e32 v5, 3, v5
	v_sub_u16_e32 v5, v98, v5
	v_bfe_i32 v91, v5, 0, 8
	v_lshl_or_b32 v76, v91, 4, v81
	v_cmp_eq_u32_e32 vcc, v10, v89
	v_ashrrev_i32_e32 v77, 31, v76
	s_nop 1
	v_cndmask_b32_e64 v141, 0, -1, vcc
	v_mul_u32_u24_e32 v14, 0x300, v11
	v_mov_b32_e32 v15, v1
	v_lshl_add_u64 v[14:15], s[16:17], 0, v[14:15]
	v_lshl_add_u64 v[14:15], v[14:15], 0, s[56:57]
	v_lshl_add_u64 v[14:15], v[76:77], 2, v[14:15]
	global_load_dword v120, v[14:15], off offset:768
	global_load_dword v121, v[14:15], off
	global_load_dword v122, v[14:15], off offset:2304
	global_load_dword v123, v[14:15], off offset:1536
	global_load_dword v124, v[14:15], off offset:3840
	global_load_dword v125, v[14:15], off offset:3072
	v_add_co_u32_e32 v14, vcc, 0x1000, v14
	s_nop 1
	v_addc_co_u32_e32 v15, vcc, 0, v15, vcc
	global_load_dword v126, v[14:15], off offset:1280
	s_nop 0
	global_load_dword v127, v[14:15], off offset:512
	v_add_u32_e32 v5, s94, v89
	v_mul_i32_i24_e32 v14, 0xc0, v5
	v_ashrrev_i32_e32 v15, 31, v14
	v_lshl_add_u64 v[14:15], v[14:15], 2, s[18:19]
; __device__ __forceinline__ unsigned pk_bf16(float lo, float hi) { unsigned r; asm volatile("v_cvt_pk_bf16_f32 %0, %1, %2" : "=v"(r) : "v"(lo), "v"(hi)); return r; }
; __device__ __forceinline__ void gla_prep_load(PrepRegs& R, const Params& p, int l, int h, int row0, int wave, int fr, int fq) {
;     const bf16_t* Z = (const bf16_t*)(p.ws + OFF_Z);
; #pragma unroll
;     for (int q = 0; q < 3; ++q) { const int tile = wave * 3 + q, mi = tile / 6, ni = tile % 6, dir = ni / 3, c = (ni % 3) * 16 + fr;
;         R.ga[q] = *(const u32x4*)(Z + (size_t)(row0 + mi * 16 + fr) * ZLD + ZC_GA + fq * 8);
;         R.bw[q] = (u32x4){0u, 0u, 0u, 0u};
;         if ((fq >> 1) == dir) { const float* aw = p.gla_alpha_w + ((size_t)(l * 2 + dir) * 16 + (fq & 1) * 8) * 192 + h * 48 + c; float w[8];
; #pragma unroll
;             for (int e = 0; e < 8; ++e) w[e] = aw[e * 192];
;             R.bw[q].x = pk_bf16(w[0], w[1]); R.bw[q].y = pk_bf16(w[2], w[3]); R.bw[q].z = pk_bf16(w[4], w[5]); R.bw[q].w = pk_bf16(w[6], w[7]); }
;         R.bias[q] = p.gla_alpha_b[(size_t)(l * 2 + dir) * 192 + h * 48 + c]; }
; }
; __device__ __forceinline__ void gla_g3_item(int wv, const Params& p, int l, int b, int n, int h, LAS unsigned char* lds) {
;     ...
;     const int t3 = tid / 6, r6 = tid % 6, half = r6 / 3, j4 = (r6 % 3) * 4, c1 = half * 24 + j4;
;     u32x2 q1w = (u32x2){0u, 0u}, q2w = q1w, k1w = q1w, k2w = q1w; f32x4 ra = (f32x4){1.f, 0.f, 1.f, 0.f}, rb = ra;
;     if (tid < 384) { const bf16_t* zq = Z + (size_t)(row0 + t3) * ZLD + ZC_GQ + h * 48 + c1; const bf16_t* zk = Z + (size_t)(row0 + t3) * ZLD + ZC_GK + h * 48 + c1;
;         q1w = *(const u32x2*)zq; q2w = *(const u32x2*)(zq + 12); k1w = *(const u32x2*)zk; k2w = *(const u32x2*)(zk + 12);
;         if (latent) { const float* rp = (const float*)(p.ws + OFF_ROPE) + ((half ? t3 : n) * 12 + j4) * 2; ra = *(const f32x4*)rp; rb = *(const f32x4*)(rp + 4); } }
	v_lshl_add_u64 v[14:15], v[14:15], 0, s[56:57]
	v_lshl_add_u64 v[14:15], v[76:77], 2, v[14:15]
	global_load_dword v104, v[14:15], off
	v_add_u32_e32 v14, 2, v12
	v_mul_hi_i32 v5, v14, s77
	v_lshrrev_b32_e32 v12, 31, v5
	v_add_u32_e32 v102, v5, v12
	v_lshlrev_b32_e32 v75, 4, v102
	v_add_u32_e32 v3, v3, v75
	v_mov_b64_e32 v[12:13], s[6:7]
	v_mad_i64_i32 v[12:13], s[4:5], v3, s86, v[12:13]
	v_mov_b32_e32 v5, v1
	v_lshl_add_u64 v[4:5], v[12:13], 0, v[4:5]
	v_add_co_u32_e32 v4, vcc, 0x2c00000, v4
	v_mul_lo_u32 v3, v102, 6
	s_nop 0
	v_addc_co_u32_e32 v5, vcc, 0, v5, vcc
	global_load_dwordx4 v[42:45], v[4:5], off offset:3072
	v_sub_u32_e32 v97, v14, v3
	v_mul_lo_u16_e32 v3, 0x56, v97
	v_lshrrev_b16_e32 v4, 15, v3
	v_add_u16_sdwa v3, v3, v4 dst_sel:DWORD dst_unused:UNUSED_PAD src0_sel:BYTE_1 src1_sel:DWORD
	v_bfe_i32 v77, v3, 0, 8
	v_mul_lo_u16_e32 v3, 3, v3
	v_sub_u16_e32 v3, v97, v3
	v_bfe_i32 v85, v3, 0, 8
	v_lshl_or_b32 v78, v85, 4, v81
	v_cmp_eq_u32_e32 vcc, v10, v77
	v_ashrrev_i32_e32 v79, 31, v78
	s_nop 1
	v_cndmask_b32_e64 v142, 0, -1, vcc
	v_mov_b32_e32 v10, 0
	v_mul_u32_u24_e32 v4, 0x300, v11
	v_mov_b32_e32 v5, v1
	v_lshl_add_u64 v[4:5], s[16:17], 0, v[4:5]
	v_lshl_add_u64 v[4:5], v[4:5], 0, s[56:57]
	v_lshl_add_u64 v[4:5], v[78:79], 2, v[4:5]
	global_load_dword v132, v[4:5], off offset:768
	global_load_dword v133, v[4:5], off
	global_load_dword v134, v[4:5], off offset:2304
	global_load_dword v135, v[4:5], off offset:1536
	global_load_dword v136, v[4:5], off offset:3840
	global_load_dword v137, v[4:5], off offset:3072
	v_add_co_u32_e32 v4, vcc, 0x1000, v4
	s_nop 1
	v_addc_co_u32_e32 v5, vcc, 0, v5, vcc
	global_load_dword v138, v[4:5], off offset:1280
	s_nop 0
	global_load_dword v139, v[4:5], off offset:512
	v_add_u32_e32 v3, s94, v77
	v_mul_i32_i24_e32 v4, 0xc0, v3
	v_ashrrev_i32_e32 v5, 31, v4
	v_lshl_add_u64 v[4:5], v[4:5], 2, s[18:19]
	v_lshl_add_u64 v[4:5], v[4:5], 0, s[56:57]
	v_lshl_add_u64 v[4:5], v[78:79], 2, v[4:5]
	global_load_dword v105, v[4:5], off
	v_mul_hi_i32 v3, v2, s77
	v_lshrrev_b32_e32 v4, 31, v3
	v_add_u32_e32 v5, v3, v4
	v_mul_lo_u32 v3, v5, 6
	v_sub_u32_e32 v3, v2, v3
	v_mul_lo_u16_e32 v4, 0x56, v3
	v_lshrrev_b16_e32 v11, 15, v4
	v_add_u16_sdwa v11, v4, v11 dst_sel:DWORD dst_unused:UNUSED_PAD src0_sel:BYTE_1 src1_sel:DWORD
	v_mul_lo_u16_e32 v4, 3, v11
	v_sub_u16_e32 v4, v3, v4
	s_add_u32 s36, s6, 0x2c00000
	v_lshlrev_b32_sdwa v4, v240, sext(v4) dst_sel:DWORD dst_unused:UNUSED_PAD src0_sel:DWORD src1_sel:BYTE_0
	v_mul_lo_u16_e32 v11, 24, v11
	s_addc_u32 s37, s7, 0
	v_add_u32_sdwa v64, v4, sext(v11) dst_sel:DWORD dst_unused:UNUSED_PAD src0_sel:DWORD src1_sel:BYTE_0
	v_cmp_gt_i32_e64 s[22:23], s52, v2
	v_mov_b32_e32 v30, 1.0
	v_mov_b32_e32 v31, 0
	v_mov_b32_e32 v32, 1.0
	v_mov_b32_e32 v33, 0
	v_mov_b32_e32 v34, 1.0
	v_mov_b32_e32 v35, 0
	v_mov_b32_e32 v36, 1.0
	v_mov_b32_e32 v37, 0
	v_mov_b32_e32 v68, 0
	v_mov_b32_e32 v69, 0
	v_mov_b32_e32 v66, 0
	v_mov_b32_e32 v67, 0
	v_mov_b32_e32 v72, 0
	v_mov_b32_e32 v73, 0
	v_mov_b32_e32 v70, 0
	v_mov_b32_e32 v71, 0
	s_and_saveexec_b64 s[16:17], s[22:23]
	s_cbranch_execz .LBB0_977
	v_add_u32_e32 v11, s3, v5
	v_mov_b64_e32 v[12:13], s[36:37]
	v_mad_i64_i32 v[12:13], s[4:5], v11, s86, v[12:13]
	s_lshl_b32 s56, s35, 1
	v_lshl_add_u64 v[12:13], v[12:13], 0, s[56:57]
	v_ashrrev_i32_e32 v65, 31, v64
	v_lshl_add_u64 v[12:13], v[64:65], 1, v[12:13]
	global_load_dwordx2 v[70:71], v[12:13], off offset:1536
	global_load_dwordx2 v[72:73], v[12:13], off offset:1560
	global_load_dwordx2 v[66:67], v[12:13], off offset:1920
	global_load_dwordx2 v[68:69], v[12:13], off offset:1944
	s_andn2_b64 vcc, exec, s[14:15]
	s_cbranch_vccnz .LBB0_976
	v_add_u32_e32 v3, 2, v3
	v_mov_b32_e32 v11, s34
	v_cmp_gt_u32_e32 vcc, 5, v3
	s_mov_b64 s[4:5], 0xfab8000
	s_nop 0
	v_cndmask_b32_e32 v3, v5, v11, vcc
	v_mul_lo_u32 v3, v3, 12
	v_add_lshl_u32 v12, v3, v4, 1
	v_ashrrev_i32_e32 v13, 31, v12
	v_lshl_add_u64 v[12:13], v[12:13], 2, s[6:7]
	v_lshl_add_u64 v[14:15], v[12:13], 0, s[4:5]
	v_add_co_u32_e32 v12, vcc, 0xfab8000, v12
	s_nop 1
	v_addc_co_u32_e32 v13, vcc, 0, v13, vcc
	global_load_dwordx4 v[34:37], v[12:13], off
	global_load_dwordx4 v[30:33], v[14:15], off offset:16
	s_branch .LBB0_977

; #define LAS __attribute__((address_space(3)))
; __device__ __forceinline__ unsigned pk_bf16(float lo, float hi) { unsigned r; asm volatile("v_cvt_pk_bf16_f32 %0, %1, %2" : "=v"(r) : "v"(lo), "v"(hi)); return r; }
; __device__ __forceinline__ f32x4 mfma16(bf16x8 a, bf16x8 b, f32x4 c) { return __builtin_amdgcn_mfma_f32_16x16x32_bf16(a, b, c, 0, 0, 0); }
; __device__ __forceinline__ void gla_prep(const PrepRegs& R, LAS unsigned char* lds, int wave, int fr, int fq) {
;     LAS float* G = (LAS float*)(lds + GL_G);
;     __syncthreads();
; #pragma unroll
;     for (int q = 0; q < 3; ++q) { const int tile = wave * 3 + q, mi = tile / 6, ni = tile % 6, dir = ni / 3, c = (ni % 3) * 16 + fr;
;         const f32x4 acc = mfma16(as_bf8(R.ga[q]), as_bf8(R.bw[q]), (f32x4){0.f, 0.f, 0.f, 0.f});
;         float g[4];
; #pragma unroll
;         for (int i = 0; i < 4; ++i) { const float sv = acc[i] + R.bias[q]; g[i] = (fminf(sv, 0.f) - __logf(1.f + __expf(-fabsf(sv)))) * (1.0f / 16.0f); }
;         u32x2 w2; w2.x = pk_bf16(g[0], g[1]); w2.y = pk_bf16(g[2], g[3]);
;         *(LAS u32x2*)(lds + GL_GT + (dir * 48 + c) * 144 + (mi * 16 + fq * 4) * 2) = w2; }
; __device__ __forceinline__ void gla_g3_item(int wv, const Params& p, int l, int b, int n, int h, LAS unsigned char* lds) {
;     ...
;     { const bf16_t* gp = Z + (size_t)(row0 + tf) * ZLD + ZC_GG + h * 96 + part * 12;
; #pragma unroll
;       for (int q4 = 0; q4 < 3; ++q4) ggw[q4] = *(const u32x2*)(gp + q4 * 4); }
.LBB0_991:
	s_or_b64 exec, exec, s[4:5]
	v_and_b32_e32 v59, 7, v83
	v_add_u32_e32 v58, s3, v63
	v_mov_b64_e32 v[60:61], s[36:37]
	v_mad_i64_i32 v[60:61], s[4:5], v58, s86, v[60:61]
	s_lshl_b32 s56, s34, 1
	v_mul_u32_u24_e32 v65, 12, v59
	v_lshl_add_u64 v[106:107], v[60:61], 0, s[56:57]
	v_lshlrev_b32_e32 v60, 1, v65
	v_mov_b32_e32 v61, v1
	v_lshl_add_u64 v[110:111], v[106:107], 0, v[60:61]
	s_waitcnt vmcnt(1)
	v_cvt_pk_bf16_f32 v46, v113, v112
	v_cvt_pk_bf16_f32 v47, v115, v114
	v_cvt_pk_bf16_f32 v48, v117, v116
	v_cvt_pk_bf16_f32 v49, v119, v118
	v_and_b32_e32 v46, v140, v46
	v_and_b32_e32 v47, v140, v47
	v_and_b32_e32 v48, v140, v48
	v_and_b32_e32 v49, v140, v49
	v_cvt_pk_bf16_f32 v50, v121, v120
	v_cvt_pk_bf16_f32 v51, v123, v122
	v_cvt_pk_bf16_f32 v52, v125, v124
	v_cvt_pk_bf16_f32 v53, v127, v126
	v_and_b32_e32 v50, v141, v50
	v_and_b32_e32 v51, v141, v51
	v_and_b32_e32 v52, v141, v52
	v_and_b32_e32 v53, v141, v53
	v_cvt_pk_bf16_f32 v54, v133, v132
	v_cvt_pk_bf16_f32 v55, v135, v134
	v_cvt_pk_bf16_f32 v56, v137, v136
	v_cvt_pk_bf16_f32 v57, v139, v138
	v_and_b32_e32 v54, v142, v54
	v_and_b32_e32 v55, v142, v55
	v_and_b32_e32 v56, v142, v56
	v_and_b32_e32 v57, v142, v57
	v_mfma_f32_16x16x32_bf16 v[106:109], v[6:9], v[46:49], 0
	s_waitcnt vmcnt(3)
	v_mfma_f32_16x16x32_bf16 v[38:41], v[38:41], v[50:53], 0
	v_lshlrev_b32_e32 v52, 5, v100
	s_nop 4
	v_add_f32_e32 v48, v103, v106
	v_mul_f32_e64 v6, |v48|, s33
	v_exp_f32_e32 v49, v6
	v_add_f32_e32 v61, v103, v107
	v_mul_f32_e64 v106, |v61|, s33
	v_exp_f32_e32 v106, v106
	v_add_f32_e32 v49, 1.0, v49
	v_cmp_gt_f32_e64 s[24:25], s68, v49
	v_min_f32_e32 v48, 0, v48
	s_waitcnt vmcnt(2)
	v_add_f32_e32 v38, v104, v38
	v_cndmask_b32_e64 v59, 0, 32, s[24:25]
	v_ldexp_f32 v49, v49, v59
	v_log_f32_e32 v49, v49
	v_mul_f32_e64 v50, |v38|, s33
	v_exp_f32_e32 v50, v50
	global_load_dwordx2 v[46:47], v[110:111], off offset:2320
	global_load_dwordx4 v[6:9], v[110:111], off offset:2304
	v_mul_f32_e32 v59, 0x3f317217, v49
	v_fma_f32 v59, v49, s2, -v59
	v_fmac_f32_e32 v59, 0x3377d1cf, v49
	v_fmac_f32_e32 v59, 0x3f317217, v49
	v_cmp_lt_f32_e64 s[26:27], |v49|, s83
	v_add_f32_e32 v50, 1.0, v50
	s_nop 0
	v_cndmask_b32_e64 v49, v49, v59, s[26:27]
	v_cndmask_b32_e64 v59, 0, v241, s[24:25]
	v_sub_f32_e32 v49, v49, v59
	v_add_f32_e32 v59, 1.0, v106
	v_cmp_gt_f32_e64 s[24:25], s68, v59
	v_sub_f32_e32 v48, v48, v49
	v_min_f32_e32 v49, 0, v61
	v_cndmask_b32_e64 v106, 0, 32, s[24:25]
	v_ldexp_f32 v59, v59, v106
	v_log_f32_e32 v59, v59
	v_add_f32_e32 v106, v103, v108
	v_mul_f32_e64 v107, |v106|, s33
	v_exp_f32_e32 v107, v107
	v_mul_f32_e32 v61, 0x3f317217, v59
	v_fma_f32 v61, v59, s2, -v61
	v_fmac_f32_e32 v61, 0x3377d1cf, v59
	v_fmac_f32_e32 v61, 0x3f317217, v59
	v_cmp_lt_f32_e64 s[26:27], |v59|, s83
	v_add_f32_e32 v103, v103, v109
	v_mul_f32_e32 v48, 0x3d800000, v48
	v_cndmask_b32_e64 v59, v59, v61, s[26:27]
	v_cndmask_b32_e64 v61, 0, v241, s[24:25]
	v_sub_f32_e32 v59, v59, v61
	v_add_f32_e32 v61, 1.0, v107
	v_cmp_gt_f32_e64 s[24:25], s68, v61
	v_sub_f32_e32 v49, v49, v59
	v_min_f32_e32 v59, 0, v106
	v_cndmask_b32_e64 v107, 0, 32, s[24:25]
	v_ldexp_f32 v61, v61, v107
	v_log_f32_e32 v61, v61
	v_mul_f32_e64 v107, |v103|, s33
	v_exp_f32_e32 v107, v107
	v_mul_f32_e32 v49, 0x3d800000, v49
	v_mul_f32_e32 v106, 0x3f317217, v61
	v_fma_f32 v106, v61, s2, -v106
	v_fmac_f32_e32 v106, 0x3377d1cf, v61
	v_fmac_f32_e32 v106, 0x3f317217, v61
	v_cmp_lt_f32_e64 s[26:27], |v61|, s83
	s_barrier
	s_nop 0
	v_cndmask_b32_e64 v61, v61, v106, s[26:27]
	v_cndmask_b32_e64 v106, 0, v241, s[24:25]
	v_sub_f32_e32 v61, v61, v106
	v_add_f32_e32 v106, 1.0, v107
	v_cmp_gt_f32_e64 s[24:25], s68, v106
	v_sub_f32_e32 v59, v59, v61
	v_min_f32_e32 v61, 0, v103
	v_cndmask_b32_e64 v107, 0, 32, s[24:25]
	v_ldexp_f32 v106, v106, v107
	v_log_f32_e32 v106, v106
	v_mul_f32_e32 v59, 0x3d800000, v59
	v_cvt_pk_bf16_f32 v48, v48, v49
	v_add_f32_e32 v39, v104, v39
	v_mul_f32_e32 v103, 0x3f317217, v106
	v_fma_f32 v103, v106, s2, -v103
	v_fmac_f32_e32 v103, 0x3377d1cf, v106
	v_fmac_f32_e32 v103, 0x3f317217, v106
	v_cmp_lt_f32_e64 s[26:27], |v106|, s83
	v_min_f32_e32 v38, 0, v38
	v_add_f32_e32 v40, v104, v40
	v_cndmask_b32_e64 v103, v106, v103, s[26:27]
	v_cndmask_b32_e64 v106, 0, v241, s[24:25]
	v_sub_f32_e32 v103, v103, v106
	v_sub_f32_e32 v61, v61, v103
	v_cmp_gt_f32_e64 s[24:25], s68, v50
	v_mul_f32_e32 v61, 0x3d800000, v61
	v_cvt_pk_bf16_f32 v49, v59, v61
	v_mad_i32_i24 v59, v94, 48, v74
	v_cndmask_b32_e64 v53, 0, 32, s[24:25]
	v_mul_lo_u32 v51, v59, s55
	v_ldexp_f32 v50, v50, v53
	v_add_u32_e32 v51, 0, v51
	v_log_f32_e32 v50, v50
	v_add3_u32 v51, v51, v52, v84
	ds_write_b64 v51, v[48:49]
	v_mul_f32_e64 v49, |v39|, s33
	v_exp_f32_e32 v49, v49
	v_mul_f32_e32 v48, 0x3f317217, v50
	v_fma_f32 v48, v50, s2, -v48
	v_fmac_f32_e32 v48, 0x3377d1cf, v50
	v_fmac_f32_e32 v48, 0x3f317217, v50
	v_cmp_lt_f32_e64 s[26:27], |v50|, s83
	v_add_f32_e32 v49, 1.0, v49
	v_min_f32_e32 v39, 0, v39
	v_cndmask_b32_e64 v48, v50, v48, s[26:27]
	v_cndmask_b32_e64 v50, 0, v241, s[24:25]
	v_cmp_gt_f32_e64 s[24:25], s68, v49
	v_sub_f32_e32 v48, v48, v50
	v_sub_f32_e32 v38, v38, v48
	v_cndmask_b32_e64 v50, 0, 32, s[24:25]
	v_ldexp_f32 v49, v49, v50
	v_log_f32_e32 v49, v49
	v_mul_f32_e64 v50, |v40|, s33
	v_exp_f32_e32 v50, v50
	v_add_f32_e32 v41, v104, v41
	v_mul_f32_e32 v48, 0x3f317217, v49
	v_fma_f32 v48, v49, s2, -v48
	v_fmac_f32_e32 v48, 0x3377d1cf, v49
	v_fmac_f32_e32 v48, 0x3f317217, v49
	v_cmp_lt_f32_e64 s[26:27], |v49|, s83
	v_min_f32_e32 v40, 0, v40
	v_mul_f32_e32 v38, 0x3d800000, v38
	v_cndmask_b32_e64 v48, v49, v48, s[26:27]
	v_cndmask_b32_e64 v49, 0, v241, s[24:25]
	v_sub_f32_e32 v48, v48, v49
; #define LAS __attribute__((address_space(3)))
; __device__ __forceinline__ unsigned pk_bf16(float lo, float hi) { unsigned r; asm volatile("v_cvt_pk_bf16_f32 %0, %1, %2" : "=v"(r) : "v"(lo), "v"(hi)); return r; }
; __device__ __forceinline__ f32x4 mfma16(bf16x8 a, bf16x8 b, f32x4 c) { return __builtin_amdgcn_mfma_f32_16x16x32_bf16(a, b, c, 0, 0, 0); }
; __device__ __forceinline__ void gla_prep(const PrepRegs& R, LAS unsigned char* lds, int wave, int fr, int fq) {
;     ...
;     for (int q = 0; q < 3; ++q) { const int tile = wave * 3 + q, mi = tile / 6, ni = tile % 6, dir = ni / 3, c = (ni % 3) * 16 + fr;
;         const f32x4 acc = mfma16(as_bf8(R.ga[q]), as_bf8(R.bw[q]), (f32x4){0.f, 0.f, 0.f, 0.f});
;         float g[4];
; #pragma unroll
;         for (int i = 0; i < 4; ++i) { const float sv = acc[i] + R.bias[q]; g[i] = (fminf(sv, 0.f) - __logf(1.f + __expf(-fabsf(sv)))) * (1.0f / 16.0f); }
;         u32x2 w2; w2.x = pk_bf16(g[0], g[1]); w2.y = pk_bf16(g[2], g[3]);
;         *(LAS u32x2*)(lds + GL_GT + (dir * 48 + c) * 144 + (mi * 16 + fq * 4) * 2) = w2; }
;     __syncthreads();
	v_add_f32_e32 v49, 1.0, v50
	v_cmp_gt_f32_e64 s[24:25], s68, v49
	v_sub_f32_e32 v39, v39, v48
	v_mul_f32_e32 v39, 0x3d800000, v39
	v_cndmask_b32_e64 v50, 0, 32, s[24:25]
	v_ldexp_f32 v49, v49, v50
	v_log_f32_e32 v49, v49
	v_mul_f32_e64 v50, |v41|, s33
	v_exp_f32_e32 v50, v50
	v_min_f32_e32 v41, 0, v41
	v_mul_f32_e32 v48, 0x3f317217, v49
	v_fma_f32 v48, v49, s2, -v48
	v_fmac_f32_e32 v48, 0x3377d1cf, v49
	v_fmac_f32_e32 v48, 0x3f317217, v49
	v_cmp_lt_f32_e64 s[26:27], |v49|, s83
	v_or_b32_e32 v59, 3, v84
	v_or_b32_e32 v61, 4, v84
	v_cndmask_b32_e64 v48, v49, v48, s[26:27]
	v_cndmask_b32_e64 v49, 0, v241, s[24:25]
	v_sub_f32_e32 v48, v48, v49
	v_add_f32_e32 v49, 1.0, v50
	v_cmp_gt_f32_e64 s[24:25], s68, v49
	v_sub_f32_e32 v40, v40, v48
	v_mul_f32_e32 v40, 0x3d800000, v40
	v_cndmask_b32_e64 v50, 0, 32, s[24:25]
	v_ldexp_f32 v49, v49, v50
	v_log_f32_e32 v49, v49
	v_mad_i32_i24 v50, v89, 48, v76
	v_or_b32_e32 v74, 5, v84
	v_or_b32_e32 v76, 6, v84
	v_mul_f32_e32 v48, 0x3f317217, v49
	v_fma_f32 v48, v49, s2, -v48
	v_fmac_f32_e32 v48, 0x3377d1cf, v49
	v_fmac_f32_e32 v48, 0x3f317217, v49
	v_cmp_lt_f32_e64 s[26:27], |v49|, s83
	v_or_b32_e32 v100, 34, v84
	v_or_b32_e32 v103, 36, v84
	v_cndmask_b32_e64 v48, v49, v48, s[26:27]
	v_cndmask_b32_e64 v49, 0, v241, s[24:25]
	v_sub_f32_e32 v48, v48, v49
	v_sub_f32_e32 v41, v41, v48
	v_mul_f32_e32 v41, 0x3d800000, v41
	v_cvt_pk_bf16_f32 v48, v38, v39
	v_cvt_pk_bf16_f32 v49, v40, v41
	s_waitcnt vmcnt(3)
	v_mfma_f32_16x16x32_bf16 v[38:41], v[42:45], v[54:57], 0
	v_mul_lo_u32 v43, v50, s55
	v_add_u32_e32 v43, 0, v43
	v_lshlrev_b32_e32 v44, 5, v101
	v_add3_u32 v43, v43, v44, v84
	ds_write_b64 v43, v[48:49]
	s_waitcnt vmcnt(2)
	s_nop 1
	v_add_f32_e32 v38, v105, v38
	v_mul_f32_e64 v42, |v38|, s33
	v_exp_f32_e32 v42, v42
	v_add_f32_e32 v39, v105, v39
	v_mul_f32_e64 v44, |v39|, s33
	v_exp_f32_e32 v44, v44
	v_add_f32_e32 v42, 1.0, v42
	v_cmp_gt_f32_e64 s[24:25], s68, v42
	v_min_f32_e32 v38, 0, v38
	v_add_f32_e32 v40, v105, v40
	v_cndmask_b32_e64 v45, 0, 32, s[24:25]
	v_ldexp_f32 v42, v42, v45
	v_log_f32_e32 v42, v42
	v_min_f32_e32 v39, 0, v39
	v_add_f32_e32 v41, v105, v41
	v_or_b32_e32 v56, 1, v84
	v_mul_f32_e32 v43, 0x3f317217, v42
	v_fma_f32 v43, v42, s2, -v43
	v_fmac_f32_e32 v43, 0x3377d1cf, v42
	v_fmac_f32_e32 v43, 0x3f317217, v42
	v_cmp_lt_f32_e64 s[26:27], |v42|, s83
	v_or_b32_e32 v57, 2, v84
	v_or_b32_e32 v101, 35, v84
	v_cndmask_b32_e64 v42, v42, v43, s[26:27]
	v_cndmask_b32_e64 v43, 0, v241, s[24:25]
	v_sub_f32_e32 v42, v42, v43
	v_add_f32_e32 v43, 1.0, v44
	v_cmp_gt_f32_e64 s[24:25], s68, v43
	v_sub_f32_e32 v38, v38, v42
	v_mul_f32_e32 v38, 0x3d800000, v38
	v_cndmask_b32_e64 v44, 0, 32, s[24:25]
	v_ldexp_f32 v43, v43, v44
	v_log_f32_e32 v43, v43
	v_mul_f32_e64 v44, |v40|, s33
	v_exp_f32_e32 v44, v44
	v_min_f32_e32 v40, 0, v40
	v_mul_f32_e32 v42, 0x3f317217, v43
	v_fma_f32 v42, v43, s2, -v42
	v_fmac_f32_e32 v42, 0x3377d1cf, v43
	v_fmac_f32_e32 v42, 0x3f317217, v43
	v_cmp_lt_f32_e64 s[26:27], |v43|, s83
	v_or_b32_e32 v104, 37, v84
	v_or_b32_e32 v106, 38, v84
	v_cndmask_b32_e64 v42, v43, v42, s[26:27]
	v_cndmask_b32_e64 v43, 0, v241, s[24:25]
	v_sub_f32_e32 v42, v42, v43
	v_add_f32_e32 v43, 1.0, v44
	v_cmp_gt_f32_e64 s[24:25], s68, v43
	v_sub_f32_e32 v39, v39, v42
	v_mul_f32_e32 v39, 0x3d800000, v39
	v_cndmask_b32_e64 v44, 0, 32, s[24:25]
	v_ldexp_f32 v43, v43, v44
	v_log_f32_e32 v43, v43
	v_mul_f32_e64 v44, |v41|, s33
	v_exp_f32_e32 v44, v44
	v_min_f32_e32 v41, 0, v41
	v_mul_f32_e32 v42, 0x3f317217, v43
	v_fma_f32 v42, v43, s2, -v42
	v_fmac_f32_e32 v42, 0x3377d1cf, v43
	v_fmac_f32_e32 v42, 0x3f317217, v43
	v_cmp_lt_f32_e64 s[26:27], |v43|, s83
	v_cvt_pk_bf16_f32 v38, v38, v39
	s_nop 1
	v_cndmask_b32_e64 v42, v43, v42, s[26:27]
	v_cndmask_b32_e64 v43, 0, v241, s[24:25]
	v_sub_f32_e32 v42, v42, v43
	v_add_f32_e32 v43, 1.0, v44
	v_cmp_gt_f32_e64 s[24:25], s68, v43
	v_sub_f32_e32 v40, v40, v42
	v_mul_f32_e32 v40, 0x3d800000, v40
	v_cndmask_b32_e64 v44, 0, 32, s[24:25]
	v_ldexp_f32 v43, v43, v44
	v_log_f32_e32 v43, v43
	s_nop 0
	v_mul_f32_e32 v42, 0x3f317217, v43
	v_fma_f32 v42, v43, s2, -v42
	v_fmac_f32_e32 v42, 0x3377d1cf, v43
	v_fmac_f32_e32 v42, 0x3f317217, v43
	v_cmp_lt_f32_e64 s[26:27], |v43|, s83
	s_nop 1
	v_cndmask_b32_e64 v42, v43, v42, s[26:27]
	v_cndmask_b32_e64 v43, 0, v241, s[24:25]
	v_sub_f32_e32 v42, v42, v43
	v_sub_f32_e32 v41, v41, v42
	v_mul_f32_e32 v41, 0x3d800000, v41
	v_cvt_pk_bf16_f32 v39, v40, v41
	v_mad_i32_i24 v40, v77, 48, v78
	v_mul_lo_u32 v40, v40, s55
	v_add_u32_e32 v40, 0, v40
	v_lshlrev_b32_e32 v41, 5, v102
	v_add3_u32 v40, v40, v41, v84
	ds_write_b64 v40, v[38:39]
	v_or_b32_e32 v39, v93, v81
	v_add_u32_e32 v38, 0, v0
	v_lshl_or_b32 v41, v99, 4, v81
	v_cmp_le_i32_e64 s[24:25], v84, v39
	v_add_u32_e32 v40, 2, v99
	v_mad_i32_i24 v44, v41, s55, v38
	v_cndmask_b32_e64 v41, 0, 1, s[24:25]
	v_cmp_ge_i32_e64 s[24:25], v84, v39
	v_or_b32_e32 v78, 7, v84
	s_waitcnt lgkmcnt(0)
	v_cndmask_b32_e64 v42, 0, 1, s[24:25]
	v_cmp_gt_u32_e64 s[24:25], 5, v40
	s_barrier
; #define LAS __attribute__((address_space(3)))
; __device__ __forceinline__ f32x4 mfma16(bf16x8 a, bf16x8 b, f32x4 c) { return __builtin_amdgcn_mfma_f32_16x16x32_bf16(a, b, c, 0, 0, 0); }
; __device__ __forceinline__ void gla_prep(const PrepRegs& R, LAS unsigned char* lds, int wave, int fr, int fq) {
;     ...
;     for (int q = 0; q < 3; ++q) { const int tile = wave * 3 + q, mi = tile / 6, ni = tile % 6, dir = ni / 3;
;         f32x4 acc = (f32x4){0.f, 0.f, 0.f, 0.f};
; #pragma unroll
;         for (int kk = 0; kk < 2; ++kk) { const int t = mi * 16 + fr; bf16x8 tri;
; #pragma unroll
;             for (int e = 0; e < 8; ++e) { const int sidx = kk * 32 + fq * 8 + e; tri[e] = (dir ? (sidx >= t) : (sidx <= t)) ? (short)0x3F80 : (short)0; }
;             const bf16x8 bb = *(const LAS bf16x8*)(lds + GL_GT + (ni * 16 + fr) * 144 + kk * 64 + fq * 16);
;             acc = mfma16(tri, bb, acc); }
	s_nop 0
	v_cndmask_b32_e64 v40, v42, v41, s[24:25]
	v_and_b32_e32 v40, 1, v40
	v_cmp_eq_u32_e64 s[26:27], 1, v40
	v_or_b32_e32 v99, 33, v84
	s_nop 0
	v_cndmask_b32_e64 v40, 0, v242, s[26:27]
	v_cmp_ge_i32_e64 s[26:27], v56, v39
	s_nop 1
	v_cndmask_b32_e64 v41, 0, 1, s[26:27]
	v_cmp_lt_i32_e64 s[26:27], v84, v39
	s_nop 1
	v_cndmask_b32_e64 v42, 0, 1, s[26:27]
	v_cndmask_b32_e64 v41, v41, v42, s[24:25]
	v_and_b32_e32 v41, 1, v41
	v_cmp_eq_u32_e64 s[26:27], 1, v41
	s_nop 1
	v_cndmask_b32_e64 v45, 0, v242, s[26:27]
	v_cmp_le_i32_e64 s[26:27], v57, v39
	v_perm_b32 v40, v45, v40, s62
	s_nop 0
	v_cndmask_b32_e64 v41, 0, 1, s[26:27]
	v_cmp_ge_i32_e64 s[26:27], v57, v39
	s_nop 1
	v_cndmask_b32_e64 v42, 0, 1, s[26:27]
	v_cndmask_b32_e64 v41, v42, v41, s[24:25]
	v_and_b32_e32 v41, 1, v41
	v_cmp_eq_u32_e64 s[26:27], 1, v41
	s_nop 1
	v_cndmask_b32_e64 v41, 0, v242, s[26:27]
	v_cmp_le_i32_e64 s[26:27], v59, v39
	s_nop 1
	v_cndmask_b32_e64 v42, 0, 1, s[26:27]
	v_cmp_ge_i32_e64 s[26:27], v59, v39
	s_nop 1
	v_cndmask_b32_e64 v43, 0, 1, s[26:27]
	v_cndmask_b32_e64 v42, v43, v42, s[24:25]
	v_and_b32_e32 v42, 1, v42
	v_cmp_eq_u32_e64 s[26:27], 1, v42
	s_nop 1
	v_cndmask_b32_e64 v48, 0, v242, s[26:27]
	v_cmp_le_i32_e64 s[26:27], v61, v39
	v_perm_b32 v41, v48, v41, s62
	s_nop 0
	v_cndmask_b32_e64 v42, 0, 1, s[26:27]
	v_cmp_ge_i32_e64 s[26:27], v61, v39
	s_nop 1
	v_cndmask_b32_e64 v43, 0, 1, s[26:27]
	v_cndmask_b32_e64 v42, v43, v42, s[24:25]
	v_and_b32_e32 v42, 1, v42
	v_cmp_eq_u32_e64 s[26:27], 1, v42
	s_nop 1
	v_cndmask_b32_e64 v42, 0, v242, s[26:27]
	v_cmp_le_i32_e64 s[26:27], v74, v39
	s_nop 1
	v_cndmask_b32_e64 v43, 0, 1, s[26:27]
	v_cmp_ge_i32_e64 s[26:27], v74, v39
	s_nop 1
	v_cndmask_b32_e64 v49, 0, 1, s[26:27]
	v_cndmask_b32_e64 v43, v49, v43, s[24:25]
	v_and_b32_e32 v43, 1, v43
	v_cmp_eq_u32_e64 s[26:27], 1, v43
	s_nop 1
	v_cndmask_b32_e64 v49, 0, v242, s[26:27]
	v_cmp_le_i32_e64 s[26:27], v76, v39
	v_perm_b32 v42, v49, v42, s62
	s_nop 0
	v_cndmask_b32_e64 v43, 0, 1, s[26:27]
	v_cmp_ge_i32_e64 s[26:27], v76, v39
	s_nop 1
	v_cndmask_b32_e64 v50, 0, 1, s[26:27]
	v_cndmask_b32_e64 v43, v50, v43, s[24:25]
	v_and_b32_e32 v43, 1, v43
	v_cmp_eq_u32_e64 s[26:27], 1, v43
	s_nop 1
	v_cndmask_b32_e64 v43, 0, v242, s[26:27]
	v_cmp_le_i32_e64 s[26:27], v78, v39
	s_nop 1
	v_cndmask_b32_e64 v50, 0, 1, s[26:27]
	v_cmp_ge_i32_e64 s[26:27], v78, v39
	s_nop 1
	v_cndmask_b32_e64 v51, 0, 1, s[26:27]
	v_cndmask_b32_e64 v50, v51, v50, s[24:25]
	v_and_b32_e32 v50, 1, v50
	v_cmp_eq_u32_e64 s[26:27], 1, v50
	s_nop 1
	v_cndmask_b32_e64 v50, 0, v242, s[26:27]
	v_perm_b32 v43, v50, v43, s62
	ds_read_b128 v[48:51], v44
	ds_read_b128 v[52:55], v44 offset:64
	s_waitcnt lgkmcnt(1)
	v_mfma_f32_16x16x32_bf16 v[42:45], v[40:43], v[48:51], 0
	v_or_b32_e32 v41, 32, v84
	v_cmp_le_i32_e64 s[26:27], v41, v39
	s_nop 1
	v_cndmask_b32_e64 v40, 0, 1, s[26:27]
	v_cmp_ge_i32_e64 s[26:27], v41, v39
	s_nop 1
	v_cndmask_b32_e64 v48, 0, 1, s[26:27]
	v_cndmask_b32_e64 v40, v48, v40, s[24:25]
	v_and_b32_e32 v40, 1, v40
	v_cmp_eq_u32_e64 s[26:27], 1, v40
	s_nop 1
	v_cndmask_b32_e64 v40, 0, v242, s[26:27]
	v_cmp_le_i32_e64 s[26:27], v99, v39
	s_nop 1
	v_cndmask_b32_e64 v48, 0, 1, s[26:27]
	v_cmp_ge_i32_e64 s[26:27], v99, v39
	s_nop 1
	v_cndmask_b32_e64 v49, 0, 1, s[26:27]
	v_cndmask_b32_e64 v48, v49, v48, s[24:25]
	v_and_b32_e32 v48, 1, v48
	v_cmp_eq_u32_e64 s[26:27], 1, v48
	s_nop 1
	v_cndmask_b32_e64 v48, 0, v242, s[26:27]
	v_cmp_le_i32_e64 s[26:27], v100, v39
	v_perm_b32 v48, v48, v40, s62
	v_lshlrev_b32_e32 v40, 2, v96
	v_cndmask_b32_e64 v49, 0, 1, s[26:27]
	v_cmp_ge_i32_e64 s[26:27], v100, v39
	s_nop 1
	v_cndmask_b32_e64 v50, 0, 1, s[26:27]
	v_cndmask_b32_e64 v49, v50, v49, s[24:25]
	v_and_b32_e32 v49, 1, v49
	v_cmp_eq_u32_e64 s[26:27], 1, v49
	s_nop 1
	v_cndmask_b32_e64 v49, 0, v242, s[26:27]
	v_cmp_le_i32_e64 s[26:27], v101, v39
	s_nop 1
	v_cndmask_b32_e64 v50, 0, 1, s[26:27]
	v_cmp_ge_i32_e64 s[26:27], v101, v39
	s_nop 1
	v_cndmask_b32_e64 v51, 0, 1, s[26:27]
	v_cndmask_b32_e64 v50, v51, v50, s[24:25]
	v_and_b32_e32 v50, 1, v50
	v_cmp_eq_u32_e64 s[26:27], 1, v50
	s_nop 1
	v_cndmask_b32_e64 v102, 0, v242, s[26:27]
	v_cmp_le_i32_e64 s[26:27], v103, v39
	v_perm_b32 v49, v102, v49, s62
	s_nop 0
	v_cndmask_b32_e64 v50, 0, 1, s[26:27]
	v_cmp_ge_i32_e64 s[26:27], v103, v39
	s_nop 1
	v_cndmask_b32_e64 v51, 0, 1, s[26:27]
	v_cndmask_b32_e64 v50, v51, v50, s[24:25]
	v_and_b32_e32 v50, 1, v50
	v_cmp_eq_u32_e64 s[26:27], 1, v50
	s_nop 1
	v_cndmask_b32_e64 v50, 0, v242, s[26:27]
	v_cmp_le_i32_e64 s[26:27], v104, v39
	s_nop 1
	v_cndmask_b32_e64 v51, 0, 1, s[26:27]
	v_cmp_ge_i32_e64 s[26:27], v104, v39
	s_nop 1
	v_cndmask_b32_e64 v105, 0, 1, s[26:27]
	v_cndmask_b32_e64 v51, v105, v51, s[24:25]
	v_and_b32_e32 v51, 1, v51
	v_cmp_eq_u32_e64 s[26:27], 1, v51
	s_nop 1
	v_cndmask_b32_e64 v105, 0, v242, s[26:27]
	v_cmp_le_i32_e64 s[26:27], v106, v39
	v_perm_b32 v50, v105, v50, s62
	s_nop 0
	v_cndmask_b32_e64 v51, 0, 1, s[26:27]
	v_cmp_ge_i32_e64 s[26:27], v106, v39
	s_nop 1
	v_cndmask_b32_e64 v107, 0, 1, s[26:27]
	v_cndmask_b32_e64 v51, v107, v51, s[24:25]
	v_and_b32_e32 v51, 1, v51
	v_cmp_eq_u32_e64 s[26:27], 1, v51
	v_or_b32_e32 v107, 39, v84
	s_nop 0
	v_cndmask_b32_e64 v51, 0, v242, s[26:27]
	v_cmp_le_i32_e64 s[26:27], v107, v39
	s_nop 1
	v_cndmask_b32_e64 v108, 0, 1, s[26:27]
	v_cmp_ge_i32_e64 s[26:27], v107, v39
	s_nop 1
	v_cndmask_b32_e64 v39, 0, 1, s[26:27]
	v_cndmask_b32_e64 v39, v39, v108, s[24:25]
	v_and_b32_e32 v39, 1, v39
	v_cmp_eq_u32_e64 s[24:25], 1, v39
	s_nop 1
	v_cndmask_b32_e64 v39, 0, v242, s[24:25]
	v_perm_b32 v51, v39, v51, s62
	v_lshl_add_u32 v39, v81, 2, 0
	s_waitcnt lgkmcnt(0)
; #define LAS __attribute__((address_space(3)))
; __device__ __forceinline__ f32x4 mfma16(bf16x8 a, bf16x8 b, f32x4 c) { return __builtin_amdgcn_mfma_f32_16x16x32_bf16(a, b, c, 0, 0, 0); }
; __device__ __forceinline__ void gla_prep(const PrepRegs& R, LAS unsigned char* lds, int wave, int fr, int fq) {
;     ...
; #pragma unroll
;     for (int q = 0; q < 3; ++q) { const int tile = wave * 3 + q, mi = tile / 6, ni = tile % 6, dir = ni / 3;
;         f32x4 acc = (f32x4){0.f, 0.f, 0.f, 0.f};
; #pragma unroll
;         for (int kk = 0; kk < 2; ++kk) { const int t = mi * 16 + fr; bf16x8 tri;
; #pragma unroll
;             for (int e = 0; e < 8; ++e) { const int sidx = kk * 32 + fq * 8 + e; tri[e] = (dir ? (sidx >= t) : (sidx <= t)) ? (short)0x3F80 : (short)0; }
;             const bf16x8 bb = *(const LAS bf16x8*)(lds + GL_GT + (ni * 16 + fr) * 144 + kk * 64 + fq * 16);
;             acc = mfma16(tri, bb, acc); }
; #pragma unroll
;         for (int i = 0; i < 4; ++i) G[(dir * 64 + mi * 16 + fq * 4 + i) * 48 + (ni % 3) * 16 + fr] = acc[i]; }
	v_mfma_f32_16x16x32_bf16 v[42:45], v[48:51], v[52:55], v[42:45]
	v_lshl_add_u32 v48, v94, 6, v93
	v_or_b32_e32 v48, v48, v40
	v_lshlrev_b32_e32 v49, 6, v95
	v_mul_lo_u32 v48, v48, s69
	v_add3_u32 v48, v39, v49, v48
	v_add_u32_e32 v49, 0x3400, v48
	v_or_b32_e32 v93, v88, v81
	s_nop 0
	ds_write2_b32 v49, v42, v43 offset0:128 offset1:176
	v_add_u32_e32 v42, 0x3600, v48
	v_lshl_or_b32 v43, v98, 4, v81
	v_cmp_le_i32_e64 s[24:25], v84, v93
	ds_write2_b32 v42, v44, v45 offset0:96 offset1:144
	v_add_u32_e32 v42, 2, v98
	v_mad_u64_u32 v[52:53], s[4:5], v43, s55, v[38:39]
	v_cndmask_b32_e64 v43, 0, 1, s[24:25]
	v_cmp_ge_i32_e64 s[24:25], v84, v93
	s_nop 1
	v_cndmask_b32_e64 v44, 0, 1, s[24:25]
	v_cmp_gt_u32_e64 s[24:25], 5, v42
	s_nop 1
	v_cndmask_b32_e64 v42, v44, v43, s[24:25]
	v_and_b32_e32 v42, 1, v42
	v_cmp_eq_u32_e64 s[26:27], 1, v42
	s_nop 1
	v_cndmask_b32_e64 v42, 0, v242, s[26:27]
	v_cmp_ge_i32_e64 s[26:27], v56, v93
	s_nop 1
	v_cndmask_b32_e64 v43, 0, 1, s[26:27]
	v_cmp_lt_i32_e64 s[26:27], v84, v93
	s_nop 1
	v_cndmask_b32_e64 v44, 0, 1, s[26:27]
	v_cndmask_b32_e64 v43, v43, v44, s[24:25]
	v_and_b32_e32 v43, 1, v43
	v_cmp_eq_u32_e64 s[26:27], 1, v43
	s_nop 1
	v_cndmask_b32_e64 v48, 0, v242, s[26:27]
	v_cmp_le_i32_e64 s[26:27], v57, v93
	v_perm_b32 v42, v48, v42, s62
	s_nop 0
	v_cndmask_b32_e64 v43, 0, 1, s[26:27]
	v_cmp_ge_i32_e64 s[26:27], v57, v93
	s_nop 1
	v_cndmask_b32_e64 v44, 0, 1, s[26:27]
	v_cndmask_b32_e64 v43, v44, v43, s[24:25]
	v_and_b32_e32 v43, 1, v43
	v_cmp_eq_u32_e64 s[26:27], 1, v43
	s_nop 1
	v_cndmask_b32_e64 v43, 0, v242, s[26:27]
	v_cmp_le_i32_e64 s[26:27], v59, v93
	s_nop 1
	v_cndmask_b32_e64 v44, 0, 1, s[26:27]
	v_cmp_ge_i32_e64 s[26:27], v59, v93
	s_nop 1
	v_cndmask_b32_e64 v45, 0, 1, s[26:27]
	v_cndmask_b32_e64 v44, v45, v44, s[24:25]
	v_and_b32_e32 v44, 1, v44
	v_cmp_eq_u32_e64 s[26:27], 1, v44
	s_nop 1
	v_cndmask_b32_e64 v49, 0, v242, s[26:27]
	v_cmp_le_i32_e64 s[26:27], v61, v93
	v_perm_b32 v43, v49, v43, s62
	s_nop 0
	v_cndmask_b32_e64 v44, 0, 1, s[26:27]
	v_cmp_ge_i32_e64 s[26:27], v61, v93
	s_nop 1
	v_cndmask_b32_e64 v45, 0, 1, s[26:27]
	v_cndmask_b32_e64 v44, v45, v44, s[24:25]
	v_and_b32_e32 v44, 1, v44
	v_cmp_eq_u32_e64 s[26:27], 1, v44
	s_nop 1
	v_cndmask_b32_e64 v44, 0, v242, s[26:27]
	v_cmp_le_i32_e64 s[26:27], v74, v93
	s_nop 1
	v_cndmask_b32_e64 v45, 0, 1, s[26:27]
	v_cmp_ge_i32_e64 s[26:27], v74, v93
	s_nop 1
	v_cndmask_b32_e64 v50, 0, 1, s[26:27]
	v_cndmask_b32_e64 v45, v50, v45, s[24:25]
	v_and_b32_e32 v45, 1, v45
	v_cmp_eq_u32_e64 s[26:27], 1, v45
	s_nop 1
	v_cndmask_b32_e64 v50, 0, v242, s[26:27]
	v_cmp_le_i32_e64 s[26:27], v76, v93
	v_perm_b32 v44, v50, v44, s62
	s_nop 0
	v_cndmask_b32_e64 v45, 0, 1, s[26:27]
	v_cmp_ge_i32_e64 s[26:27], v76, v93
	s_nop 1
	v_cndmask_b32_e64 v51, 0, 1, s[26:27]
	v_cndmask_b32_e64 v45, v51, v45, s[24:25]
	v_and_b32_e32 v45, 1, v45
	v_cmp_eq_u32_e64 s[26:27], 1, v45
	s_nop 1
	v_cndmask_b32_e64 v45, 0, v242, s[26:27]
	v_cmp_le_i32_e64 s[26:27], v78, v93
	s_nop 1
	v_cndmask_b32_e64 v51, 0, 1, s[26:27]
	v_cmp_ge_i32_e64 s[26:27], v78, v93
	s_nop 1
	v_cndmask_b32_e64 v53, 0, 1, s[26:27]
	v_cndmask_b32_e64 v51, v53, v51, s[24:25]
	v_and_b32_e32 v51, 1, v51
	v_cmp_eq_u32_e64 s[26:27], 1, v51
	s_nop 1
	v_cndmask_b32_e64 v51, 0, v242, s[26:27]
	v_perm_b32 v45, v51, v45, s62
	ds_read_b128 v[48:51], v52
	ds_read_b128 v[52:55], v52 offset:64
	v_cmp_le_i32_e64 s[26:27], v41, v93
	s_waitcnt lgkmcnt(1)
	v_mfma_f32_16x16x32_bf16 v[42:45], v[42:45], v[48:51], 0
	v_cndmask_b32_e64 v48, 0, 1, s[26:27]
	v_cmp_ge_i32_e64 s[26:27], v41, v93
	s_nop 1
	v_cndmask_b32_e64 v49, 0, 1, s[26:27]
	v_cndmask_b32_e64 v48, v49, v48, s[24:25]
	v_and_b32_e32 v48, 1, v48
	v_cmp_eq_u32_e64 s[26:27], 1, v48
	s_nop 1
	v_cndmask_b32_e64 v48, 0, v242, s[26:27]
	v_cmp_le_i32_e64 s[26:27], v99, v93
	s_nop 1
	v_cndmask_b32_e64 v49, 0, 1, s[26:27]
	v_cmp_ge_i32_e64 s[26:27], v99, v93
	s_nop 1
	v_cndmask_b32_e64 v50, 0, 1, s[26:27]
	v_cndmask_b32_e64 v49, v50, v49, s[24:25]
	v_and_b32_e32 v49, 1, v49
	v_cmp_eq_u32_e64 s[26:27], 1, v49
	s_nop 1
	v_cndmask_b32_e64 v94, 0, v242, s[26:27]
	v_cmp_le_i32_e64 s[26:27], v100, v93
	v_perm_b32 v48, v94, v48, s62
	s_nop 0
	v_cndmask_b32_e64 v49, 0, 1, s[26:27]
	v_cmp_ge_i32_e64 s[26:27], v100, v93
	s_nop 1
	v_cndmask_b32_e64 v50, 0, 1, s[26:27]
	v_cndmask_b32_e64 v49, v50, v49, s[24:25]
	v_and_b32_e32 v49, 1, v49
	v_cmp_eq_u32_e64 s[26:27], 1, v49
	s_nop 1
	v_cndmask_b32_e64 v49, 0, v242, s[26:27]
	v_cmp_le_i32_e64 s[26:27], v101, v93
	s_nop 1
	v_cndmask_b32_e64 v50, 0, 1, s[26:27]
	v_cmp_ge_i32_e64 s[26:27], v101, v93
	s_nop 1
	v_cndmask_b32_e64 v51, 0, 1, s[26:27]
	v_cndmask_b32_e64 v50, v51, v50, s[24:25]
	v_and_b32_e32 v50, 1, v50
	v_cmp_eq_u32_e64 s[26:27], 1, v50
	s_nop 1
	v_cndmask_b32_e64 v95, 0, v242, s[26:27]
	v_cmp_le_i32_e64 s[26:27], v103, v93
	v_perm_b32 v49, v95, v49, s62
	s_nop 0
	v_cndmask_b32_e64 v50, 0, 1, s[26:27]
	v_cmp_ge_i32_e64 s[26:27], v103, v93
	s_nop 1
	v_cndmask_b32_e64 v51, 0, 1, s[26:27]
	v_cndmask_b32_e64 v50, v51, v50, s[24:25]
	v_and_b32_e32 v50, 1, v50
	v_cmp_eq_u32_e64 s[26:27], 1, v50
	s_nop 1
	v_cndmask_b32_e64 v50, 0, v242, s[26:27]
	v_cmp_le_i32_e64 s[26:27], v104, v93
	s_nop 1
	v_cndmask_b32_e64 v51, 0, 1, s[26:27]
	v_cmp_ge_i32_e64 s[26:27], v104, v93
	s_nop 1
	v_cndmask_b32_e64 v96, 0, 1, s[26:27]
	v_cndmask_b32_e64 v51, v96, v51, s[24:25]
	v_and_b32_e32 v51, 1, v51
	v_cmp_eq_u32_e64 s[26:27], 1, v51
	s_nop 1
	v_cndmask_b32_e64 v96, 0, v242, s[26:27]
	v_cmp_le_i32_e64 s[26:27], v106, v93
	v_perm_b32 v50, v96, v50, s62
	s_nop 0
	v_cndmask_b32_e64 v51, 0, 1, s[26:27]
	v_cmp_ge_i32_e64 s[26:27], v106, v93
	s_nop 1
	v_cndmask_b32_e64 v98, 0, 1, s[26:27]
	v_cndmask_b32_e64 v51, v98, v51, s[24:25]
	v_and_b32_e32 v51, 1, v51
	v_cmp_eq_u32_e64 s[26:27], 1, v51
	s_nop 1
	v_cndmask_b32_e64 v51, 0, v242, s[26:27]
	v_cmp_le_i32_e64 s[26:27], v107, v93
	s_nop 1
	v_cndmask_b32_e64 v98, 0, 1, s[26:27]
	v_cmp_ge_i32_e64 s[26:27], v107, v93
	s_nop 1
	v_cndmask_b32_e64 v93, 0, 1, s[26:27]
	v_cndmask_b32_e64 v93, v93, v98, s[24:25]
	v_and_b32_e32 v93, 1, v93
	v_cmp_eq_u32_e64 s[24:25], 1, v93
	s_nop 1
	v_cndmask_b32_e64 v93, 0, v242, s[24:25]
	v_perm_b32 v51, v93, v51, s62
	s_waitcnt lgkmcnt(0)
; #define LAS __attribute__((address_space(3)))
; __device__ __forceinline__ f32x4 mfma16(bf16x8 a, bf16x8 b, f32x4 c) { return __builtin_amdgcn_mfma_f32_16x16x32_bf16(a, b, c, 0, 0, 0); }
; __device__ __forceinline__ void gla_prep(const PrepRegs& R, LAS unsigned char* lds, int wave, int fr, int fq) {
;     ...
; #pragma unroll
;     for (int q = 0; q < 3; ++q) { const int tile = wave * 3 + q, mi = tile / 6, ni = tile % 6, dir = ni / 3;
;         f32x4 acc = (f32x4){0.f, 0.f, 0.f, 0.f};
; #pragma unroll
;         for (int kk = 0; kk < 2; ++kk) { const int t = mi * 16 + fr; bf16x8 tri;
; #pragma unroll
;             for (int e = 0; e < 8; ++e) { const int sidx = kk * 32 + fq * 8 + e; tri[e] = (dir ? (sidx >= t) : (sidx <= t)) ? (short)0x3F80 : (short)0; }
;             const bf16x8 bb = *(const LAS bf16x8*)(lds + GL_GT + (ni * 16 + fr) * 144 + kk * 64 + fq * 16);
;             acc = mfma16(tri, bb, acc); }
; #pragma unroll
;         for (int i = 0; i < 4; ++i) G[(dir * 64 + mi * 16 + fq * 4 + i) * 48 + (ni % 3) * 16 + fr] = acc[i]; }
;     __syncthreads();
	s_nop 0
	v_mfma_f32_16x16x32_bf16 v[42:45], v[48:51], v[52:55], v[42:45]
	v_lshl_add_u32 v48, v89, 6, v88
	v_or_b32_e32 v48, v48, v40
	v_lshlrev_b32_e32 v49, 6, v91
	v_mul_lo_u32 v48, v48, s69
	v_add3_u32 v48, v39, v49, v48
	v_add_u32_e32 v49, 0x3400, v48
	v_or_b32_e32 v88, v75, v81
	s_nop 0
	ds_write2_b32 v49, v42, v43 offset0:128 offset1:176
	v_add_u32_e32 v42, 0x3600, v48
	v_lshl_or_b32 v43, v97, 4, v81
	v_cmp_le_i32_e64 s[24:25], v84, v88
	ds_write2_b32 v42, v44, v45 offset0:96 offset1:144
	v_add_u32_e32 v42, 2, v97
	v_mad_u64_u32 v[52:53], s[4:5], v43, s55, v[38:39]
	v_cndmask_b32_e64 v43, 0, 1, s[24:25]
	v_cmp_ge_i32_e64 s[24:25], v84, v88
	s_nop 1
	v_cndmask_b32_e64 v44, 0, 1, s[24:25]
	v_cmp_gt_u32_e64 s[24:25], 5, v42
	s_nop 1
	v_cndmask_b32_e64 v42, v44, v43, s[24:25]
	v_and_b32_e32 v42, 1, v42
	v_cmp_eq_u32_e64 s[26:27], 1, v42
	s_nop 1
	v_cndmask_b32_e64 v42, 0, v242, s[26:27]
	v_cmp_ge_i32_e64 s[26:27], v56, v88
	s_nop 1
	v_cndmask_b32_e64 v43, 0, 1, s[26:27]
	v_cmp_lt_i32_e64 s[26:27], v84, v88
	s_nop 1
	v_cndmask_b32_e64 v44, 0, 1, s[26:27]
	v_cndmask_b32_e64 v43, v43, v44, s[24:25]
	v_and_b32_e32 v43, 1, v43
	v_cmp_eq_u32_e64 s[26:27], 1, v43
	s_nop 1
	v_cndmask_b32_e64 v48, 0, v242, s[26:27]
	v_cmp_le_i32_e64 s[26:27], v57, v88
	v_perm_b32 v42, v48, v42, s62
	s_nop 0
	v_cndmask_b32_e64 v43, 0, 1, s[26:27]
	v_cmp_ge_i32_e64 s[26:27], v57, v88
	s_nop 1
	v_cndmask_b32_e64 v44, 0, 1, s[26:27]
	v_cndmask_b32_e64 v43, v44, v43, s[24:25]
	v_and_b32_e32 v43, 1, v43
	v_cmp_eq_u32_e64 s[26:27], 1, v43
	s_nop 1
	v_cndmask_b32_e64 v43, 0, v242, s[26:27]
	v_cmp_le_i32_e64 s[26:27], v59, v88
	s_nop 1
	v_cndmask_b32_e64 v44, 0, 1, s[26:27]
	v_cmp_ge_i32_e64 s[26:27], v59, v88
	s_nop 1
	v_cndmask_b32_e64 v45, 0, 1, s[26:27]
	v_cndmask_b32_e64 v44, v45, v44, s[24:25]
	v_and_b32_e32 v44, 1, v44
	v_cmp_eq_u32_e64 s[26:27], 1, v44
	s_nop 1
	v_cndmask_b32_e64 v49, 0, v242, s[26:27]
	v_cmp_le_i32_e64 s[26:27], v61, v88
	v_perm_b32 v43, v49, v43, s62
	s_nop 0
	v_cndmask_b32_e64 v44, 0, 1, s[26:27]
	v_cmp_ge_i32_e64 s[26:27], v61, v88
	s_nop 1
	v_cndmask_b32_e64 v45, 0, 1, s[26:27]
	v_cndmask_b32_e64 v44, v45, v44, s[24:25]
	v_and_b32_e32 v44, 1, v44
	v_cmp_eq_u32_e64 s[26:27], 1, v44
	s_nop 1
	v_cndmask_b32_e64 v44, 0, v242, s[26:27]
	v_cmp_le_i32_e64 s[26:27], v74, v88
	s_nop 1
	v_cndmask_b32_e64 v45, 0, 1, s[26:27]
	v_cmp_ge_i32_e64 s[26:27], v74, v88
	s_nop 1
	v_cndmask_b32_e64 v50, 0, 1, s[26:27]
	v_cndmask_b32_e64 v45, v50, v45, s[24:25]
	v_and_b32_e32 v45, 1, v45
	v_cmp_eq_u32_e64 s[26:27], 1, v45
	s_nop 1
	v_cndmask_b32_e64 v50, 0, v242, s[26:27]
	v_cmp_le_i32_e64 s[26:27], v76, v88
	v_perm_b32 v44, v50, v44, s62
	s_nop 0
	v_cndmask_b32_e64 v45, 0, 1, s[26:27]
	v_cmp_ge_i32_e64 s[26:27], v76, v88
	s_nop 1
	v_cndmask_b32_e64 v51, 0, 1, s[26:27]
	v_cndmask_b32_e64 v45, v51, v45, s[24:25]
	v_and_b32_e32 v45, 1, v45
	v_cmp_eq_u32_e64 s[26:27], 1, v45
	s_nop 1
	v_cndmask_b32_e64 v45, 0, v242, s[26:27]
	v_cmp_le_i32_e64 s[26:27], v78, v88
	s_nop 1
	v_cndmask_b32_e64 v51, 0, 1, s[26:27]
	v_cmp_ge_i32_e64 s[26:27], v78, v88
	s_nop 1
	v_cndmask_b32_e64 v53, 0, 1, s[26:27]
	v_cndmask_b32_e64 v51, v53, v51, s[24:25]
	v_and_b32_e32 v51, 1, v51
	v_cmp_eq_u32_e64 s[26:27], 1, v51
	s_nop 1
	v_cndmask_b32_e64 v51, 0, v242, s[26:27]
	v_perm_b32 v45, v51, v45, s62
	ds_read_b128 v[48:51], v52
	ds_read_b128 v[52:55], v52 offset:64
	v_cmp_le_i32_e64 s[26:27], v41, v88
	s_waitcnt lgkmcnt(1)
	v_mfma_f32_16x16x32_bf16 v[42:45], v[42:45], v[48:51], 0
	v_cndmask_b32_e64 v48, 0, 1, s[26:27]
	v_cmp_ge_i32_e64 s[26:27], v41, v88
	s_nop 1
	v_cndmask_b32_e64 v41, 0, 1, s[26:27]
	v_cndmask_b32_e64 v41, v41, v48, s[24:25]
	v_and_b32_e32 v41, 1, v41
	v_cmp_eq_u32_e64 s[26:27], 1, v41
	s_nop 1
	v_cndmask_b32_e64 v41, 0, v242, s[26:27]
	v_cmp_le_i32_e64 s[26:27], v99, v88
	s_nop 1
	v_cndmask_b32_e64 v48, 0, 1, s[26:27]
	v_cmp_ge_i32_e64 s[26:27], v99, v88
	s_nop 1
	v_cndmask_b32_e64 v49, 0, 1, s[26:27]
	v_cndmask_b32_e64 v48, v49, v48, s[24:25]
	v_and_b32_e32 v48, 1, v48
	v_cmp_eq_u32_e64 s[26:27], 1, v48
	s_nop 1
	v_cndmask_b32_e64 v48, 0, v242, s[26:27]
	v_cmp_le_i32_e64 s[26:27], v100, v88
	v_perm_b32 v48, v48, v41, s62
	v_lshl_add_u32 v41, v77, 6, v75
	v_cndmask_b32_e64 v49, 0, 1, s[26:27]
	v_cmp_ge_i32_e64 s[26:27], v100, v88
	v_or_b32_e32 v41, v41, v40
	v_mul_lo_u32 v41, v41, s69
	v_cndmask_b32_e64 v50, 0, 1, s[26:27]
	v_cndmask_b32_e64 v49, v50, v49, s[24:25]
	v_and_b32_e32 v49, 1, v49
	v_cmp_eq_u32_e64 s[26:27], 1, v49
	s_nop 1
	v_cndmask_b32_e64 v49, 0, v242, s[26:27]
	v_cmp_le_i32_e64 s[26:27], v101, v88
	s_nop 1
	v_cndmask_b32_e64 v50, 0, 1, s[26:27]
	v_cmp_ge_i32_e64 s[26:27], v101, v88
	s_nop 1
	v_cndmask_b32_e64 v51, 0, 1, s[26:27]
	v_cndmask_b32_e64 v50, v51, v50, s[24:25]
	v_and_b32_e32 v50, 1, v50
	v_cmp_eq_u32_e64 s[26:27], 1, v50
	s_nop 1
	v_cndmask_b32_e64 v56, 0, v242, s[26:27]
	v_cmp_le_i32_e64 s[26:27], v103, v88
	v_perm_b32 v49, v56, v49, s62
	s_nop 0
	v_cndmask_b32_e64 v50, 0, 1, s[26:27]
	v_cmp_ge_i32_e64 s[26:27], v103, v88
	s_nop 1
	v_cndmask_b32_e64 v51, 0, 1, s[26:27]
	v_cndmask_b32_e64 v50, v51, v50, s[24:25]
	v_and_b32_e32 v50, 1, v50
	v_cmp_eq_u32_e64 s[26:27], 1, v50
	s_nop 1
	v_cndmask_b32_e64 v50, 0, v242, s[26:27]
	v_cmp_le_i32_e64 s[26:27], v104, v88
	s_nop 1
	v_cndmask_b32_e64 v51, 0, 1, s[26:27]
	v_cmp_ge_i32_e64 s[26:27], v104, v88
	s_nop 1
	v_cndmask_b32_e64 v57, 0, 1, s[26:27]
	v_cndmask_b32_e64 v51, v57, v51, s[24:25]
	v_and_b32_e32 v51, 1, v51
	v_cmp_eq_u32_e64 s[26:27], 1, v51
	s_nop 1
	v_cndmask_b32_e64 v57, 0, v242, s[26:27]
	v_cmp_le_i32_e64 s[26:27], v106, v88
	v_perm_b32 v50, v57, v50, s62
	s_nop 0
	v_cndmask_b32_e64 v51, 0, 1, s[26:27]
	v_cmp_ge_i32_e64 s[26:27], v106, v88
	s_nop 1
	v_cndmask_b32_e64 v59, 0, 1, s[26:27]
	v_cndmask_b32_e64 v51, v59, v51, s[24:25]
	v_and_b32_e32 v51, 1, v51
	v_cmp_eq_u32_e64 s[26:27], 1, v51
	s_nop 1
	v_cndmask_b32_e64 v51, 0, v242, s[26:27]
	v_cmp_le_i32_e64 s[26:27], v107, v88
	s_nop 1
	v_cndmask_b32_e64 v59, 0, 1, s[26:27]
	v_cmp_ge_i32_e64 s[26:27], v107, v88
	s_nop 1
	v_cndmask_b32_e64 v61, 0, 1, s[26:27]
	v_cndmask_b32_e64 v59, v61, v59, s[24:25]
	v_and_b32_e32 v59, 1, v59
	v_cmp_eq_u32_e64 s[24:25], 1, v59
	s_nop 1
	v_cndmask_b32_e64 v59, 0, v242, s[24:25]
	v_perm_b32 v51, v59, v51, s62
	s_waitcnt lgkmcnt(0)
	s_nop 0
	v_mfma_f32_16x16x32_bf16 v[42:45], v[48:51], v[52:55], v[42:45]
	v_lshlrev_b32_e32 v48, 6, v85
	v_add3_u32 v41, v39, v48, v41
	v_add_u32_e32 v48, 0x3400, v41
	v_add_u32_e32 v41, 0x3600, v41
	s_nop 3
	ds_write2_b32 v48, v42, v43 offset0:128 offset1:176
	ds_write2_b32 v41, v44, v45 offset0:96 offset1:144
	s_waitcnt lgkmcnt(0)
	s_barrier
; #define LAS __attribute__((address_space(3)))
; __device__ __forceinline__ unsigned pk_bf16(float lo, float hi) { unsigned r; asm volatile("v_cvt_pk_bf16_f32 %0, %1, %2" : "=v"(r) : "v"(lo), "v"(hi)); return r; }
; __device__ __forceinline__ float bflo(unsigned w) { return __uint_as_float(w << 16); }
; __device__ __forceinline__ void gla_g3_item(int wv, const Params& p, int l, int b, int n, int h, LAS unsigned char* lds) {
;     ...
;     if (tid < 384) { const int t = t3;
;         float q1[4] = {bflo(q1w.x), bfhi(q1w.x), bflo(q1w.y), bfhi(q1w.y)}, q2[4] = {bflo(q2w.x), bfhi(q2w.x), bflo(q2w.y), bfhi(q2w.y)};
;         float k1[4] = {bflo(k1w.x), bfhi(k1w.x), bflo(k1w.y), bfhi(k1w.y)}, k2[4] = {bflo(k2w.x), bfhi(k2w.x), bflo(k2w.y), bfhi(k2w.y)};
;         { const float cn[4] = {ra[0], ra[2], rb[0], rb[2]}, sn[4] = {ra[1], ra[3], rb[1], rb[3]};
; #pragma unroll
;             for (int e = 0; e < 4; ++e) { float a1 = q1[e], a2 = q2[e]; q1[e] = a1 * cn[e] - a2 * sn[e]; q2[e] = a2 * cn[e] + a1 * sn[e];
;                 a1 = k1[e]; a2 = k2[e]; k1[e] = a1 * cn[e] - a2 * sn[e]; k2[e] = a2 * cn[e] + a1 * sn[e]; } }
; #pragma unroll
;         for (int dir = 0; dir < 2; ++dir) {
;             const f32x4 b1 = *(const LAS f32x4*)(G + (dir * 64 + t) * 48 + c1), b2 = *(const LAS f32x4*)(G + (dir * 64 + t) * 48 + c1 + 12);
;             float e1[4], e2[4], i1[4], i2[4];
; #pragma unroll
;             for (int e = 0; e < 4; ++e) { e1[e] = __expf(b1[e]); e2[e] = __expf(b2[e]); i1[e] = __expf(-b1[e]); i2[e] = __expf(-b2[e]); }
;             const float qs = 0.14433756729740643f;
;             u32x2 w;
;             w.x = pk_bf16(q1[0] * qs * e1[0], q1[1] * qs * e1[1]); w.y = pk_bf16(q1[2] * qs * e1[2], q1[3] * qs * e1[3]); *(LAS u32x2*)(lds + GL_Q + (dir * 64 + t) * 144 + c1 * 2) = w;
;             w.x = pk_bf16(q2[0] * qs * e2[0], q2[1] * qs * e2[1]); w.y = pk_bf16(q2[2] * qs * e2[2], q2[3] * qs * e2[3]); *(LAS u32x2*)(lds + GL_Q + (dir * 64 + t) * 144 + (c1 + 12) * 2) = w;
;             w.x = pk_bf16(k1[0] * i1[0], k1[1] * i1[1]); w.y = pk_bf16(k1[2] * i1[2], k1[3] * i1[3]); *(LAS u32x2*)(lds + GL_K + (dir * 64 + t) * 144 + c1 * 2) = w;
;             w.x = pk_bf16(k2[0] * i2[0], k2[1] * i2[1]); w.y = pk_bf16(k2[2] * i2[2], k2[3] * i2[3]); *(LAS u32x2*)(lds + GL_K + (dir * 64 + t) * 144 + (c1 + 12) * 2) = w; } }
	s_and_saveexec_b64 s[24:25], s[22:23]
	s_cbranch_execz .LBB0_993
	v_lshlrev_b32_e32 v43, 16, v72
	v_lshlrev_b32_e32 v42, 16, v70
	v_pk_mul_f32 v[44:45], v[34:35], v[42:43]
	v_pk_mul_f32 v[42:43], v[34:35], v[42:43] op_sel:[0,1] op_sel_hi:[1,0]
	v_sub_f32_e32 v41, v44, v45
	v_add_f32_e32 v48, v42, v43
	v_lshlrev_b32_e32 v43, 16, v68
	v_lshlrev_b32_e32 v42, 16, v66
	v_pk_mul_f32 v[44:45], v[34:35], v[42:43]
	v_pk_mul_f32 v[34:35], v[34:35], v[42:43] op_sel:[0,1] op_sel_hi:[1,0]
	v_sub_f32_e32 v44, v44, v45
	v_add_f32_e32 v45, v34, v35
	v_and_b32_e32 v35, 0xffff0000, v72
	v_and_b32_e32 v34, 0xffff0000, v70
	v_pk_mul_f32 v[42:43], v[36:37], v[34:35]
	v_pk_mul_f32 v[34:35], v[36:37], v[34:35] op_sel:[0,1] op_sel_hi:[1,0]
	v_sub_f32_e32 v49, v42, v43
	v_add_f32_e32 v50, v34, v35
	v_and_b32_e32 v35, 0xffff0000, v68
	v_and_b32_e32 v34, 0xffff0000, v66
	v_pk_mul_f32 v[42:43], v[36:37], v[34:35]
	v_pk_mul_f32 v[34:35], v[36:37], v[34:35] op_sel:[0,1] op_sel_hi:[1,0]
	v_sub_f32_e32 v42, v42, v43
	v_add_f32_e32 v43, v34, v35
	v_lshlrev_b32_e32 v35, 16, v73
	v_lshlrev_b32_e32 v34, 16, v71
	v_pk_mul_f32 v[36:37], v[30:31], v[34:35]
	v_pk_mul_f32 v[34:35], v[30:31], v[34:35] op_sel:[0,1] op_sel_hi:[1,0]
	v_sub_f32_e32 v51, v36, v37
	v_add_f32_e32 v52, v34, v35
	v_lshlrev_b32_e32 v35, 16, v69
	v_lshlrev_b32_e32 v34, 16, v67
	v_pk_mul_f32 v[36:37], v[30:31], v[34:35]
	v_pk_mul_f32 v[30:31], v[30:31], v[34:35] op_sel:[0,1] op_sel_hi:[1,0]
	v_sub_f32_e32 v53, v36, v37
	v_add_f32_e32 v54, v30, v31
	v_and_b32_e32 v31, 0xffff0000, v73
	v_and_b32_e32 v30, 0xffff0000, v71
	v_pk_mul_f32 v[34:35], v[32:33], v[30:31]
	v_pk_mul_f32 v[30:31], v[32:33], v[30:31] op_sel:[0,1] op_sel_hi:[1,0]
	v_sub_f32_e32 v36, v34, v35
	v_add_f32_e32 v55, v30, v31
	v_and_b32_e32 v31, 0xffff0000, v69
	v_and_b32_e32 v30, 0xffff0000, v67
	v_pk_mul_f32 v[34:35], v[32:33], v[30:31]
	v_pk_mul_f32 v[30:31], v[32:33], v[30:31] op_sel:[0,1] op_sel_hi:[1,0]
	v_lshlrev_b32_e32 v61, 1, v64
	v_add_f32_e32 v57, v30, v31
	v_lshlrev_b32_e32 v30, 2, v64
	v_mul_lo_u32 v31, v5, s69
	v_add3_u32 v64, 0, v30, v31
	ds_read_b128 v[30:33], v64 offset:13824
	v_sub_f32_e32 v56, v34, v35
	v_mul_f32_e32 v59, 0x3e13cd3a, v36
	ds_read_b128 v[34:37], v64 offset:13872
	v_mul_f32_e32 v41, 0x3e13cd3a, v41
	s_waitcnt lgkmcnt(1)
	v_mul_f32_e32 v66, 0x3fb8aa3b, v30
	v_mul_f32_e32 v30, 0xbfb8aa3b, v30
	v_exp_f32_e32 v68, v30
	s_waitcnt lgkmcnt(0)
	v_mul_f32_e32 v30, 0xbfb8aa3b, v34
	v_mul_f32_e32 v67, 0x3fb8aa3b, v34
	v_exp_f32_e32 v34, v30
	v_mul_f32_e32 v30, 0x3fb8aa3b, v31
	v_mul_f32_e32 v31, 0xbfb8aa3b, v31
	v_exp_f32_e32 v70, v31
	v_mul_f32_e32 v31, 0xbfb8aa3b, v35
	v_mul_f32_e32 v69, 0x3fb8aa3b, v35
	v_exp_f32_e32 v35, v31
	v_mul_f32_e32 v31, 0x3fb8aa3b, v32
	v_exp_f32_e32 v66, v66
	v_exp_f32_e32 v30, v30
	v_exp_f32_e32 v31, v31
	v_mul_f32_e32 v72, 0x3fb8aa3b, v33
	v_exp_f32_e32 v72, v72
	v_exp_f32_e32 v67, v67
	v_exp_f32_e32 v69, v69
	v_mul_f32_e32 v71, 0x3fb8aa3b, v36
	v_mul_f32_e32 v49, 0x3e13cd3a, v49
	v_mul_f32_e32 v51, 0x3e13cd3a, v51
	v_exp_f32_e32 v71, v71
	v_mul_f32_e32 v73, 0x3fb8aa3b, v37
	v_exp_f32_e32 v73, v73
	v_mul_f32_e32 v66, v41, v66
	v_mul_f32_e32 v30, v49, v30
	v_mul_f32_e32 v31, v51, v31
	v_mul_lo_u32 v5, v5, s55
	v_mul_f32_e32 v48, 0x3e13cd3a, v48
	v_mul_f32_e32 v50, 0x3e13cd3a, v50
	v_mul_f32_e32 v32, 0xbfb8aa3b, v32
	v_cvt_pk_bf16_f32 v30, v66, v30
	v_mul_f32_e32 v66, v59, v72
	v_cvt_pk_bf16_f32 v31, v31, v66
	v_add3_u32 v5, 0, v5, v61
	v_mul_f32_e32 v52, 0x3e13cd3a, v52
	v_exp_f32_e32 v32, v32
	v_mul_f32_e32 v33, 0xbfb8aa3b, v33
	ds_write_b64 v5, v[30:31] offset:39424
	v_mul_f32_e32 v30, v48, v67
	v_mul_f32_e32 v31, v50, v69
	v_mul_f32_e32 v55, 0x3e13cd3a, v55
	v_exp_f32_e32 v33, v33
	v_cvt_pk_bf16_f32 v30, v30, v31
	v_mul_f32_e32 v31, v52, v71
	v_mul_f32_e32 v36, 0xbfb8aa3b, v36
	v_mul_f32_e32 v61, v55, v73
	v_cvt_pk_bf16_f32 v31, v31, v61
	v_exp_f32_e32 v36, v36
	v_mul_f32_e32 v37, 0xbfb8aa3b, v37
	ds_write_b64 v5, v[30:31] offset:39448
	v_mul_f32_e32 v30, v44, v68
	v_mul_f32_e32 v31, v42, v70
	v_exp_f32_e32 v37, v37
	v_cvt_pk_bf16_f32 v30, v30, v31
	v_mul_f32_e32 v31, v53, v32
	v_mul_f32_e32 v32, v56, v33
	v_cvt_pk_bf16_f32 v31, v31, v32
	ds_write_b64 v5, v[30:31] offset:57856
	v_mul_f32_e32 v30, v45, v34
	v_mul_f32_e32 v31, v43, v35
	v_cvt_pk_bf16_f32 v30, v30, v31
	v_mul_f32_e32 v31, v54, v36
	v_mul_f32_e32 v32, v57, v37
	v_cvt_pk_bf16_f32 v31, v31, v32
	ds_write_b64 v5, v[30:31] offset:57880
	ds_read_b128 v[30:33], v64 offset:26112
	ds_read_b128 v[34:37], v64 offset:26160
	s_waitcnt lgkmcnt(1)
	v_mul_f32_e32 v61, 0x3fb8aa3b, v30
	v_mul_f32_e32 v30, 0xbfb8aa3b, v30
	v_exp_f32_e32 v66, v30
	s_waitcnt lgkmcnt(0)
	v_mul_f32_e32 v30, 0xbfb8aa3b, v34
	v_mul_f32_e32 v64, 0x3fb8aa3b, v34
	v_exp_f32_e32 v34, v30
	v_mul_f32_e32 v30, 0x3fb8aa3b, v31
	v_mul_f32_e32 v31, 0xbfb8aa3b, v31
	v_exp_f32_e32 v68, v31
	v_mul_f32_e32 v31, 0xbfb8aa3b, v35
	v_mul_f32_e32 v67, 0x3fb8aa3b, v35
	v_exp_f32_e32 v35, v31
	v_mul_f32_e32 v31, 0x3fb8aa3b, v32
	v_exp_f32_e32 v61, v61
	v_exp_f32_e32 v30, v30
	v_exp_f32_e32 v31, v31
	v_mul_f32_e32 v70, 0x3fb8aa3b, v33
	v_exp_f32_e32 v70, v70
	v_exp_f32_e32 v64, v64
	v_exp_f32_e32 v67, v67
	v_mul_f32_e32 v69, 0x3fb8aa3b, v36
	v_exp_f32_e32 v69, v69
	v_mul_f32_e32 v71, 0x3fb8aa3b, v37
	v_exp_f32_e32 v71, v71
	v_mul_f32_e32 v33, 0xbfb8aa3b, v33
	v_mul_f32_e32 v41, v41, v61
	v_mul_f32_e32 v30, v49, v30
	v_mul_f32_e32 v31, v51, v31
	v_mul_f32_e32 v32, 0xbfb8aa3b, v32
	v_exp_f32_e32 v33, v33
	v_cvt_pk_bf16_f32 v30, v41, v30
	v_mul_f32_e32 v41, v59, v70
	v_cvt_pk_bf16_f32 v31, v31, v41
	v_exp_f32_e32 v32, v32
	v_mul_f32_e32 v37, 0xbfb8aa3b, v37
	ds_write_b64 v5, v[30:31] offset:48640
	v_mul_f32_e32 v30, v48, v64
	v_mul_f32_e32 v31, v50, v67
	v_mul_f32_e32 v36, 0xbfb8aa3b, v36
	v_exp_f32_e32 v37, v37
	v_cvt_pk_bf16_f32 v30, v30, v31
	v_mul_f32_e32 v31, v52, v69
	v_exp_f32_e32 v36, v36
	v_mul_f32_e32 v48, v55, v71
	v_cvt_pk_bf16_f32 v31, v31, v48
	v_add_u32_e32 v41, 0x2400, v5
	ds_write_b64 v5, v[30:31] offset:48664
	v_mul_f32_e32 v5, v44, v66
	v_mul_f32_e32 v30, v42, v68
	v_mul_f32_e32 v31, v56, v33
	v_cvt_pk_bf16_f32 v30, v5, v30
	v_mul_f32_e32 v5, v53, v32
	v_cvt_pk_bf16_f32 v31, v5, v31
	ds_write_b64 v41, v[30:31] offset:57856
	v_mul_f32_e32 v5, v45, v34
	v_mul_f32_e32 v30, v43, v35
	v_mul_f32_e32 v31, v57, v37
	v_cvt_pk_bf16_f32 v30, v5, v30
	v_mul_f32_e32 v5, v54, v36
	v_cvt_pk_bf16_f32 v31, v5, v31
	ds_write_b64 v41, v[30:31] offset:57880
